# GEMM epilogues de-serialised: EpiMerge (k5) gate/prev loads 4 row groups in flight; EpiResid (k6,k10) gates loaded once per tile and X pieces 4 groups in flight; EpiUq/EpiUkv per-row rstd loads issued
# speedup vs baseline: 1.0047x; 1.0047x over previous
.LBB0_57:
	s_lshl_b32 s0, s64, 8
	v_mov_b32_e32 v148, v37
	v_mov_b32_e32 v149, v41
	s_or_b32 s0, s0, s56
	s_mov_b64 s[18:19], 0x5000
	v_lshl_add_u32 v150, v148, 3, s0
	s_lshl_b32 s0, s65, 8
	s_add_i32 s0, s0, s55
	v_add_u32_e32 v160, s0, v149
	v_readlane_b32 s64, v254, 31
	v_readlane_b32 s65, v254, 32
	v_readlane_b32 s24, v254, 25
	v_readlane_b32 s25, v254, 26
	s_nop 4
	v_cmp_lt_i32_e32 vcc, s84, v160
	s_movk_i32 s0, 0xff
	v_lshlrev_b32_e32 v148, 12, v160
	v_cndmask_b32_e32 v208, 0, v226, vcc
	v_cndmask_b32_e32 v209, 0, v227, vcc
	v_add_u32_e32 v208, v208, v160
	v_lshl_add_u32 v148, v150, 2, v148
	v_cmp_lt_i32_e32 vcc, s0, v208
	s_mov_b64 s[18:19], 0x5000
	s_nop 0
	v_cndmask_b32_e32 v208, v228, v209, vcc
	v_lshlrev_b32_e32 v149, 2, v208
	v_lshl_add_u32 v149, v150, 2, v149
	v_add_u32_e32 v149, 0x5000, v149
	global_load_dwordx4 v[152:155], v149, s[64:65] offset:0
	global_load_dwordx4 v[156:159], v149, s[64:65] offset:16
	global_load_dwordx4 v[164:167], v149, s[64:65] offset:512
	global_load_dwordx4 v[168:171], v149, s[64:65] offset:528
	global_load_dwordx4 v[172:175], v148, s[24:25]
	global_load_dwordx4 v[176:179], v148, s[24:25] offset:16
	v_add_u32_e32 v209, 0x10000, v148
	global_load_dwordx4 v[180:183], v209, s[24:25]
	global_load_dwordx4 v[184:187], v209, s[24:25] offset:16
	v_add_u32_e32 v209, 0x20000, v148
	global_load_dwordx4 v[188:191], v209, s[24:25]
	global_load_dwordx4 v[192:195], v209, s[24:25] offset:16
	v_add_u32_e32 v209, 0x30000, v148
	global_load_dwordx4 v[196:199], v209, s[24:25]
	global_load_dwordx4 v[204:207], v209, s[24:25] offset:16
	s_waitcnt vmcnt(6)
	v_pk_fma_f32 v[132:133], v[132:133], v[152:153], v[172:173]
	v_pk_fma_f32 v[134:135], v[134:135], v[154:155], v[174:175]
	v_pk_fma_f32 v[136:137], v[136:137], v[156:157], v[176:177]
	v_pk_fma_f32 v[138:139], v[138:139], v[158:159], v[178:179]
	global_store_dwordx4 v148, v[132:135], s[24:25]
	global_store_dwordx4 v148, v[136:139], s[24:25] offset:16
	v_add_u32_e32 v209, 0x80000, v148
	global_load_dwordx4 v[172:175], v209, s[24:25]
	global_load_dwordx4 v[176:179], v209, s[24:25] offset:16
	s_waitcnt vmcnt(8)
	v_pk_fma_f32 v[128:129], v[128:129], v[152:153], v[180:181]
	v_pk_fma_f32 v[130:131], v[130:131], v[154:155], v[182:183]
	v_pk_fma_f32 v[124:125], v[124:125], v[156:157], v[184:185]
	v_pk_fma_f32 v[126:127], v[126:127], v[158:159], v[186:187]
	v_add_u32_e32 v151, 0x10000, v148
	global_store_dwordx4 v151, v[128:131], s[24:25]
	global_store_dwordx4 v151, v[124:127], s[24:25] offset:16
	v_add_u32_e32 v209, 0x90000, v148
	global_load_dwordx4 v[180:183], v209, s[24:25]
	global_load_dwordx4 v[184:187], v209, s[24:25] offset:16
	s_waitcnt vmcnt(10)
	v_pk_fma_f32 v[120:121], v[120:121], v[152:153], v[188:189]
	v_pk_fma_f32 v[122:123], v[122:123], v[154:155], v[190:191]
	v_pk_fma_f32 v[116:117], v[116:117], v[156:157], v[192:193]
	v_pk_fma_f32 v[118:119], v[118:119], v[158:159], v[194:195]
	v_add_u32_e32 v151, 0x20000, v148
	global_store_dwordx4 v151, v[120:123], s[24:25]
	global_store_dwordx4 v151, v[116:119], s[24:25] offset:16
	v_add_u32_e32 v209, 0xa0000, v148
	global_load_dwordx4 v[188:191], v209, s[24:25]
	global_load_dwordx4 v[192:195], v209, s[24:25] offset:16
	s_waitcnt vmcnt(12)
	v_pk_fma_f32 v[112:113], v[112:113], v[152:153], v[196:197]
	v_pk_fma_f32 v[114:115], v[114:115], v[154:155], v[198:199]
	v_pk_fma_f32 v[108:109], v[108:109], v[156:157], v[204:205]
	v_pk_fma_f32 v[110:111], v[110:111], v[158:159], v[206:207]
	v_add_u32_e32 v151, 0x30000, v148
	global_store_dwordx4 v151, v[112:115], s[24:25]
	global_store_dwordx4 v151, v[108:111], s[24:25] offset:16
	v_add_u32_e32 v209, 0xb0000, v148
	global_load_dwordx4 v[196:199], v209, s[24:25]
	global_load_dwordx4 v[204:207], v209, s[24:25] offset:16
	s_waitcnt vmcnt(12)
	v_pk_fma_f32 v[104:105], v[104:105], v[152:153], v[172:173]
	v_pk_fma_f32 v[106:107], v[106:107], v[154:155], v[174:175]
	v_pk_fma_f32 v[100:101], v[100:101], v[156:157], v[176:177]
	v_pk_fma_f32 v[102:103], v[102:103], v[158:159], v[178:179]
	v_add_u32_e32 v151, 0x80000, v148
	global_store_dwordx4 v151, v[104:107], s[24:25]
	global_store_dwordx4 v151, v[100:103], s[24:25] offset:16
	v_add_u32_e32 v209, 0x200, v148
	global_load_dwordx4 v[172:175], v209, s[24:25]
	global_load_dwordx4 v[176:179], v209, s[24:25] offset:16
	s_waitcnt vmcnt(12)
	v_pk_fma_f32 v[96:97], v[96:97], v[152:153], v[180:181]
	v_pk_fma_f32 v[98:99], v[98:99], v[154:155], v[182:183]
	v_pk_fma_f32 v[92:93], v[92:93], v[156:157], v[184:185]
	v_pk_fma_f32 v[94:95], v[94:95], v[158:159], v[186:187]
	v_add_u32_e32 v151, 0x90000, v148
	global_store_dwordx4 v151, v[96:99], s[24:25]
	global_store_dwordx4 v151, v[92:95], s[24:25] offset:16
	v_add_u32_e32 v209, 0x10200, v148
	global_load_dwordx4 v[180:183], v209, s[24:25]
	global_load_dwordx4 v[184:187], v209, s[24:25] offset:16
	s_waitcnt vmcnt(12)
	v_pk_fma_f32 v[88:89], v[88:89], v[152:153], v[188:189]
	v_pk_fma_f32 v[90:91], v[90:91], v[154:155], v[190:191]
	v_pk_fma_f32 v[84:85], v[84:85], v[156:157], v[192:193]
	v_pk_fma_f32 v[86:87], v[86:87], v[158:159], v[194:195]
	v_add_u32_e32 v151, 0xa0000, v148
	global_store_dwordx4 v151, v[88:91], s[24:25]
	global_store_dwordx4 v151, v[84:87], s[24:25] offset:16
	v_add_u32_e32 v209, 0x20200, v148
	global_load_dwordx4 v[188:191], v209, s[24:25]
	global_load_dwordx4 v[192:195], v209, s[24:25] offset:16
	s_waitcnt vmcnt(12)
	v_pk_fma_f32 v[80:81], v[80:81], v[152:153], v[196:197]
	v_pk_fma_f32 v[82:83], v[82:83], v[154:155], v[198:199]
	v_pk_fma_f32 v[76:77], v[76:77], v[156:157], v[204:205]
	v_pk_fma_f32 v[78:79], v[78:79], v[158:159], v[206:207]
	v_add_u32_e32 v151, 0xb0000, v148
	global_store_dwordx4 v151, v[80:83], s[24:25]
	global_store_dwordx4 v151, v[76:79], s[24:25] offset:16
	v_add_u32_e32 v209, 0x30200, v148
	global_load_dwordx4 v[196:199], v209, s[24:25]
	global_load_dwordx4 v[204:207], v209, s[24:25] offset:16
	s_waitcnt vmcnt(12)
	v_pk_fma_f32 v[72:73], v[72:73], v[164:165], v[172:173]
	v_pk_fma_f32 v[74:75], v[74:75], v[166:167], v[174:175]
	v_pk_fma_f32 v[68:69], v[68:69], v[168:169], v[176:177]
	v_pk_fma_f32 v[70:71], v[70:71], v[170:171], v[178:179]
	v_add_u32_e32 v151, 0x200, v148
	global_store_dwordx4 v151, v[72:75], s[24:25]
	global_store_dwordx4 v151, v[68:71], s[24:25] offset:16
	v_add_u32_e32 v209, 0x80200, v148
	global_load_dwordx4 v[172:175], v209, s[24:25]
	global_load_dwordx4 v[176:179], v209, s[24:25] offset:16
	s_waitcnt vmcnt(12)
	v_pk_fma_f32 v[64:65], v[64:65], v[164:165], v[180:181]
	v_pk_fma_f32 v[66:67], v[66:67], v[166:167], v[182:183]
	v_pk_fma_f32 v[60:61], v[60:61], v[168:169], v[184:185]
	v_pk_fma_f32 v[62:63], v[62:63], v[170:171], v[186:187]
	v_add_u32_e32 v151, 0x10200, v148
	global_store_dwordx4 v151, v[64:67], s[24:25]
	global_store_dwordx4 v151, v[60:63], s[24:25] offset:16
	v_add_u32_e32 v209, 0x90200, v148
	global_load_dwordx4 v[180:183], v209, s[24:25]
	global_load_dwordx4 v[184:187], v209, s[24:25] offset:16
	s_waitcnt vmcnt(12)
	v_pk_fma_f32 v[56:57], v[56:57], v[164:165], v[188:189]
	v_pk_fma_f32 v[58:59], v[58:59], v[166:167], v[190:191]
	v_pk_fma_f32 v[52:53], v[52:53], v[168:169], v[192:193]
	v_pk_fma_f32 v[54:55], v[54:55], v[170:171], v[194:195]
	v_add_u32_e32 v151, 0x20200, v148
	global_store_dwordx4 v151, v[56:59], s[24:25]
	global_store_dwordx4 v151, v[52:55], s[24:25] offset:16
	v_add_u32_e32 v209, 0xa0200, v148
	global_load_dwordx4 v[188:191], v209, s[24:25]
	global_load_dwordx4 v[192:195], v209, s[24:25] offset:16
	s_waitcnt vmcnt(12)
	v_pk_fma_f32 v[48:49], v[48:49], v[164:165], v[196:197]
	v_pk_fma_f32 v[50:51], v[50:51], v[166:167], v[198:199]
	v_pk_fma_f32 v[32:33], v[32:33], v[168:169], v[204:205]
	v_pk_fma_f32 v[34:35], v[34:35], v[170:171], v[206:207]
	v_add_u32_e32 v151, 0x30200, v148
	global_store_dwordx4 v151, v[48:51], s[24:25]
	global_store_dwordx4 v151, v[32:35], s[24:25] offset:16
	v_add_u32_e32 v209, 0xb0200, v148
	global_load_dwordx4 v[196:199], v209, s[24:25]
	global_load_dwordx4 v[204:207], v209, s[24:25] offset:16
	s_waitcnt vmcnt(12)
	v_pk_fma_f32 v[28:29], v[28:29], v[164:165], v[172:173]
	v_pk_fma_f32 v[30:31], v[30:31], v[166:167], v[174:175]
	v_pk_fma_f32 v[24:25], v[24:25], v[168:169], v[176:177]
	v_pk_fma_f32 v[26:27], v[26:27], v[170:171], v[178:179]
	v_add_u32_e32 v151, 0x80200, v148
	global_store_dwordx4 v151, v[28:31], s[24:25]
	global_store_dwordx4 v151, v[24:27], s[24:25] offset:16
	s_waitcnt vmcnt(10)
	v_pk_fma_f32 v[20:21], v[20:21], v[164:165], v[180:181]
	v_pk_fma_f32 v[22:23], v[22:23], v[166:167], v[182:183]
	v_pk_fma_f32 v[16:17], v[16:17], v[168:169], v[184:185]
	v_pk_fma_f32 v[18:19], v[18:19], v[170:171], v[186:187]
	v_add_u32_e32 v151, 0x90200, v148
	global_store_dwordx4 v151, v[20:23], s[24:25]
	global_store_dwordx4 v151, v[16:19], s[24:25] offset:16
	s_waitcnt vmcnt(8)
	v_pk_fma_f32 v[12:13], v[12:13], v[164:165], v[188:189]
	v_pk_fma_f32 v[14:15], v[14:15], v[166:167], v[190:191]
	v_pk_fma_f32 v[8:9], v[8:9], v[168:169], v[192:193]
	v_pk_fma_f32 v[10:11], v[10:11], v[170:171], v[194:195]
	v_add_u32_e32 v151, 0xa0200, v148
	global_store_dwordx4 v151, v[12:15], s[24:25]
	global_store_dwordx4 v151, v[8:11], s[24:25] offset:16
	s_waitcnt vmcnt(6)
	v_pk_fma_f32 v[4:5], v[4:5], v[164:165], v[196:197]
	v_pk_fma_f32 v[6:7], v[6:7], v[166:167], v[198:199]
	v_pk_fma_f32 v[0:1], v[0:1], v[168:169], v[204:205]
	v_pk_fma_f32 v[2:3], v[2:3], v[170:171], v[206:207]
	v_add_u32_e32 v151, 0xb0200, v148
	global_store_dwordx4 v151, v[4:7], s[24:25]
	global_store_dwordx4 v151, v[0:3], s[24:25] offset:16
	s_and_b64 vcc, exec, s[38:39]
	s_mov_b64 s[0:1], -1
	s_cbranch_vccnz .LBB0_44
	s_andn2_b64 vcc, exec, s[16:17]
	s_cbranch_vccnz .LBB0_43
	s_barrier
	s_branch .LBB0_43

.LBB0_229:
	s_lshl_b32 s0, s62, 8
	v_mov_b32_e32 v148, v37
	v_mov_b32_e32 v149, v41
	s_or_b32 s0, s0, s54
	s_mov_b64 s[18:19], 0x2000
	v_lshl_add_u32 v150, v148, 3, s0
	s_lshl_b32 s0, s63, 8
	s_add_i32 s0, s0, s53
	v_add_u32_e32 v160, s0, v149
	v_readlane_b32 s62, v254, 31
	v_readlane_b32 s63, v254, 32
	v_readlane_b32 s24, v254, 25
	v_readlane_b32 s25, v254, 26
	s_nop 4
	v_cmp_lt_i32_e32 vcc, s84, v160
	s_movk_i32 s0, 0xff
	v_lshlrev_b32_e32 v148, 12, v160
	v_cndmask_b32_e32 v208, 0, v226, vcc
	v_cndmask_b32_e32 v209, 0, v227, vcc
	v_add_u32_e32 v208, v208, v160
	v_lshl_add_u32 v148, v150, 2, v148
	v_cmp_lt_i32_e32 vcc, s0, v208
	s_mov_b64 s[18:19], 0x2000
	s_nop 0
	v_cndmask_b32_e32 v208, v228, v209, vcc
	v_lshlrev_b32_e32 v149, 2, v208
	v_lshl_add_u32 v149, v150, 2, v149
	v_add_u32_e32 v149, 0x2000, v149
	global_load_dwordx4 v[152:155], v149, s[62:63] offset:0
	global_load_dwordx4 v[156:159], v149, s[62:63] offset:16
	global_load_dwordx4 v[164:167], v149, s[62:63] offset:512
	global_load_dwordx4 v[168:171], v149, s[62:63] offset:528
	global_load_dwordx4 v[172:175], v148, s[24:25]
	global_load_dwordx4 v[176:179], v148, s[24:25] offset:16
	v_add_u32_e32 v209, 0x10000, v148
	global_load_dwordx4 v[180:183], v209, s[24:25]
	global_load_dwordx4 v[184:187], v209, s[24:25] offset:16
	v_add_u32_e32 v209, 0x20000, v148
	global_load_dwordx4 v[188:191], v209, s[24:25]
	global_load_dwordx4 v[192:195], v209, s[24:25] offset:16
	v_add_u32_e32 v209, 0x30000, v148
	global_load_dwordx4 v[196:199], v209, s[24:25]
	global_load_dwordx4 v[204:207], v209, s[24:25] offset:16
	s_waitcnt vmcnt(6)
	v_pk_fma_f32 v[132:133], v[132:133], v[152:153], v[172:173]
	v_pk_fma_f32 v[134:135], v[134:135], v[154:155], v[174:175]
	v_pk_fma_f32 v[136:137], v[136:137], v[156:157], v[176:177]
	v_pk_fma_f32 v[138:139], v[138:139], v[158:159], v[178:179]
	global_store_dwordx4 v148, v[132:135], s[24:25]
	global_store_dwordx4 v148, v[136:139], s[24:25] offset:16
	v_add_u32_e32 v209, 0x80000, v148
	global_load_dwordx4 v[172:175], v209, s[24:25]
	global_load_dwordx4 v[176:179], v209, s[24:25] offset:16
	s_waitcnt vmcnt(8)
	v_pk_fma_f32 v[128:129], v[128:129], v[152:153], v[180:181]
	v_pk_fma_f32 v[130:131], v[130:131], v[154:155], v[182:183]
	v_pk_fma_f32 v[124:125], v[124:125], v[156:157], v[184:185]
	v_pk_fma_f32 v[126:127], v[126:127], v[158:159], v[186:187]
	v_add_u32_e32 v151, 0x10000, v148
	global_store_dwordx4 v151, v[128:131], s[24:25]
	global_store_dwordx4 v151, v[124:127], s[24:25] offset:16
	v_add_u32_e32 v209, 0x90000, v148
	global_load_dwordx4 v[180:183], v209, s[24:25]
	global_load_dwordx4 v[184:187], v209, s[24:25] offset:16
	s_waitcnt vmcnt(10)
	v_pk_fma_f32 v[120:121], v[120:121], v[152:153], v[188:189]
	v_pk_fma_f32 v[122:123], v[122:123], v[154:155], v[190:191]
	v_pk_fma_f32 v[116:117], v[116:117], v[156:157], v[192:193]
	v_pk_fma_f32 v[118:119], v[118:119], v[158:159], v[194:195]
	v_add_u32_e32 v151, 0x20000, v148
	global_store_dwordx4 v151, v[120:123], s[24:25]
	global_store_dwordx4 v151, v[116:119], s[24:25] offset:16
	v_add_u32_e32 v209, 0xa0000, v148
	global_load_dwordx4 v[188:191], v209, s[24:25]
	global_load_dwordx4 v[192:195], v209, s[24:25] offset:16
	s_waitcnt vmcnt(12)
	v_pk_fma_f32 v[112:113], v[112:113], v[152:153], v[196:197]
	v_pk_fma_f32 v[114:115], v[114:115], v[154:155], v[198:199]
	v_pk_fma_f32 v[108:109], v[108:109], v[156:157], v[204:205]
	v_pk_fma_f32 v[110:111], v[110:111], v[158:159], v[206:207]
	v_add_u32_e32 v151, 0x30000, v148
	global_store_dwordx4 v151, v[112:115], s[24:25]
	global_store_dwordx4 v151, v[108:111], s[24:25] offset:16
	v_add_u32_e32 v209, 0xb0000, v148
	global_load_dwordx4 v[196:199], v209, s[24:25]
	global_load_dwordx4 v[204:207], v209, s[24:25] offset:16
	s_waitcnt vmcnt(12)
	v_pk_fma_f32 v[104:105], v[104:105], v[152:153], v[172:173]
	v_pk_fma_f32 v[106:107], v[106:107], v[154:155], v[174:175]
	v_pk_fma_f32 v[100:101], v[100:101], v[156:157], v[176:177]
	v_pk_fma_f32 v[102:103], v[102:103], v[158:159], v[178:179]
	v_add_u32_e32 v151, 0x80000, v148
	global_store_dwordx4 v151, v[104:107], s[24:25]
	global_store_dwordx4 v151, v[100:103], s[24:25] offset:16
	v_add_u32_e32 v209, 0x200, v148
	global_load_dwordx4 v[172:175], v209, s[24:25]
	global_load_dwordx4 v[176:179], v209, s[24:25] offset:16
	s_waitcnt vmcnt(12)
	v_pk_fma_f32 v[96:97], v[96:97], v[152:153], v[180:181]
	v_pk_fma_f32 v[98:99], v[98:99], v[154:155], v[182:183]
	v_pk_fma_f32 v[92:93], v[92:93], v[156:157], v[184:185]
	v_pk_fma_f32 v[94:95], v[94:95], v[158:159], v[186:187]
	v_add_u32_e32 v151, 0x90000, v148
	global_store_dwordx4 v151, v[96:99], s[24:25]
	global_store_dwordx4 v151, v[92:95], s[24:25] offset:16
	v_add_u32_e32 v209, 0x10200, v148
	global_load_dwordx4 v[180:183], v209, s[24:25]
	global_load_dwordx4 v[184:187], v209, s[24:25] offset:16
	s_waitcnt vmcnt(12)
	v_pk_fma_f32 v[88:89], v[88:89], v[152:153], v[188:189]
	v_pk_fma_f32 v[90:91], v[90:91], v[154:155], v[190:191]
	v_pk_fma_f32 v[84:85], v[84:85], v[156:157], v[192:193]
	v_pk_fma_f32 v[86:87], v[86:87], v[158:159], v[194:195]
	v_add_u32_e32 v151, 0xa0000, v148
	global_store_dwordx4 v151, v[88:91], s[24:25]
	global_store_dwordx4 v151, v[84:87], s[24:25] offset:16
	v_add_u32_e32 v209, 0x20200, v148
	global_load_dwordx4 v[188:191], v209, s[24:25]
	global_load_dwordx4 v[192:195], v209, s[24:25] offset:16
	s_waitcnt vmcnt(12)
	v_pk_fma_f32 v[80:81], v[80:81], v[152:153], v[196:197]
	v_pk_fma_f32 v[82:83], v[82:83], v[154:155], v[198:199]
	v_pk_fma_f32 v[76:77], v[76:77], v[156:157], v[204:205]
	v_pk_fma_f32 v[78:79], v[78:79], v[158:159], v[206:207]
	v_add_u32_e32 v151, 0xb0000, v148
	global_store_dwordx4 v151, v[80:83], s[24:25]
	global_store_dwordx4 v151, v[76:79], s[24:25] offset:16
	v_add_u32_e32 v209, 0x30200, v148
	global_load_dwordx4 v[196:199], v209, s[24:25]
	global_load_dwordx4 v[204:207], v209, s[24:25] offset:16
	s_waitcnt vmcnt(12)
	v_pk_fma_f32 v[72:73], v[72:73], v[164:165], v[172:173]
	v_pk_fma_f32 v[74:75], v[74:75], v[166:167], v[174:175]
	v_pk_fma_f32 v[68:69], v[68:69], v[168:169], v[176:177]
	v_pk_fma_f32 v[70:71], v[70:71], v[170:171], v[178:179]
	v_add_u32_e32 v151, 0x200, v148
	global_store_dwordx4 v151, v[72:75], s[24:25]
	global_store_dwordx4 v151, v[68:71], s[24:25] offset:16
	v_add_u32_e32 v209, 0x80200, v148
	global_load_dwordx4 v[172:175], v209, s[24:25]
	global_load_dwordx4 v[176:179], v209, s[24:25] offset:16
	s_waitcnt vmcnt(12)
	v_pk_fma_f32 v[64:65], v[64:65], v[164:165], v[180:181]
	v_pk_fma_f32 v[66:67], v[66:67], v[166:167], v[182:183]
	v_pk_fma_f32 v[60:61], v[60:61], v[168:169], v[184:185]
	v_pk_fma_f32 v[62:63], v[62:63], v[170:171], v[186:187]
	v_add_u32_e32 v151, 0x10200, v148
	global_store_dwordx4 v151, v[64:67], s[24:25]
	global_store_dwordx4 v151, v[60:63], s[24:25] offset:16
	v_add_u32_e32 v209, 0x90200, v148
	global_load_dwordx4 v[180:183], v209, s[24:25]
	global_load_dwordx4 v[184:187], v209, s[24:25] offset:16
	s_waitcnt vmcnt(12)
	v_pk_fma_f32 v[56:57], v[56:57], v[164:165], v[188:189]
	v_pk_fma_f32 v[58:59], v[58:59], v[166:167], v[190:191]
	v_pk_fma_f32 v[52:53], v[52:53], v[168:169], v[192:193]
	v_pk_fma_f32 v[54:55], v[54:55], v[170:171], v[194:195]
	v_add_u32_e32 v151, 0x20200, v148
	global_store_dwordx4 v151, v[56:59], s[24:25]
	global_store_dwordx4 v151, v[52:55], s[24:25] offset:16
	v_add_u32_e32 v209, 0xa0200, v148
	global_load_dwordx4 v[188:191], v209, s[24:25]
	global_load_dwordx4 v[192:195], v209, s[24:25] offset:16
	s_waitcnt vmcnt(12)
	v_pk_fma_f32 v[48:49], v[48:49], v[164:165], v[196:197]
	v_pk_fma_f32 v[50:51], v[50:51], v[166:167], v[198:199]
	v_pk_fma_f32 v[32:33], v[32:33], v[168:169], v[204:205]
	v_pk_fma_f32 v[34:35], v[34:35], v[170:171], v[206:207]
	v_add_u32_e32 v151, 0x30200, v148
	global_store_dwordx4 v151, v[48:51], s[24:25]
	global_store_dwordx4 v151, v[32:35], s[24:25] offset:16
	v_add_u32_e32 v209, 0xb0200, v148
	global_load_dwordx4 v[196:199], v209, s[24:25]
	global_load_dwordx4 v[204:207], v209, s[24:25] offset:16
	s_waitcnt vmcnt(12)
	v_pk_fma_f32 v[28:29], v[28:29], v[164:165], v[172:173]
	v_pk_fma_f32 v[30:31], v[30:31], v[166:167], v[174:175]
	v_pk_fma_f32 v[24:25], v[24:25], v[168:169], v[176:177]
	v_pk_fma_f32 v[26:27], v[26:27], v[170:171], v[178:179]
	v_add_u32_e32 v151, 0x80200, v148
	global_store_dwordx4 v151, v[28:31], s[24:25]
	global_store_dwordx4 v151, v[24:27], s[24:25] offset:16
	s_waitcnt vmcnt(10)
	v_pk_fma_f32 v[20:21], v[20:21], v[164:165], v[180:181]
	v_pk_fma_f32 v[22:23], v[22:23], v[166:167], v[182:183]
	v_pk_fma_f32 v[16:17], v[16:17], v[168:169], v[184:185]
	v_pk_fma_f32 v[18:19], v[18:19], v[170:171], v[186:187]
	v_add_u32_e32 v151, 0x90200, v148
	global_store_dwordx4 v151, v[20:23], s[24:25]
	global_store_dwordx4 v151, v[16:19], s[24:25] offset:16
	s_waitcnt vmcnt(8)
	v_pk_fma_f32 v[12:13], v[12:13], v[164:165], v[188:189]
	v_pk_fma_f32 v[14:15], v[14:15], v[166:167], v[190:191]
	v_pk_fma_f32 v[8:9], v[8:9], v[168:169], v[192:193]
	v_pk_fma_f32 v[10:11], v[10:11], v[170:171], v[194:195]
	v_add_u32_e32 v151, 0xa0200, v148
	global_store_dwordx4 v151, v[12:15], s[24:25]
	global_store_dwordx4 v151, v[8:11], s[24:25] offset:16
	s_waitcnt vmcnt(6)
	v_pk_fma_f32 v[4:5], v[4:5], v[164:165], v[196:197]
	v_pk_fma_f32 v[6:7], v[6:7], v[166:167], v[198:199]
	v_pk_fma_f32 v[0:1], v[0:1], v[168:169], v[204:205]
	v_pk_fma_f32 v[2:3], v[2:3], v[170:171], v[206:207]
	v_add_u32_e32 v151, 0xb0200, v148
	global_store_dwordx4 v151, v[4:7], s[24:25]
	global_store_dwordx4 v151, v[0:3], s[24:25] offset:16
	s_and_b64 vcc, exec, s[38:39]
	s_mov_b64 s[0:1], -1
	s_cbranch_vccnz .LBB0_216
	s_andn2_b64 vcc, exec, s[16:17]
	s_cbranch_vccnz .LBB0_215
	s_barrier
	s_branch .LBB0_215

; __device__ __forceinline__ u32x4 pack8(const float* v) { u32x4 w; w.x = pk2(v[0], v[1]); w.y = pk2(v[2], v[3]); w.z = pk2(v[4], v[5]); w.w = pk2(v[6], v[7]); return w; }
;     __device__ __forceinline__ void operator()(const f32x4 (&acc)[2][2][4][2], const pg8::Unit& u, int wr, int wc, int fr, int fq) const {
;     ...
;             const int b = (t >= TB) ? 1 : 0, i = t - b * TB; const bool lat = i >= LC; const int pos = i - LC;
;             const float rstd = rsqrtf(((const float*)(ws + O_SSQ))[t * 2] * (1.f / 256.f) + EPS) * (0.10206207261596575f * LOG2E);
; #pragma unroll
;             for (int e = 0; e < 8; ++e) v[e] *= rstd;
;             const int h = c0 / 96, w = c0 - h * 96;
;             if (w >= 64 && lat) { const float* cs = (const float*)(ws + O_ROPEB) + (size_t)pos * 32 + ((w - 64) >> 1);
; #pragma unroll
;                 for (int p = 0; p < 4; ++p) { const float c = cs[p], s = cs[16 + p], a = v[2 * p], bb = v[2 * p + 1]; v[2 * p] = a * c - bb * s; v[2 * p + 1] = a * s + bb * c; } }
;             *(u32x4*)((bf16_t*)(ws + O_QB) + (size_t)t * 768 + c0) = pack8(v);
.LBB0_535:
	v_mov_b32_e32 v149, v41
	v_mov_b32_e32 v148, v37
	s_lshl_b32 s0, s43, 8
	s_or_b32 s0, s0, s75
	v_lshl_add_u32 v148, v148, 3, s0
	s_lshl_b32 s0, s42, 8
	s_add_i32 s0, s0, s74
	v_add_u32_e32 v158, s0, v149
	s_mov_b32 s0, 0x2aaaaaab
	v_mul_hi_i32 v149, v148, s0
	v_lshrrev_b32_e32 v150, 31, v149
	v_lshrrev_b32_e32 v149, 4, v149
	v_add_u32_e32 v149, v149, v150
	v_lshlrev_b32_e32 v150, 1, v158
	v_ashrrev_i32_e32 v151, 31, v150
	v_lshl_add_u64 v[150:151], v[150:151], 2, s[34:35]
	global_load_dword v178, v[150:151], off offset:0
	global_load_dword v179, v[150:151], off offset:128
	global_load_dword v180, v[150:151], off offset:256
	global_load_dword v181, v[150:151], off offset:384
	global_load_dword v182, v[150:151], off offset:1024
	global_load_dword v183, v[150:151], off offset:1152
	global_load_dword v184, v[150:151], off offset:1280
	global_load_dword v185, v[150:151], off offset:1408
	s_movk_i32 s0, 0x60
	v_mul_lo_u32 v149, v149, s0
	v_sub_u32_e32 v149, v148, v149
	s_movk_i32 s0, 0x2100
	v_cmp_lt_i32_e64 s[40:41], 63, v149
	v_subrev_u32_e32 v149, 64, v149
	v_cmp_gt_i32_e32 vcc, s0, v158
	v_lshrrev_b32_e32 v152, 1, v149
	s_movk_i32 s0, 0xff
	v_cndmask_b32_e64 v149, v226, 0, vcc
	v_add_u32_e32 v149, v149, v158
	v_cmp_lt_i32_e32 vcc, s0, v149
	v_mov_b32_e32 v153, v36
	s_and_b64 s[18:19], s[40:41], vcc
	s_waitcnt vmcnt(0)
	v_mov_b32_e32 v154, v178
	v_fmamk_f32 v154, v154, 0x3b800000, v216
	v_cmp_gt_f32_e64 s[42:43], s33, v154
	v_mul_f32_e32 v155, 0x4b800000, v154
	s_nop 0
	v_cndmask_b32_e64 v154, v154, v155, s[42:43]
	v_rsq_f32_e32 v154, v154
	s_nop 0
	v_mul_f32_e32 v155, 0x45800000, v154
	v_cndmask_b32_e64 v154, v154, v155, s[42:43]
	v_mul_f32_e32 v160, 0x3e16c740, v154
	v_pk_mul_f32 v[154:155], v[132:133], v[160:161] op_sel_hi:[1,0]
	v_pk_mul_f32 v[134:135], v[134:135], v[160:161] op_sel_hi:[1,0]
	v_pk_mul_f32 v[136:137], v[136:137], v[160:161] op_sel_hi:[1,0]
	v_pk_mul_f32 v[138:139], v[138:139], v[160:161] op_sel_hi:[1,0]
	v_add_u32_e32 v132, 0xffffff00, v149
	s_and_saveexec_b64 s[0:1], s[18:19]
	s_cbranch_execz .LBB0_537
	v_mov_b32_e32 v133, v36
	v_lshlrev_b64 v[160:161], 7, v[132:133]
	v_lshl_add_u64 v[160:161], s[58:59], 0, v[160:161]
	v_lshl_add_u64 v[164:165], v[152:153], 2, v[160:161]
	global_load_dwordx4 v[160:163], v[164:165], off
	s_nop 0
	global_load_dwordx4 v[164:167], v[164:165], off offset:64
	s_waitcnt vmcnt(0)
	v_pk_mul_f32 v[170:171], v[154:155], v[160:161] op_sel_hi:[1,0]
	v_pk_mul_f32 v[168:169], v[154:155], v[164:165] op_sel:[1,0] op_sel_hi:[0,0]
	v_pk_mul_f32 v[164:165], v[134:135], v[164:165] op_sel:[1,1] op_sel_hi:[0,1]
	v_pk_fma_f32 v[172:173], v[134:135], v[160:161], v[164:165] op_sel:[0,1,0] neg_lo:[0,0,1] neg_hi:[0,0,1]
	v_pk_fma_f32 v[134:135], v[134:135], v[160:161], v[164:165] op_sel:[0,1,0]
	v_pk_fma_f32 v[154:155], v[154:155], v[160:161], v[168:169] op_sel_hi:[1,0,1]
	v_pk_mul_f32 v[160:161], v[136:137], v[166:167] op_sel:[1,0] op_sel_hi:[0,0]
	v_mov_b32_e32 v166, v163
	v_mul_f32_e32 v134, v139, v167
	v_pk_fma_f32 v[164:165], v[136:137], v[162:163], v[160:161] op_sel_hi:[1,0,1] neg_lo:[0,0,1] neg_hi:[0,0,1]
	v_pk_fma_f32 v[136:137], v[136:137], v[162:163], v[160:161] op_sel_hi:[1,0,1]
	v_pk_fma_f32 v[160:161], v[138:139], v[166:167], v[134:135] op_sel_hi:[1,1,0] neg_lo:[0,0,1] neg_hi:[0,0,1]
	v_mov_b32_e32 v162, v167
	v_mul_f32_e32 v134, v139, v163
	v_pk_fma_f32 v[162:163], v[138:139], v[162:163], v[134:135] op_sel_hi:[1,1,0]
	v_sub_f32_e32 v154, v170, v168
	v_mov_b32_e32 v134, v172
	v_mov_b32_e32 v136, v164
	v_mov_b32_e32 v138, v160
	v_mov_b32_e32 v139, v162
.LBB0_537:
	s_or_b64 exec, exec, s[0:1]
	v_cvt_pk_bf16_f32 v161, v134, v135
	v_mov_b64_e32 v[134:135], s[60:61]
	s_movk_i32 s0, 0x600
	v_ashrrev_i32_e32 v149, 31, v148
	v_mad_i64_i32 v[134:135], s[0:1], v158, s0, v[134:135]
	v_add_u32_e32 v133, 16, v158
	v_cvt_pk_bf16_f32 v160, v154, v155
	v_cvt_pk_bf16_f32 v162, v136, v137
	v_cvt_pk_bf16_f32 v163, v138, v139
	v_lshl_add_u64 v[136:137], v[148:149], 1, v[134:135]
	v_lshlrev_b32_e32 v134, 1, v133
	global_store_dwordx4 v[136:137], v[160:163], off
	v_ashrrev_i32_e32 v135, 31, v134
	v_lshl_add_u64 v[138:139], v[134:135], 2, s[34:35]
	s_nop 0
	s_movk_i32 s0, 0x2100
	v_cmp_gt_i32_e64 s[42:43], s0, v133
	s_movk_i32 s0, 0xff
	v_mov_b32_e32 v134, v179
	v_fmamk_f32 v134, v134, 0x3b800000, v216
	v_mul_f32_e32 v154, 0x4b800000, v134
	v_cmp_gt_f32_e64 s[44:45], s33, v134
	v_cndmask_b32_e64 v135, v226, 0, s[42:43]
	s_nop 0
	v_cndmask_b32_e64 v134, v134, v154, s[44:45]
	v_rsq_f32_e32 v154, v134
	v_add_u32_e32 v134, v135, v133
	v_cmp_lt_i32_e64 s[42:43], s0, v134
	v_add_u32_e32 v134, 0xffffff00, v134
	v_mul_f32_e32 v135, 0x45800000, v154
	v_cndmask_b32_e64 v135, v154, v135, s[44:45]
	v_mul_f32_e32 v154, 0x3e16c740, v135
	v_pk_mul_f32 v[128:129], v[128:129], v[154:155] op_sel_hi:[1,0]
	v_pk_mul_f32 v[130:131], v[130:131], v[154:155] op_sel_hi:[1,0]
	v_pk_mul_f32 v[124:125], v[124:125], v[154:155] op_sel_hi:[1,0]
	v_pk_mul_f32 v[126:127], v[126:127], v[154:155] op_sel_hi:[1,0]
	s_and_b64 s[18:19], s[40:41], s[42:43]
	s_and_saveexec_b64 s[0:1], s[18:19]
	s_cbranch_execz .LBB0_539
	v_mov_b32_e32 v135, v36
	v_lshlrev_b64 v[154:155], 7, v[134:135]
	v_lshl_add_u64 v[154:155], s[58:59], 0, v[154:155]
	v_lshl_add_u64 v[154:155], v[152:153], 2, v[154:155]
	global_load_dwordx4 v[160:163], v[154:155], off
	global_load_dwordx4 v[164:167], v[154:155], off offset:64
	s_waitcnt vmcnt(0)
	v_pk_mul_f32 v[168:169], v[128:129], v[160:161] op_sel_hi:[1,0]
	v_pk_mul_f32 v[154:155], v[128:129], v[164:165] op_sel:[1,0] op_sel_hi:[0,0]
	v_pk_mul_f32 v[164:165], v[130:131], v[164:165] op_sel:[1,1] op_sel_hi:[0,1]
	v_pk_fma_f32 v[128:129], v[128:129], v[160:161], v[154:155] op_sel_hi:[1,0,1]
	v_pk_fma_f32 v[170:171], v[130:131], v[160:161], v[164:165] op_sel:[0,1,0] neg_lo:[0,0,1] neg_hi:[0,0,1]
	v_pk_fma_f32 v[130:131], v[130:131], v[160:161], v[164:165] op_sel:[0,1,0]
	v_pk_mul_f32 v[160:161], v[124:125], v[166:167] op_sel:[1,0] op_sel_hi:[0,0]
	v_pk_fma_f32 v[164:165], v[124:125], v[162:163], v[160:161] op_sel_hi:[1,0,1] neg_lo:[0,0,1] neg_hi:[0,0,1]
	v_pk_fma_f32 v[124:125], v[124:125], v[162:163], v[160:161] op_sel_hi:[1,0,1]
	v_mov_b32_e32 v166, v163
	v_mul_f32_e32 v124, v127, v167
	v_pk_fma_f32 v[160:161], v[126:127], v[166:167], v[124:125] op_sel_hi:[1,1,0] neg_lo:[0,0,1] neg_hi:[0,0,1]
	v_mov_b32_e32 v162, v167
	v_mul_f32_e32 v124, v127, v163
	v_pk_fma_f32 v[162:163], v[126:127], v[162:163], v[124:125] op_sel_hi:[1,1,0]
	v_sub_f32_e32 v128, v168, v154
	v_mov_b32_e32 v130, v170
	v_mov_b32_e32 v124, v164
	v_mov_b32_e32 v126, v160
	v_mov_b32_e32 v127, v162
; __device__ __forceinline__ u32x4 pack8(const float* v) { u32x4 w; w.x = pk2(v[0], v[1]); w.y = pk2(v[2], v[3]); w.z = pk2(v[4], v[5]); w.w = pk2(v[6], v[7]); return w; }
;     __device__ __forceinline__ void operator()(const f32x4 (&acc)[2][2][4][2], const pg8::Unit& u, int wr, int wc, int fr, int fq) const {
;     ...
;             const int b = (t >= TB) ? 1 : 0, i = t - b * TB; const bool lat = i >= LC; const int pos = i - LC;
;             const float rstd = rsqrtf(((const float*)(ws + O_SSQ))[t * 2] * (1.f / 256.f) + EPS) * (0.10206207261596575f * LOG2E);
; #pragma unroll
;             for (int e = 0; e < 8; ++e) v[e] *= rstd;
;             const int h = c0 / 96, w = c0 - h * 96;
;             if (w >= 64 && lat) { const float* cs = (const float*)(ws + O_ROPEB) + (size_t)pos * 32 + ((w - 64) >> 1);
; #pragma unroll
;                 for (int p = 0; p < 4; ++p) { const float c = cs[p], s = cs[16 + p], a = v[2 * p], bb = v[2 * p + 1]; v[2 * p] = a * c - bb * s; v[2 * p + 1] = a * s + bb * c; } }
;             *(u32x4*)((bf16_t*)(ws + O_QB) + (size_t)t * 768 + c0) = pack8(v);
.LBB0_539:
	s_or_b64 exec, exec, s[0:1]
	v_cvt_pk_bf16_f32 v128, v128, v129
	v_cvt_pk_bf16_f32 v129, v130, v131
	v_cvt_pk_bf16_f32 v130, v124, v125
	v_mov_b64_e32 v[124:125], s[60:61]
	s_movk_i32 s0, 0x600
	v_mad_i64_i32 v[124:125], s[0:1], v133, s0, v[124:125]
	v_cvt_pk_bf16_f32 v131, v126, v127
	v_lshl_add_u64 v[126:127], v[148:149], 1, v[124:125]
	global_store_dwordx4 v[126:127], v[128:131], off
	s_movk_i32 s0, 0x2100
	s_nop 0
	v_add_u32_e32 v130, 32, v158
	v_lshlrev_b32_e32 v124, 1, v130
	v_ashrrev_i32_e32 v125, 31, v124
	v_lshl_add_u64 v[128:129], v[124:125], 2, s[34:35]
	s_nop 0
	v_cmp_gt_i32_e64 s[44:45], s0, v130
	s_movk_i32 s0, 0xff
	v_mov_b32_e32 v124, v180
	v_fmamk_f32 v124, v124, 0x3b800000, v216
	v_mul_f32_e32 v131, 0x4b800000, v124
	v_cmp_gt_f32_e64 s[46:47], s33, v124
	v_cndmask_b32_e64 v125, v226, 0, s[44:45]
	s_nop 0
	v_cndmask_b32_e64 v124, v124, v131, s[46:47]
	v_rsq_f32_e32 v131, v124
	v_add_u32_e32 v124, v125, v130
	v_cmp_lt_i32_e64 s[44:45], s0, v124
	v_add_u32_e32 v124, 0xffffff00, v124
	v_mul_f32_e32 v125, 0x45800000, v131
	v_cndmask_b32_e64 v125, v131, v125, s[46:47]
	v_mul_f32_e32 v154, 0x3e16c740, v125
	v_pk_mul_f32 v[120:121], v[120:121], v[154:155] op_sel_hi:[1,0]
	v_pk_mul_f32 v[122:123], v[122:123], v[154:155] op_sel_hi:[1,0]
	v_pk_mul_f32 v[116:117], v[116:117], v[154:155] op_sel_hi:[1,0]
	v_pk_mul_f32 v[118:119], v[118:119], v[154:155] op_sel_hi:[1,0]
	s_and_b64 s[18:19], s[40:41], s[44:45]
	s_and_saveexec_b64 s[0:1], s[18:19]
	s_cbranch_execz .LBB0_541
	v_mov_b32_e32 v125, v36
	v_lshlrev_b64 v[154:155], 7, v[124:125]
	v_lshl_add_u64 v[154:155], s[58:59], 0, v[154:155]
	v_lshl_add_u64 v[154:155], v[152:153], 2, v[154:155]
	global_load_dwordx4 v[160:163], v[154:155], off
	global_load_dwordx4 v[164:167], v[154:155], off offset:64
	s_waitcnt vmcnt(0)
	v_pk_mul_f32 v[168:169], v[120:121], v[160:161] op_sel_hi:[1,0]
	v_pk_mul_f32 v[154:155], v[120:121], v[164:165] op_sel:[1,0] op_sel_hi:[0,0]
	v_pk_mul_f32 v[164:165], v[122:123], v[164:165] op_sel:[1,1] op_sel_hi:[0,1]
	v_pk_fma_f32 v[120:121], v[120:121], v[160:161], v[154:155] op_sel_hi:[1,0,1]
	v_pk_fma_f32 v[170:171], v[122:123], v[160:161], v[164:165] op_sel:[0,1,0] neg_lo:[0,0,1] neg_hi:[0,0,1]
	v_pk_fma_f32 v[122:123], v[122:123], v[160:161], v[164:165] op_sel:[0,1,0]
	v_pk_mul_f32 v[160:161], v[116:117], v[166:167] op_sel:[1,0] op_sel_hi:[0,0]
	v_pk_fma_f32 v[164:165], v[116:117], v[162:163], v[160:161] op_sel_hi:[1,0,1] neg_lo:[0,0,1] neg_hi:[0,0,1]
	v_pk_fma_f32 v[116:117], v[116:117], v[162:163], v[160:161] op_sel_hi:[1,0,1]
	v_mov_b32_e32 v166, v163
	v_mul_f32_e32 v116, v119, v167
	v_pk_fma_f32 v[160:161], v[118:119], v[166:167], v[116:117] op_sel_hi:[1,1,0] neg_lo:[0,0,1] neg_hi:[0,0,1]
	v_mov_b32_e32 v162, v167
	v_mul_f32_e32 v116, v119, v163
	v_pk_fma_f32 v[162:163], v[118:119], v[162:163], v[116:117] op_sel_hi:[1,1,0]
	v_sub_f32_e32 v120, v168, v154
	v_mov_b32_e32 v122, v170
	v_mov_b32_e32 v116, v164
	v_mov_b32_e32 v118, v160
	v_mov_b32_e32 v119, v162
.LBB0_541:
	s_or_b64 exec, exec, s[0:1]
	v_cvt_pk_bf16_f32 v120, v120, v121
	v_cvt_pk_bf16_f32 v121, v122, v123
	v_cvt_pk_bf16_f32 v122, v116, v117
	v_mov_b64_e32 v[116:117], s[60:61]
	s_movk_i32 s0, 0x600
	v_mad_i64_i32 v[116:117], s[0:1], v130, s0, v[116:117]
	v_cvt_pk_bf16_f32 v123, v118, v119
	v_lshl_add_u64 v[118:119], v[148:149], 1, v[116:117]
	global_store_dwordx4 v[118:119], v[120:123], off
	s_movk_i32 s0, 0x2100
	s_nop 0
	v_add_u32_e32 v122, 48, v158
	v_lshlrev_b32_e32 v116, 1, v122
	v_ashrrev_i32_e32 v117, 31, v116
	v_lshl_add_u64 v[120:121], v[116:117], 2, s[34:35]
	s_nop 0
	v_cmp_gt_i32_e64 s[46:47], s0, v122
	s_movk_i32 s0, 0xff
	v_mov_b32_e32 v116, v181
	v_fmamk_f32 v116, v116, 0x3b800000, v216
	v_mul_f32_e32 v123, 0x4b800000, v116
	v_cmp_gt_f32_e64 s[48:49], s33, v116
	v_cndmask_b32_e64 v117, v226, 0, s[46:47]
	s_nop 0
	v_cndmask_b32_e64 v116, v116, v123, s[48:49]
	v_rsq_f32_e32 v123, v116
	v_add_u32_e32 v116, v117, v122
	v_cmp_lt_i32_e64 s[46:47], s0, v116
	v_add_u32_e32 v116, 0xffffff00, v116
	v_mul_f32_e32 v117, 0x45800000, v123
	v_cndmask_b32_e64 v117, v123, v117, s[48:49]
	v_mul_f32_e32 v130, 0x3e16c740, v117
	v_pk_mul_f32 v[112:113], v[112:113], v[130:131] op_sel_hi:[1,0]
	v_pk_mul_f32 v[114:115], v[114:115], v[130:131] op_sel_hi:[1,0]
	v_pk_mul_f32 v[108:109], v[108:109], v[130:131] op_sel_hi:[1,0]
	v_pk_mul_f32 v[110:111], v[110:111], v[130:131] op_sel_hi:[1,0]
	s_and_b64 s[18:19], s[40:41], s[46:47]
	s_and_saveexec_b64 s[0:1], s[18:19]
	s_cbranch_execz .LBB0_543
	v_mov_b32_e32 v117, v36
	v_lshlrev_b64 v[130:131], 7, v[116:117]
	v_lshl_add_u64 v[130:131], s[58:59], 0, v[130:131]
	v_lshl_add_u64 v[130:131], v[152:153], 2, v[130:131]
	global_load_dwordx4 v[160:163], v[130:131], off
	global_load_dwordx4 v[164:167], v[130:131], off offset:64
	s_waitcnt vmcnt(0)
	v_pk_mul_f32 v[154:155], v[112:113], v[160:161] op_sel_hi:[1,0]
	v_pk_mul_f32 v[130:131], v[112:113], v[164:165] op_sel:[1,0] op_sel_hi:[0,0]
	v_pk_mul_f32 v[164:165], v[114:115], v[164:165] op_sel:[1,1] op_sel_hi:[0,1]
	v_pk_fma_f32 v[112:113], v[112:113], v[160:161], v[130:131] op_sel_hi:[1,0,1]
	v_pk_fma_f32 v[168:169], v[114:115], v[160:161], v[164:165] op_sel:[0,1,0] neg_lo:[0,0,1] neg_hi:[0,0,1]
	v_pk_fma_f32 v[114:115], v[114:115], v[160:161], v[164:165] op_sel:[0,1,0]
	v_pk_mul_f32 v[160:161], v[108:109], v[166:167] op_sel:[1,0] op_sel_hi:[0,0]
	v_pk_fma_f32 v[164:165], v[108:109], v[162:163], v[160:161] op_sel_hi:[1,0,1] neg_lo:[0,0,1] neg_hi:[0,0,1]
	v_pk_fma_f32 v[108:109], v[108:109], v[162:163], v[160:161] op_sel_hi:[1,0,1]
	v_mov_b32_e32 v166, v163
	v_mul_f32_e32 v108, v111, v167
	v_pk_fma_f32 v[160:161], v[110:111], v[166:167], v[108:109] op_sel_hi:[1,1,0] neg_lo:[0,0,1] neg_hi:[0,0,1]
	v_mov_b32_e32 v162, v167
	v_mul_f32_e32 v108, v111, v163
	v_pk_fma_f32 v[162:163], v[110:111], v[162:163], v[108:109] op_sel_hi:[1,1,0]
	v_sub_f32_e32 v112, v154, v130
	v_mov_b32_e32 v114, v168
	v_mov_b32_e32 v108, v164
	v_mov_b32_e32 v110, v160
	v_mov_b32_e32 v111, v162
; __device__ __forceinline__ u32x4 pack8(const float* v) { u32x4 w; w.x = pk2(v[0], v[1]); w.y = pk2(v[2], v[3]); w.z = pk2(v[4], v[5]); w.w = pk2(v[6], v[7]); return w; }
;     __device__ __forceinline__ void operator()(const f32x4 (&acc)[2][2][4][2], const pg8::Unit& u, int wr, int wc, int fr, int fq) const {
;     ...
;             const int b = (t >= TB) ? 1 : 0, i = t - b * TB; const bool lat = i >= LC; const int pos = i - LC;
;             const float rstd = rsqrtf(((const float*)(ws + O_SSQ))[t * 2] * (1.f / 256.f) + EPS) * (0.10206207261596575f * LOG2E);
; #pragma unroll
;             for (int e = 0; e < 8; ++e) v[e] *= rstd;
;             const int h = c0 / 96, w = c0 - h * 96;
;             if (w >= 64 && lat) { const float* cs = (const float*)(ws + O_ROPEB) + (size_t)pos * 32 + ((w - 64) >> 1);
; #pragma unroll
;                 for (int p = 0; p < 4; ++p) { const float c = cs[p], s = cs[16 + p], a = v[2 * p], bb = v[2 * p + 1]; v[2 * p] = a * c - bb * s; v[2 * p + 1] = a * s + bb * c; } }
;             *(u32x4*)((bf16_t*)(ws + O_QB) + (size_t)t * 768 + c0) = pack8(v);
.LBB0_543:
	s_or_b64 exec, exec, s[0:1]
	v_cvt_pk_bf16_f32 v112, v112, v113
	v_cvt_pk_bf16_f32 v113, v114, v115
	v_cvt_pk_bf16_f32 v114, v108, v109
	v_mov_b64_e32 v[108:109], s[60:61]
	s_movk_i32 s0, 0x600
	v_mad_i64_i32 v[108:109], s[0:1], v122, s0, v[108:109]
	v_cvt_pk_bf16_f32 v115, v110, v111
	v_lshl_add_u64 v[110:111], v[148:149], 1, v[108:109]
	global_store_dwordx4 v[110:111], v[112:115], off
	s_movk_i32 s0, 0x2100
	s_nop 0
	v_add_u32_e32 v114, 0x80, v158
	v_lshlrev_b32_e32 v108, 1, v114
	v_ashrrev_i32_e32 v109, 31, v108
	v_lshl_add_u64 v[112:113], v[108:109], 2, s[34:35]
	s_nop 0
	v_cmp_gt_i32_e64 s[48:49], s0, v114
	s_movk_i32 s0, 0xff
	v_mov_b32_e32 v108, v182
	v_fmamk_f32 v108, v108, 0x3b800000, v216
	v_mul_f32_e32 v115, 0x4b800000, v108
	v_cmp_gt_f32_e64 s[50:51], s33, v108
	v_cndmask_b32_e64 v109, v226, 0, s[48:49]
	s_nop 0
	v_cndmask_b32_e64 v108, v108, v115, s[50:51]
	v_rsq_f32_e32 v115, v108
	v_add_u32_e32 v108, v109, v114
	v_cmp_lt_i32_e64 s[48:49], s0, v108
	v_add_u32_e32 v108, 0xffffff00, v108
	v_mul_f32_e32 v109, 0x45800000, v115
	v_cndmask_b32_e64 v109, v115, v109, s[50:51]
	v_mul_f32_e32 v122, 0x3e16c740, v109
	v_pk_mul_f32 v[104:105], v[104:105], v[122:123] op_sel_hi:[1,0]
	v_pk_mul_f32 v[106:107], v[106:107], v[122:123] op_sel_hi:[1,0]
	v_pk_mul_f32 v[100:101], v[100:101], v[122:123] op_sel_hi:[1,0]
	v_pk_mul_f32 v[102:103], v[102:103], v[122:123] op_sel_hi:[1,0]
	s_and_b64 s[18:19], s[40:41], s[48:49]
	s_and_saveexec_b64 s[0:1], s[18:19]
	s_cbranch_execz .LBB0_545
	v_mov_b32_e32 v109, v36
	v_lshlrev_b64 v[122:123], 7, v[108:109]
	v_lshl_add_u64 v[122:123], s[58:59], 0, v[122:123]
	v_lshl_add_u64 v[122:123], v[152:153], 2, v[122:123]
	global_load_dwordx4 v[160:163], v[122:123], off
	global_load_dwordx4 v[164:167], v[122:123], off offset:64
	s_waitcnt vmcnt(0)
	v_pk_mul_f32 v[130:131], v[104:105], v[160:161] op_sel_hi:[1,0]
	v_pk_mul_f32 v[154:155], v[106:107], v[164:165] op_sel:[1,1] op_sel_hi:[0,1]
	v_pk_mul_f32 v[122:123], v[104:105], v[164:165] op_sel:[1,0] op_sel_hi:[0,0]
	v_pk_fma_f32 v[164:165], v[106:107], v[160:161], v[154:155] op_sel:[0,1,0] neg_lo:[0,0,1] neg_hi:[0,0,1]
	v_pk_fma_f32 v[106:107], v[106:107], v[160:161], v[154:155] op_sel:[0,1,0]
	v_pk_mul_f32 v[154:155], v[100:101], v[166:167] op_sel:[1,0] op_sel_hi:[0,0]
	v_pk_fma_f32 v[104:105], v[104:105], v[160:161], v[122:123] op_sel_hi:[1,0,1]
	v_pk_fma_f32 v[160:161], v[100:101], v[162:163], v[154:155] op_sel_hi:[1,0,1] neg_lo:[0,0,1] neg_hi:[0,0,1]
	v_pk_fma_f32 v[100:101], v[100:101], v[162:163], v[154:155] op_sel_hi:[1,0,1]
	v_mov_b32_e32 v166, v163
	v_mul_f32_e32 v100, v103, v167
	v_pk_fma_f32 v[154:155], v[102:103], v[166:167], v[100:101] op_sel_hi:[1,1,0] neg_lo:[0,0,1] neg_hi:[0,0,1]
	v_mov_b32_e32 v162, v167
	v_mul_f32_e32 v100, v103, v163
	v_pk_fma_f32 v[162:163], v[102:103], v[162:163], v[100:101] op_sel_hi:[1,1,0]
	v_sub_f32_e32 v104, v130, v122
	v_mov_b32_e32 v106, v164
	v_mov_b32_e32 v100, v160
	v_mov_b32_e32 v102, v154
	v_mov_b32_e32 v103, v162
.LBB0_545:
	s_or_b64 exec, exec, s[0:1]
	v_cvt_pk_bf16_f32 v104, v104, v105
	v_cvt_pk_bf16_f32 v105, v106, v107
	v_cvt_pk_bf16_f32 v106, v100, v101
	v_mov_b64_e32 v[100:101], s[60:61]
	s_movk_i32 s0, 0x600
	v_mad_i64_i32 v[100:101], s[0:1], v114, s0, v[100:101]
	v_cvt_pk_bf16_f32 v107, v102, v103
	v_lshl_add_u64 v[102:103], v[148:149], 1, v[100:101]
	global_store_dwordx4 v[102:103], v[104:107], off
	s_movk_i32 s0, 0x2100
	s_nop 0
	v_add_u32_e32 v106, 0x90, v158
	v_lshlrev_b32_e32 v100, 1, v106
	v_ashrrev_i32_e32 v101, 31, v100
	v_lshl_add_u64 v[104:105], v[100:101], 2, s[34:35]
	s_nop 0
	v_cmp_gt_i32_e64 s[50:51], s0, v106
	s_movk_i32 s0, 0xff
	v_mov_b32_e32 v100, v183
	v_fmamk_f32 v100, v100, 0x3b800000, v216
	v_mul_f32_e32 v107, 0x4b800000, v100
	v_cmp_gt_f32_e64 s[52:53], s33, v100
	v_cndmask_b32_e64 v101, v226, 0, s[50:51]
	s_nop 0
	v_cndmask_b32_e64 v100, v100, v107, s[52:53]
	v_rsq_f32_e32 v107, v100
	v_add_u32_e32 v100, v101, v106
	v_cmp_lt_i32_e64 s[50:51], s0, v100
	v_add_u32_e32 v100, 0xffffff00, v100
	v_mul_f32_e32 v101, 0x45800000, v107
	v_cndmask_b32_e64 v101, v107, v101, s[52:53]
	v_mul_f32_e32 v114, 0x3e16c740, v101
	v_pk_mul_f32 v[96:97], v[96:97], v[114:115] op_sel_hi:[1,0]
	v_pk_mul_f32 v[98:99], v[98:99], v[114:115] op_sel_hi:[1,0]
	v_pk_mul_f32 v[92:93], v[92:93], v[114:115] op_sel_hi:[1,0]
	v_pk_mul_f32 v[94:95], v[94:95], v[114:115] op_sel_hi:[1,0]
	s_and_b64 s[18:19], s[40:41], s[50:51]
	s_and_saveexec_b64 s[0:1], s[18:19]
	s_cbranch_execz .LBB0_547
	v_mov_b32_e32 v101, v36
	v_lshlrev_b64 v[114:115], 7, v[100:101]
	v_lshl_add_u64 v[114:115], s[58:59], 0, v[114:115]
	v_lshl_add_u64 v[114:115], v[152:153], 2, v[114:115]
	global_load_dwordx4 v[160:163], v[114:115], off
	global_load_dwordx4 v[164:167], v[114:115], off offset:64
	s_waitcnt vmcnt(0)
	v_pk_mul_f32 v[122:123], v[96:97], v[160:161] op_sel_hi:[1,0]
	v_pk_mul_f32 v[130:131], v[98:99], v[164:165] op_sel:[1,1] op_sel_hi:[0,1]
	v_pk_mul_f32 v[114:115], v[96:97], v[164:165] op_sel:[1,0] op_sel_hi:[0,0]
	v_pk_fma_f32 v[154:155], v[98:99], v[160:161], v[130:131] op_sel:[0,1,0] neg_lo:[0,0,1] neg_hi:[0,0,1]
	v_pk_fma_f32 v[98:99], v[98:99], v[160:161], v[130:131] op_sel:[0,1,0]
	v_pk_mul_f32 v[130:131], v[92:93], v[166:167] op_sel:[1,0] op_sel_hi:[0,0]
	v_pk_fma_f32 v[96:97], v[96:97], v[160:161], v[114:115] op_sel_hi:[1,0,1]
	v_pk_fma_f32 v[160:161], v[92:93], v[162:163], v[130:131] op_sel_hi:[1,0,1] neg_lo:[0,0,1] neg_hi:[0,0,1]
	v_pk_fma_f32 v[92:93], v[92:93], v[162:163], v[130:131] op_sel_hi:[1,0,1]
	v_mov_b32_e32 v166, v163
	v_mul_f32_e32 v92, v95, v167
	v_pk_fma_f32 v[130:131], v[94:95], v[166:167], v[92:93] op_sel_hi:[1,1,0] neg_lo:[0,0,1] neg_hi:[0,0,1]
	v_mov_b32_e32 v162, v167
	v_mul_f32_e32 v92, v95, v163
	v_pk_fma_f32 v[162:163], v[94:95], v[162:163], v[92:93] op_sel_hi:[1,1,0]
	v_sub_f32_e32 v96, v122, v114
	v_mov_b32_e32 v98, v154
	v_mov_b32_e32 v92, v160
	v_mov_b32_e32 v94, v130
	v_mov_b32_e32 v95, v162
; __device__ __forceinline__ u32x4 pack8(const float* v) { u32x4 w; w.x = pk2(v[0], v[1]); w.y = pk2(v[2], v[3]); w.z = pk2(v[4], v[5]); w.w = pk2(v[6], v[7]); return w; }
;     __device__ __forceinline__ void operator()(const f32x4 (&acc)[2][2][4][2], const pg8::Unit& u, int wr, int wc, int fr, int fq) const {
;     ...
;             const int b = (t >= TB) ? 1 : 0, i = t - b * TB; const bool lat = i >= LC; const int pos = i - LC;
;             const float rstd = rsqrtf(((const float*)(ws + O_SSQ))[t * 2] * (1.f / 256.f) + EPS) * (0.10206207261596575f * LOG2E);
; #pragma unroll
;             for (int e = 0; e < 8; ++e) v[e] *= rstd;
;             const int h = c0 / 96, w = c0 - h * 96;
;             if (w >= 64 && lat) { const float* cs = (const float*)(ws + O_ROPEB) + (size_t)pos * 32 + ((w - 64) >> 1);
; #pragma unroll
;                 for (int p = 0; p < 4; ++p) { const float c = cs[p], s = cs[16 + p], a = v[2 * p], bb = v[2 * p + 1]; v[2 * p] = a * c - bb * s; v[2 * p + 1] = a * s + bb * c; } }
;             *(u32x4*)((bf16_t*)(ws + O_QB) + (size_t)t * 768 + c0) = pack8(v);
.LBB0_547:
	s_or_b64 exec, exec, s[0:1]
	v_cvt_pk_bf16_f32 v96, v96, v97
	v_cvt_pk_bf16_f32 v97, v98, v99
	v_cvt_pk_bf16_f32 v98, v92, v93
	v_mov_b64_e32 v[92:93], s[60:61]
	s_movk_i32 s0, 0x600
	v_mad_i64_i32 v[92:93], s[0:1], v106, s0, v[92:93]
	v_cvt_pk_bf16_f32 v99, v94, v95
	v_lshl_add_u64 v[94:95], v[148:149], 1, v[92:93]
	global_store_dwordx4 v[94:95], v[96:99], off
	s_movk_i32 s0, 0x2100
	s_nop 0
	v_add_u32_e32 v98, 0xa0, v158
	v_lshlrev_b32_e32 v92, 1, v98
	v_ashrrev_i32_e32 v93, 31, v92
	v_lshl_add_u64 v[96:97], v[92:93], 2, s[34:35]
	s_nop 0
	v_cmp_gt_i32_e64 s[52:53], s0, v98
	s_movk_i32 s0, 0xff
	v_mov_b32_e32 v92, v184
	v_fmamk_f32 v92, v92, 0x3b800000, v216
	v_mul_f32_e32 v99, 0x4b800000, v92
	v_cmp_gt_f32_e64 s[54:55], s33, v92
	v_cndmask_b32_e64 v93, v226, 0, s[52:53]
	s_nop 0
	v_cndmask_b32_e64 v92, v92, v99, s[54:55]
	v_rsq_f32_e32 v99, v92
	v_add_u32_e32 v92, v93, v98
	v_cmp_lt_i32_e64 s[52:53], s0, v92
	v_add_u32_e32 v92, 0xffffff00, v92
	v_mul_f32_e32 v93, 0x45800000, v99
	v_cndmask_b32_e64 v93, v99, v93, s[54:55]
	v_mul_f32_e32 v106, 0x3e16c740, v93
	v_pk_mul_f32 v[88:89], v[88:89], v[106:107] op_sel_hi:[1,0]
	v_pk_mul_f32 v[90:91], v[90:91], v[106:107] op_sel_hi:[1,0]
	v_pk_mul_f32 v[84:85], v[84:85], v[106:107] op_sel_hi:[1,0]
	v_pk_mul_f32 v[86:87], v[86:87], v[106:107] op_sel_hi:[1,0]
	s_and_b64 s[18:19], s[40:41], s[52:53]
	s_and_saveexec_b64 s[0:1], s[18:19]
	s_cbranch_execz .LBB0_549
	v_mov_b32_e32 v93, v36
	v_lshlrev_b64 v[106:107], 7, v[92:93]
	v_lshl_add_u64 v[106:107], s[58:59], 0, v[106:107]
	v_lshl_add_u64 v[106:107], v[152:153], 2, v[106:107]
	global_load_dwordx4 v[160:163], v[106:107], off
	global_load_dwordx4 v[164:167], v[106:107], off offset:64
	s_waitcnt vmcnt(0)
	v_pk_mul_f32 v[114:115], v[88:89], v[160:161] op_sel_hi:[1,0]
	v_pk_mul_f32 v[122:123], v[90:91], v[164:165] op_sel:[1,1] op_sel_hi:[0,1]
	v_pk_fma_f32 v[130:131], v[90:91], v[160:161], v[122:123] op_sel:[0,1,0] neg_lo:[0,0,1] neg_hi:[0,0,1]
	v_pk_fma_f32 v[90:91], v[90:91], v[160:161], v[122:123] op_sel:[0,1,0]
	v_pk_mul_f32 v[122:123], v[84:85], v[166:167] op_sel:[1,0] op_sel_hi:[0,0]
	v_pk_fma_f32 v[154:155], v[84:85], v[162:163], v[122:123] op_sel_hi:[1,0,1] neg_lo:[0,0,1] neg_hi:[0,0,1]
	v_pk_fma_f32 v[84:85], v[84:85], v[162:163], v[122:123] op_sel_hi:[1,0,1]
	v_mov_b32_e32 v166, v163
	v_mul_f32_e32 v84, v87, v167
	v_pk_mul_f32 v[106:107], v[88:89], v[164:165] op_sel:[1,0] op_sel_hi:[0,0]
	v_pk_fma_f32 v[122:123], v[86:87], v[166:167], v[84:85] op_sel_hi:[1,1,0] neg_lo:[0,0,1] neg_hi:[0,0,1]
	v_mov_b32_e32 v162, v167
	v_mul_f32_e32 v84, v87, v163
	v_pk_fma_f32 v[88:89], v[88:89], v[160:161], v[106:107] op_sel_hi:[1,0,1]
	v_pk_fma_f32 v[160:161], v[86:87], v[162:163], v[84:85] op_sel_hi:[1,1,0]
	v_sub_f32_e32 v88, v114, v106
	v_mov_b32_e32 v90, v130
	v_mov_b32_e32 v84, v154
	v_mov_b32_e32 v86, v122
	v_mov_b32_e32 v87, v160
.LBB0_549:
	s_or_b64 exec, exec, s[0:1]
	v_cvt_pk_bf16_f32 v88, v88, v89
	v_cvt_pk_bf16_f32 v89, v90, v91
	v_cvt_pk_bf16_f32 v90, v84, v85
	v_mov_b64_e32 v[84:85], s[60:61]
	s_movk_i32 s0, 0x600
	v_mad_i64_i32 v[84:85], s[0:1], v98, s0, v[84:85]
	v_cvt_pk_bf16_f32 v91, v86, v87
	v_lshl_add_u64 v[86:87], v[148:149], 1, v[84:85]
	global_store_dwordx4 v[86:87], v[88:91], off
	s_movk_i32 s0, 0x2100
	s_nop 0
	v_add_u32_e32 v90, 0xb0, v158
	v_lshlrev_b32_e32 v84, 1, v90
	v_ashrrev_i32_e32 v85, 31, v84
	v_lshl_add_u64 v[88:89], v[84:85], 2, s[34:35]
	s_nop 0
	v_cmp_gt_i32_e64 s[54:55], s0, v90
	s_movk_i32 s0, 0xff
	v_mov_b32_e32 v84, v185
	v_fmamk_f32 v84, v84, 0x3b800000, v216
	v_mul_f32_e32 v91, 0x4b800000, v84
	v_cmp_gt_f32_e64 s[56:57], s33, v84
	v_cndmask_b32_e64 v85, v226, 0, s[54:55]
	s_nop 0
	v_cndmask_b32_e64 v84, v84, v91, s[56:57]
	v_rsq_f32_e32 v91, v84
	v_add_u32_e32 v84, v85, v90
	v_cmp_lt_i32_e64 s[54:55], s0, v84
	v_add_u32_e32 v84, 0xffffff00, v84
	v_mul_f32_e32 v85, 0x45800000, v91
	v_cndmask_b32_e64 v85, v91, v85, s[56:57]
	v_mul_f32_e32 v98, 0x3e16c740, v85
	v_pk_mul_f32 v[80:81], v[80:81], v[98:99] op_sel_hi:[1,0]
	v_pk_mul_f32 v[82:83], v[82:83], v[98:99] op_sel_hi:[1,0]
	v_pk_mul_f32 v[76:77], v[76:77], v[98:99] op_sel_hi:[1,0]
	v_pk_mul_f32 v[78:79], v[78:79], v[98:99] op_sel_hi:[1,0]
	s_and_b64 s[18:19], s[40:41], s[54:55]
	s_and_saveexec_b64 s[0:1], s[18:19]
	s_cbranch_execz .LBB0_551
	v_mov_b32_e32 v85, v36
	v_lshlrev_b64 v[98:99], 7, v[84:85]
	v_lshl_add_u64 v[98:99], s[58:59], 0, v[98:99]
	v_lshl_add_u64 v[98:99], v[152:153], 2, v[98:99]
	global_load_dwordx4 v[152:155], v[98:99], off
	global_load_dwordx4 v[158:161], v[98:99], off offset:64
	s_waitcnt vmcnt(0)
	v_pk_mul_f32 v[106:107], v[80:81], v[152:153] op_sel_hi:[1,0]
	v_pk_mul_f32 v[114:115], v[82:83], v[158:159] op_sel:[1,1] op_sel_hi:[0,1]
	v_pk_fma_f32 v[122:123], v[82:83], v[152:153], v[114:115] op_sel:[0,1,0] neg_lo:[0,0,1] neg_hi:[0,0,1]
	v_pk_fma_f32 v[82:83], v[82:83], v[152:153], v[114:115] op_sel:[0,1,0]
	v_pk_mul_f32 v[114:115], v[76:77], v[160:161] op_sel:[1,0] op_sel_hi:[0,0]
	v_pk_fma_f32 v[130:131], v[76:77], v[154:155], v[114:115] op_sel_hi:[1,0,1] neg_lo:[0,0,1] neg_hi:[0,0,1]
	v_pk_fma_f32 v[76:77], v[76:77], v[154:155], v[114:115] op_sel_hi:[1,0,1]
	v_mov_b32_e32 v160, v155
	v_mul_f32_e32 v76, v79, v161
	v_pk_mul_f32 v[98:99], v[80:81], v[158:159] op_sel:[1,0] op_sel_hi:[0,0]
	v_pk_fma_f32 v[114:115], v[78:79], v[160:161], v[76:77] op_sel_hi:[1,1,0] neg_lo:[0,0,1] neg_hi:[0,0,1]
	v_mov_b32_e32 v154, v161
	v_mul_f32_e32 v76, v79, v155
	v_pk_fma_f32 v[80:81], v[80:81], v[152:153], v[98:99] op_sel_hi:[1,0,1]
	v_pk_fma_f32 v[152:153], v[78:79], v[154:155], v[76:77] op_sel_hi:[1,1,0]
	v_sub_f32_e32 v80, v106, v98
	v_mov_b32_e32 v82, v122
	v_mov_b32_e32 v76, v130
	v_mov_b32_e32 v78, v114
	v_mov_b32_e32 v79, v152
; __device__ __forceinline__ u32x4 pack8(const float* v) { u32x4 w; w.x = pk2(v[0], v[1]); w.y = pk2(v[2], v[3]); w.z = pk2(v[4], v[5]); w.w = pk2(v[6], v[7]); return w; }
; #define EPI_LOOP_END asm volatile("" ::: "memory"); } }
;     __device__ __forceinline__ void operator()(const f32x4 (&acc)[2][2][4][2], const pg8::Unit& u, int wr, int wc, int fr, int fq) const {
;         EPI_LOOP_BEGIN
;             const int b = (t >= TB) ? 1 : 0, i = t - b * TB; const bool lat = i >= LC; const int pos = i - LC;
;             const float rstd = rsqrtf(((const float*)(ws + O_SSQ))[t * 2] * (1.f / 256.f) + EPS) * (0.10206207261596575f * LOG2E);
; #pragma unroll
;             for (int e = 0; e < 8; ++e) v[e] *= rstd;
;             const int h = c0 / 96, w = c0 - h * 96;
;             if (w >= 64 && lat) { const float* cs = (const float*)(ws + O_ROPEB) + (size_t)pos * 32 + ((w - 64) >> 1);
; #pragma unroll
;                 for (int p = 0; p < 4; ++p) { const float c = cs[p], s = cs[16 + p], a = v[2 * p], bb = v[2 * p + 1]; v[2 * p] = a * c - bb * s; v[2 * p + 1] = a * s + bb * c; } }
;             *(u32x4*)((bf16_t*)(ws + O_QB) + (size_t)t * 768 + c0) = pack8(v);
;         EPI_LOOP_END
.LBB0_551:
	s_or_b64 exec, exec, s[0:1]
	v_cvt_pk_bf16_f32 v80, v80, v81
	v_cvt_pk_bf16_f32 v81, v82, v83
	v_cvt_pk_bf16_f32 v82, v76, v77
	v_mov_b64_e32 v[76:77], s[60:61]
	s_movk_i32 s0, 0x600
	v_mad_i64_i32 v[76:77], s[0:1], v90, s0, v[76:77]
	v_cvt_pk_bf16_f32 v83, v78, v79
	v_lshl_add_u64 v[76:77], v[148:149], 1, v[76:77]
	global_store_dwordx4 v[76:77], v[80:83], off
	s_nop 0
	s_mov_b32 s0, 0x2aaaaaab
	v_add_u32_e32 v80, 0x80, v148
	v_mul_hi_i32 v81, v80, s0
	v_lshrrev_b32_e32 v82, 31, v81
	v_lshrrev_b32_e32 v81, 4, v81
	v_add_u32_e32 v81, v81, v82
	s_movk_i32 s0, 0x60
	v_mul_lo_u32 v81, v81, s0
	v_sub_u32_e32 v80, v80, v81
	v_cmp_lt_i32_e64 s[40:41], 63, v80
	v_mov_b32_e32 v79, v36
	s_and_b64 s[18:19], s[40:41], vcc
	v_mov_b32_e32 v78, v178
	v_fmamk_f32 v78, v78, 0x3b800000, v216
	v_mul_f32_e32 v81, 0x4b800000, v78
	v_cmp_gt_f32_e64 s[56:57], s33, v78
	s_nop 1
	v_cndmask_b32_e64 v78, v78, v81, s[56:57]
	v_rsq_f32_e32 v81, v78
	v_subrev_u32_e32 v78, 64, v80
	v_lshrrev_b32_e32 v78, 1, v78
	v_mul_f32_e32 v80, 0x45800000, v81
	v_cndmask_b32_e64 v80, v81, v80, s[56:57]
	v_mul_f32_e32 v80, 0x3e16c740, v80
	v_pk_mul_f32 v[72:73], v[72:73], v[80:81] op_sel_hi:[1,0]
	v_pk_mul_f32 v[74:75], v[74:75], v[80:81] op_sel_hi:[1,0]
	v_pk_mul_f32 v[68:69], v[68:69], v[80:81] op_sel_hi:[1,0]
	v_pk_mul_f32 v[70:71], v[70:71], v[80:81] op_sel_hi:[1,0]
	s_and_saveexec_b64 s[0:1], s[18:19]
	s_cbranch_execz .LBB0_553
	v_mov_b32_e32 v133, v36
	v_lshlrev_b64 v[80:81], 7, v[132:133]
	v_lshl_add_u64 v[80:81], s[58:59], 0, v[80:81]
	v_lshl_add_u64 v[90:91], v[78:79], 2, v[80:81]
	global_load_dwordx4 v[80:83], v[90:91], off
	global_load_dwordx4 v[130:133], v[90:91], off offset:64
	s_waitcnt vmcnt(0)
	v_pk_mul_f32 v[98:99], v[72:73], v[80:81] op_sel_hi:[1,0]
	v_pk_mul_f32 v[90:91], v[72:73], v[130:131] op_sel:[1,0] op_sel_hi:[0,0]
	v_pk_mul_f32 v[106:107], v[74:75], v[130:131] op_sel:[1,1] op_sel_hi:[0,1]
	v_pk_fma_f32 v[72:73], v[72:73], v[80:81], v[90:91] op_sel_hi:[1,0,1]
	v_pk_fma_f32 v[114:115], v[74:75], v[80:81], v[106:107] op_sel:[0,1,0] neg_lo:[0,0,1] neg_hi:[0,0,1]
	v_pk_fma_f32 v[74:75], v[74:75], v[80:81], v[106:107] op_sel:[0,1,0]
	v_pk_mul_f32 v[80:81], v[68:69], v[132:133] op_sel:[1,0] op_sel_hi:[0,0]
	v_pk_fma_f32 v[106:107], v[68:69], v[82:83], v[80:81] op_sel_hi:[1,0,1] neg_lo:[0,0,1] neg_hi:[0,0,1]
	v_pk_fma_f32 v[68:69], v[68:69], v[82:83], v[80:81] op_sel_hi:[1,0,1]
	v_mov_b32_e32 v132, v83
	v_mul_f32_e32 v68, v71, v133
	v_pk_fma_f32 v[80:81], v[70:71], v[132:133], v[68:69] op_sel_hi:[1,1,0] neg_lo:[0,0,1] neg_hi:[0,0,1]
	v_mov_b32_e32 v82, v133
	v_mul_f32_e32 v68, v71, v83
	v_pk_fma_f32 v[82:83], v[70:71], v[82:83], v[68:69] op_sel_hi:[1,1,0]
	v_sub_f32_e32 v72, v98, v90
	v_mov_b32_e32 v74, v114
	v_mov_b32_e32 v68, v106
	v_mov_b32_e32 v70, v80
	v_mov_b32_e32 v71, v82
.LBB0_553:
	s_or_b64 exec, exec, s[0:1]
	v_cvt_pk_bf16_f32 v72, v72, v73
	v_cvt_pk_bf16_f32 v73, v74, v75
	v_cvt_pk_bf16_f32 v74, v68, v69
	v_cvt_pk_bf16_f32 v75, v70, v71
	global_store_dwordx4 v[136:137], v[72:75], off offset:256
	s_nop 0
	s_and_b64 s[18:19], s[40:41], s[42:43]
	v_mov_b32_e32 v68, v179
	v_fmamk_f32 v68, v68, 0x3b800000, v216
	v_mul_f32_e32 v69, 0x4b800000, v68
	v_cmp_gt_f32_e32 vcc, s33, v68
	s_nop 1
	v_cndmask_b32_e32 v68, v68, v69, vcc
	v_rsq_f32_e32 v68, v68
	s_nop 0
	v_mul_f32_e32 v69, 0x45800000, v68
	v_cndmask_b32_e32 v68, v68, v69, vcc
	v_mul_f32_e32 v68, 0x3e16c740, v68
	v_pk_mul_f32 v[64:65], v[64:65], v[68:69] op_sel_hi:[1,0]
	v_pk_mul_f32 v[66:67], v[66:67], v[68:69] op_sel_hi:[1,0]
	v_pk_mul_f32 v[60:61], v[60:61], v[68:69] op_sel_hi:[1,0]
	v_pk_mul_f32 v[62:63], v[62:63], v[68:69] op_sel_hi:[1,0]
	s_and_saveexec_b64 s[0:1], s[18:19]
	s_cbranch_execz .LBB0_555
	v_mov_b32_e32 v135, v36
	v_lshlrev_b64 v[68:69], 7, v[134:135]
	v_lshl_add_u64 v[68:69], s[58:59], 0, v[68:69]
	v_lshl_add_u64 v[72:73], v[78:79], 2, v[68:69]
	global_load_dwordx4 v[68:71], v[72:73], off
	s_nop 0
	global_load_dwordx4 v[72:75], v[72:73], off offset:64
	s_waitcnt vmcnt(0)
	v_pk_mul_f32 v[82:83], v[64:65], v[68:69] op_sel_hi:[1,0]
	v_pk_mul_f32 v[80:81], v[64:65], v[72:73] op_sel:[1,0] op_sel_hi:[0,0]
	v_pk_mul_f32 v[72:73], v[66:67], v[72:73] op_sel:[1,1] op_sel_hi:[0,1]
	v_pk_fma_f32 v[64:65], v[64:65], v[68:69], v[80:81] op_sel_hi:[1,0,1]
	v_pk_fma_f32 v[90:91], v[66:67], v[68:69], v[72:73] op_sel:[0,1,0] neg_lo:[0,0,1] neg_hi:[0,0,1]
	v_pk_fma_f32 v[66:67], v[66:67], v[68:69], v[72:73] op_sel:[0,1,0]
	v_pk_mul_f32 v[68:69], v[60:61], v[74:75] op_sel:[1,0] op_sel_hi:[0,0]
	v_pk_fma_f32 v[72:73], v[60:61], v[70:71], v[68:69] op_sel_hi:[1,0,1] neg_lo:[0,0,1] neg_hi:[0,0,1]
	v_pk_fma_f32 v[60:61], v[60:61], v[70:71], v[68:69] op_sel_hi:[1,0,1]
	v_mov_b32_e32 v74, v71
	v_mul_f32_e32 v60, v63, v75
	v_pk_fma_f32 v[68:69], v[62:63], v[74:75], v[60:61] op_sel_hi:[1,1,0] neg_lo:[0,0,1] neg_hi:[0,0,1]
	v_mov_b32_e32 v70, v75
	v_mul_f32_e32 v60, v63, v71
	v_pk_fma_f32 v[70:71], v[62:63], v[70:71], v[60:61] op_sel_hi:[1,1,0]
	v_sub_f32_e32 v64, v82, v80
	v_mov_b32_e32 v66, v90
	v_mov_b32_e32 v60, v72
	v_mov_b32_e32 v62, v68
	v_mov_b32_e32 v63, v70
; __device__ __forceinline__ u32x4 pack8(const float* v) { u32x4 w; w.x = pk2(v[0], v[1]); w.y = pk2(v[2], v[3]); w.z = pk2(v[4], v[5]); w.w = pk2(v[6], v[7]); return w; }
; #define EPI_LOOP_END asm volatile("" ::: "memory"); } }
;     __device__ __forceinline__ void operator()(const f32x4 (&acc)[2][2][4][2], const pg8::Unit& u, int wr, int wc, int fr, int fq) const {
;         EPI_LOOP_BEGIN
;             const int b = (t >= TB) ? 1 : 0, i = t - b * TB; const bool lat = i >= LC; const int pos = i - LC;
;             const float rstd = rsqrtf(((const float*)(ws + O_SSQ))[t * 2] * (1.f / 256.f) + EPS) * (0.10206207261596575f * LOG2E);
; #pragma unroll
;             for (int e = 0; e < 8; ++e) v[e] *= rstd;
;             const int h = c0 / 96, w = c0 - h * 96;
;             if (w >= 64 && lat) { const float* cs = (const float*)(ws + O_ROPEB) + (size_t)pos * 32 + ((w - 64) >> 1);
; #pragma unroll
;                 for (int p = 0; p < 4; ++p) { const float c = cs[p], s = cs[16 + p], a = v[2 * p], bb = v[2 * p + 1]; v[2 * p] = a * c - bb * s; v[2 * p + 1] = a * s + bb * c; } }
;             *(u32x4*)((bf16_t*)(ws + O_QB) + (size_t)t * 768 + c0) = pack8(v);
;         EPI_LOOP_END
.LBB0_555:
	s_or_b64 exec, exec, s[0:1]
	v_cvt_pk_bf16_f32 v64, v64, v65
	v_cvt_pk_bf16_f32 v65, v66, v67
	v_cvt_pk_bf16_f32 v66, v60, v61
	v_cvt_pk_bf16_f32 v67, v62, v63
	global_store_dwordx4 v[126:127], v[64:67], off offset:256
	s_nop 0
	s_and_b64 s[18:19], s[40:41], s[44:45]
	v_mov_b32_e32 v60, v180
	v_fmamk_f32 v60, v60, 0x3b800000, v216
	v_mul_f32_e32 v61, 0x4b800000, v60
	v_cmp_gt_f32_e32 vcc, s33, v60
	s_nop 1
	v_cndmask_b32_e32 v60, v60, v61, vcc
	v_rsq_f32_e32 v60, v60
	s_nop 0
	v_mul_f32_e32 v61, 0x45800000, v60
	v_cndmask_b32_e32 v60, v60, v61, vcc
	v_mul_f32_e32 v60, 0x3e16c740, v60
	v_pk_mul_f32 v[56:57], v[56:57], v[60:61] op_sel_hi:[1,0]
	v_pk_mul_f32 v[58:59], v[58:59], v[60:61] op_sel_hi:[1,0]
	v_pk_mul_f32 v[52:53], v[52:53], v[60:61] op_sel_hi:[1,0]
	v_pk_mul_f32 v[54:55], v[54:55], v[60:61] op_sel_hi:[1,0]
	s_and_saveexec_b64 s[0:1], s[18:19]
	s_cbranch_execz .LBB0_557
	v_mov_b32_e32 v125, v36
	v_lshlrev_b64 v[60:61], 7, v[124:125]
	v_lshl_add_u64 v[60:61], s[58:59], 0, v[60:61]
	v_lshl_add_u64 v[64:65], v[78:79], 2, v[60:61]
	global_load_dwordx4 v[60:63], v[64:65], off
	s_nop 0
	global_load_dwordx4 v[64:67], v[64:65], off offset:64
	s_waitcnt vmcnt(0)
	v_pk_mul_f32 v[70:71], v[56:57], v[60:61] op_sel_hi:[1,0]
	v_pk_mul_f32 v[68:69], v[56:57], v[64:65] op_sel:[1,0] op_sel_hi:[0,0]
	v_pk_mul_f32 v[64:65], v[58:59], v[64:65] op_sel:[1,1] op_sel_hi:[0,1]
	v_pk_fma_f32 v[56:57], v[56:57], v[60:61], v[68:69] op_sel_hi:[1,0,1]
	v_pk_fma_f32 v[72:73], v[58:59], v[60:61], v[64:65] op_sel:[0,1,0] neg_lo:[0,0,1] neg_hi:[0,0,1]
	v_pk_fma_f32 v[58:59], v[58:59], v[60:61], v[64:65] op_sel:[0,1,0]
	v_pk_mul_f32 v[60:61], v[52:53], v[66:67] op_sel:[1,0] op_sel_hi:[0,0]
	v_pk_fma_f32 v[64:65], v[52:53], v[62:63], v[60:61] op_sel_hi:[1,0,1] neg_lo:[0,0,1] neg_hi:[0,0,1]
	v_pk_fma_f32 v[52:53], v[52:53], v[62:63], v[60:61] op_sel_hi:[1,0,1]
	v_mov_b32_e32 v66, v63
	v_mul_f32_e32 v52, v55, v67
	v_pk_fma_f32 v[60:61], v[54:55], v[66:67], v[52:53] op_sel_hi:[1,1,0] neg_lo:[0,0,1] neg_hi:[0,0,1]
	v_mov_b32_e32 v62, v67
	v_mul_f32_e32 v52, v55, v63
	v_pk_fma_f32 v[62:63], v[54:55], v[62:63], v[52:53] op_sel_hi:[1,1,0]
	v_sub_f32_e32 v56, v70, v68
	v_mov_b32_e32 v58, v72
	v_mov_b32_e32 v52, v64
	v_mov_b32_e32 v54, v60
	v_mov_b32_e32 v55, v62
.LBB0_557:
	s_or_b64 exec, exec, s[0:1]
	v_cvt_pk_bf16_f32 v56, v56, v57
	v_cvt_pk_bf16_f32 v57, v58, v59
	v_cvt_pk_bf16_f32 v58, v52, v53
	v_cvt_pk_bf16_f32 v59, v54, v55
	global_store_dwordx4 v[118:119], v[56:59], off offset:256
	s_nop 0
	s_and_b64 s[18:19], s[40:41], s[46:47]
	v_mov_b32_e32 v52, v181
	v_fmamk_f32 v52, v52, 0x3b800000, v216
	v_mul_f32_e32 v53, 0x4b800000, v52
	v_cmp_gt_f32_e32 vcc, s33, v52
	s_nop 1
	v_cndmask_b32_e32 v52, v52, v53, vcc
	v_rsq_f32_e32 v52, v52
	s_nop 0
	v_mul_f32_e32 v53, 0x45800000, v52
	v_cndmask_b32_e32 v52, v52, v53, vcc
	v_mul_f32_e32 v52, 0x3e16c740, v52
	v_pk_mul_f32 v[48:49], v[48:49], v[52:53] op_sel_hi:[1,0]
	v_pk_mul_f32 v[50:51], v[50:51], v[52:53] op_sel_hi:[1,0]
	v_pk_mul_f32 v[32:33], v[32:33], v[52:53] op_sel_hi:[1,0]
	v_pk_mul_f32 v[34:35], v[34:35], v[52:53] op_sel_hi:[1,0]
	s_and_saveexec_b64 s[0:1], s[18:19]
	s_cbranch_execz .LBB0_559
	v_mov_b32_e32 v117, v36
	v_lshlrev_b64 v[52:53], 7, v[116:117]
	v_lshl_add_u64 v[52:53], s[58:59], 0, v[52:53]
	v_lshl_add_u64 v[56:57], v[78:79], 2, v[52:53]
	global_load_dwordx4 v[52:55], v[56:57], off
	s_nop 0
	global_load_dwordx4 v[56:59], v[56:57], off offset:64
	s_waitcnt vmcnt(0)
	v_pk_mul_f32 v[62:63], v[48:49], v[52:53] op_sel_hi:[1,0]
	v_pk_mul_f32 v[60:61], v[48:49], v[56:57] op_sel:[1,0] op_sel_hi:[0,0]
	v_pk_mul_f32 v[56:57], v[50:51], v[56:57] op_sel:[1,1] op_sel_hi:[0,1]
	v_pk_fma_f32 v[48:49], v[48:49], v[52:53], v[60:61] op_sel_hi:[1,0,1]
	v_pk_fma_f32 v[64:65], v[50:51], v[52:53], v[56:57] op_sel:[0,1,0] neg_lo:[0,0,1] neg_hi:[0,0,1]
	v_pk_fma_f32 v[50:51], v[50:51], v[52:53], v[56:57] op_sel:[0,1,0]
	v_pk_mul_f32 v[52:53], v[32:33], v[58:59] op_sel:[1,0] op_sel_hi:[0,0]
	v_pk_fma_f32 v[56:57], v[32:33], v[54:55], v[52:53] op_sel_hi:[1,0,1] neg_lo:[0,0,1] neg_hi:[0,0,1]
	v_pk_fma_f32 v[32:33], v[32:33], v[54:55], v[52:53] op_sel_hi:[1,0,1]
	v_mov_b32_e32 v58, v55
	v_mul_f32_e32 v32, v35, v59
	v_pk_fma_f32 v[52:53], v[34:35], v[58:59], v[32:33] op_sel_hi:[1,1,0] neg_lo:[0,0,1] neg_hi:[0,0,1]
	v_mov_b32_e32 v54, v59
	v_mul_f32_e32 v32, v35, v55
	v_pk_fma_f32 v[54:55], v[34:35], v[54:55], v[32:33] op_sel_hi:[1,1,0]
	v_sub_f32_e32 v48, v62, v60
	v_mov_b32_e32 v50, v64
	v_mov_b32_e32 v32, v56
	v_mov_b32_e32 v34, v52
	v_mov_b32_e32 v35, v54
; __device__ __forceinline__ u32x4 pack8(const float* v) { u32x4 w; w.x = pk2(v[0], v[1]); w.y = pk2(v[2], v[3]); w.z = pk2(v[4], v[5]); w.w = pk2(v[6], v[7]); return w; }
; #define EPI_LOOP_END asm volatile("" ::: "memory"); } }
;     __device__ __forceinline__ void operator()(const f32x4 (&acc)[2][2][4][2], const pg8::Unit& u, int wr, int wc, int fr, int fq) const {
;         EPI_LOOP_BEGIN
;             const int b = (t >= TB) ? 1 : 0, i = t - b * TB; const bool lat = i >= LC; const int pos = i - LC;
;             const float rstd = rsqrtf(((const float*)(ws + O_SSQ))[t * 2] * (1.f / 256.f) + EPS) * (0.10206207261596575f * LOG2E);
; #pragma unroll
;             for (int e = 0; e < 8; ++e) v[e] *= rstd;
;             const int h = c0 / 96, w = c0 - h * 96;
;             if (w >= 64 && lat) { const float* cs = (const float*)(ws + O_ROPEB) + (size_t)pos * 32 + ((w - 64) >> 1);
; #pragma unroll
;                 for (int p = 0; p < 4; ++p) { const float c = cs[p], s = cs[16 + p], a = v[2 * p], bb = v[2 * p + 1]; v[2 * p] = a * c - bb * s; v[2 * p + 1] = a * s + bb * c; } }
;             *(u32x4*)((bf16_t*)(ws + O_QB) + (size_t)t * 768 + c0) = pack8(v);
;         EPI_LOOP_END
.LBB0_559:
	s_or_b64 exec, exec, s[0:1]
	v_cvt_pk_bf16_f32 v48, v48, v49
	v_cvt_pk_bf16_f32 v49, v50, v51
	v_cvt_pk_bf16_f32 v50, v32, v33
	v_cvt_pk_bf16_f32 v51, v34, v35
	global_store_dwordx4 v[110:111], v[48:51], off offset:256
	s_nop 0
	s_and_b64 s[18:19], s[40:41], s[48:49]
	v_mov_b32_e32 v32, v182
	v_fmamk_f32 v32, v32, 0x3b800000, v216
	v_mul_f32_e32 v33, 0x4b800000, v32
	v_cmp_gt_f32_e32 vcc, s33, v32
	s_nop 1
	v_cndmask_b32_e32 v32, v32, v33, vcc
	v_rsq_f32_e32 v32, v32
	s_nop 0
	v_mul_f32_e32 v33, 0x45800000, v32
	v_cndmask_b32_e32 v32, v32, v33, vcc
	v_mul_f32_e32 v32, 0x3e16c740, v32
	v_pk_mul_f32 v[28:29], v[28:29], v[32:33] op_sel_hi:[1,0]
	v_pk_mul_f32 v[30:31], v[30:31], v[32:33] op_sel_hi:[1,0]
	v_pk_mul_f32 v[24:25], v[24:25], v[32:33] op_sel_hi:[1,0]
	v_pk_mul_f32 v[26:27], v[26:27], v[32:33] op_sel_hi:[1,0]
	s_and_saveexec_b64 s[0:1], s[18:19]
	s_cbranch_execz .LBB0_561
	v_mov_b32_e32 v109, v36
	v_lshlrev_b64 v[32:33], 7, v[108:109]
	v_lshl_add_u64 v[32:33], s[58:59], 0, v[32:33]
	v_lshl_add_u64 v[48:49], v[78:79], 2, v[32:33]
	global_load_dwordx4 v[32:35], v[48:49], off
	s_nop 0
	global_load_dwordx4 v[48:51], v[48:49], off offset:64
	s_waitcnt vmcnt(0)
	v_pk_mul_f32 v[54:55], v[28:29], v[32:33] op_sel_hi:[1,0]
	v_pk_mul_f32 v[52:53], v[28:29], v[48:49] op_sel:[1,0] op_sel_hi:[0,0]
	v_pk_mul_f32 v[48:49], v[30:31], v[48:49] op_sel:[1,1] op_sel_hi:[0,1]
	v_pk_fma_f32 v[28:29], v[28:29], v[32:33], v[52:53] op_sel_hi:[1,0,1]
	v_pk_fma_f32 v[56:57], v[30:31], v[32:33], v[48:49] op_sel:[0,1,0] neg_lo:[0,0,1] neg_hi:[0,0,1]
	v_pk_fma_f32 v[30:31], v[30:31], v[32:33], v[48:49] op_sel:[0,1,0]
	v_pk_mul_f32 v[32:33], v[24:25], v[50:51] op_sel:[1,0] op_sel_hi:[0,0]
	v_pk_fma_f32 v[48:49], v[24:25], v[34:35], v[32:33] op_sel_hi:[1,0,1] neg_lo:[0,0,1] neg_hi:[0,0,1]
	v_pk_fma_f32 v[24:25], v[24:25], v[34:35], v[32:33] op_sel_hi:[1,0,1]
	v_mov_b32_e32 v50, v35
	v_mul_f32_e32 v24, v27, v51
	v_pk_fma_f32 v[32:33], v[26:27], v[50:51], v[24:25] op_sel_hi:[1,1,0] neg_lo:[0,0,1] neg_hi:[0,0,1]
	v_mov_b32_e32 v34, v51
	v_mul_f32_e32 v24, v27, v35
	v_pk_fma_f32 v[34:35], v[26:27], v[34:35], v[24:25] op_sel_hi:[1,1,0]
	v_sub_f32_e32 v28, v54, v52
	v_mov_b32_e32 v30, v56
	v_mov_b32_e32 v24, v48
	v_mov_b32_e32 v26, v32
	v_mov_b32_e32 v27, v34
.LBB0_561:
	s_or_b64 exec, exec, s[0:1]
	v_cvt_pk_bf16_f32 v28, v28, v29
	v_cvt_pk_bf16_f32 v29, v30, v31
	v_cvt_pk_bf16_f32 v30, v24, v25
	v_cvt_pk_bf16_f32 v31, v26, v27
	global_store_dwordx4 v[102:103], v[28:31], off offset:256
	s_nop 0
	s_and_b64 s[18:19], s[40:41], s[50:51]
	v_mov_b32_e32 v24, v183
	v_fmamk_f32 v24, v24, 0x3b800000, v216
	v_mul_f32_e32 v25, 0x4b800000, v24
	v_cmp_gt_f32_e32 vcc, s33, v24
	s_nop 1
	v_cndmask_b32_e32 v24, v24, v25, vcc
	v_rsq_f32_e32 v24, v24
	s_nop 0
	v_mul_f32_e32 v25, 0x45800000, v24
	v_cndmask_b32_e32 v24, v24, v25, vcc
	v_mul_f32_e32 v24, 0x3e16c740, v24
	v_pk_mul_f32 v[20:21], v[20:21], v[24:25] op_sel_hi:[1,0]
	v_pk_mul_f32 v[22:23], v[22:23], v[24:25] op_sel_hi:[1,0]
	v_pk_mul_f32 v[16:17], v[16:17], v[24:25] op_sel_hi:[1,0]
	v_pk_mul_f32 v[18:19], v[18:19], v[24:25] op_sel_hi:[1,0]
	s_and_saveexec_b64 s[0:1], s[18:19]
	s_cbranch_execz .LBB0_563
	v_mov_b32_e32 v101, v36
	v_lshlrev_b64 v[24:25], 7, v[100:101]
	v_lshl_add_u64 v[24:25], s[58:59], 0, v[24:25]
	v_lshl_add_u64 v[28:29], v[78:79], 2, v[24:25]
	global_load_dwordx4 v[24:27], v[28:29], off
	s_nop 0
	global_load_dwordx4 v[28:31], v[28:29], off offset:64
	s_waitcnt vmcnt(0)
	v_pk_mul_f32 v[34:35], v[20:21], v[24:25] op_sel_hi:[1,0]
	v_pk_mul_f32 v[32:33], v[20:21], v[28:29] op_sel:[1,0] op_sel_hi:[0,0]
	v_pk_mul_f32 v[28:29], v[22:23], v[28:29] op_sel:[1,1] op_sel_hi:[0,1]
	v_pk_fma_f32 v[20:21], v[20:21], v[24:25], v[32:33] op_sel_hi:[1,0,1]
	v_pk_fma_f32 v[48:49], v[22:23], v[24:25], v[28:29] op_sel:[0,1,0] neg_lo:[0,0,1] neg_hi:[0,0,1]
	v_pk_fma_f32 v[22:23], v[22:23], v[24:25], v[28:29] op_sel:[0,1,0]
	v_pk_mul_f32 v[24:25], v[16:17], v[30:31] op_sel:[1,0] op_sel_hi:[0,0]
	v_pk_fma_f32 v[28:29], v[16:17], v[26:27], v[24:25] op_sel_hi:[1,0,1] neg_lo:[0,0,1] neg_hi:[0,0,1]
	v_pk_fma_f32 v[16:17], v[16:17], v[26:27], v[24:25] op_sel_hi:[1,0,1]
	v_mov_b32_e32 v30, v27
	v_mul_f32_e32 v16, v19, v31
	v_pk_fma_f32 v[24:25], v[18:19], v[30:31], v[16:17] op_sel_hi:[1,1,0] neg_lo:[0,0,1] neg_hi:[0,0,1]
	v_mov_b32_e32 v26, v31
	v_mul_f32_e32 v16, v19, v27
	v_pk_fma_f32 v[26:27], v[18:19], v[26:27], v[16:17] op_sel_hi:[1,1,0]
	v_sub_f32_e32 v20, v34, v32
	v_mov_b32_e32 v22, v48
	v_mov_b32_e32 v16, v28
	v_mov_b32_e32 v18, v24
	v_mov_b32_e32 v19, v26
; __device__ __forceinline__ u32x4 pack8(const float* v) { u32x4 w; w.x = pk2(v[0], v[1]); w.y = pk2(v[2], v[3]); w.z = pk2(v[4], v[5]); w.w = pk2(v[6], v[7]); return w; }
; #define EPI_LOOP_END asm volatile("" ::: "memory"); } }
;     __device__ __forceinline__ void operator()(const f32x4 (&acc)[2][2][4][2], const pg8::Unit& u, int wr, int wc, int fr, int fq) const {
;         EPI_LOOP_BEGIN
;             const int b = (t >= TB) ? 1 : 0, i = t - b * TB; const bool lat = i >= LC; const int pos = i - LC;
;             const float rstd = rsqrtf(((const float*)(ws + O_SSQ))[t * 2] * (1.f / 256.f) + EPS) * (0.10206207261596575f * LOG2E);
; #pragma unroll
;             for (int e = 0; e < 8; ++e) v[e] *= rstd;
;             const int h = c0 / 96, w = c0 - h * 96;
;             if (w >= 64 && lat) { const float* cs = (const float*)(ws + O_ROPEB) + (size_t)pos * 32 + ((w - 64) >> 1);
; #pragma unroll
;                 for (int p = 0; p < 4; ++p) { const float c = cs[p], s = cs[16 + p], a = v[2 * p], bb = v[2 * p + 1]; v[2 * p] = a * c - bb * s; v[2 * p + 1] = a * s + bb * c; } }
;             *(u32x4*)((bf16_t*)(ws + O_QB) + (size_t)t * 768 + c0) = pack8(v);
;         EPI_LOOP_END
.LBB0_563:
	s_or_b64 exec, exec, s[0:1]
	v_cvt_pk_bf16_f32 v20, v20, v21
	v_cvt_pk_bf16_f32 v21, v22, v23
	v_cvt_pk_bf16_f32 v22, v16, v17
	v_cvt_pk_bf16_f32 v23, v18, v19
	global_store_dwordx4 v[94:95], v[20:23], off offset:256
	s_nop 0
	s_and_b64 s[18:19], s[40:41], s[52:53]
	v_mov_b32_e32 v16, v184
	v_fmamk_f32 v16, v16, 0x3b800000, v216
	v_mul_f32_e32 v17, 0x4b800000, v16
	v_cmp_gt_f32_e32 vcc, s33, v16
	s_nop 1
	v_cndmask_b32_e32 v16, v16, v17, vcc
	v_rsq_f32_e32 v16, v16
	s_nop 0
	v_mul_f32_e32 v17, 0x45800000, v16
	v_cndmask_b32_e32 v16, v16, v17, vcc
	v_mul_f32_e32 v16, 0x3e16c740, v16
	v_pk_mul_f32 v[12:13], v[12:13], v[16:17] op_sel_hi:[1,0]
	v_pk_mul_f32 v[14:15], v[14:15], v[16:17] op_sel_hi:[1,0]
	v_pk_mul_f32 v[8:9], v[8:9], v[16:17] op_sel_hi:[1,0]
	v_pk_mul_f32 v[10:11], v[10:11], v[16:17] op_sel_hi:[1,0]
	s_and_saveexec_b64 s[0:1], s[18:19]
	s_cbranch_execz .LBB0_565
	v_mov_b32_e32 v93, v36
	v_lshlrev_b64 v[16:17], 7, v[92:93]
	v_lshl_add_u64 v[16:17], s[58:59], 0, v[16:17]
	v_lshl_add_u64 v[20:21], v[78:79], 2, v[16:17]
	global_load_dwordx4 v[16:19], v[20:21], off
	s_nop 0
	global_load_dwordx4 v[20:23], v[20:21], off offset:64
	s_waitcnt vmcnt(0)
	v_pk_mul_f32 v[26:27], v[12:13], v[16:17] op_sel_hi:[1,0]
	v_pk_mul_f32 v[24:25], v[12:13], v[20:21] op_sel:[1,0] op_sel_hi:[0,0]
	v_pk_mul_f32 v[20:21], v[14:15], v[20:21] op_sel:[1,1] op_sel_hi:[0,1]
	v_pk_fma_f32 v[12:13], v[12:13], v[16:17], v[24:25] op_sel_hi:[1,0,1]
	v_pk_fma_f32 v[28:29], v[14:15], v[16:17], v[20:21] op_sel:[0,1,0] neg_lo:[0,0,1] neg_hi:[0,0,1]
	v_pk_fma_f32 v[14:15], v[14:15], v[16:17], v[20:21] op_sel:[0,1,0]
	v_pk_mul_f32 v[16:17], v[8:9], v[22:23] op_sel:[1,0] op_sel_hi:[0,0]
	v_pk_fma_f32 v[20:21], v[8:9], v[18:19], v[16:17] op_sel_hi:[1,0,1] neg_lo:[0,0,1] neg_hi:[0,0,1]
	v_pk_fma_f32 v[8:9], v[8:9], v[18:19], v[16:17] op_sel_hi:[1,0,1]
	v_mov_b32_e32 v22, v19
	v_mul_f32_e32 v8, v11, v23
	v_pk_fma_f32 v[16:17], v[10:11], v[22:23], v[8:9] op_sel_hi:[1,1,0] neg_lo:[0,0,1] neg_hi:[0,0,1]
	v_mov_b32_e32 v18, v23
	v_mul_f32_e32 v8, v11, v19
	v_pk_fma_f32 v[18:19], v[10:11], v[18:19], v[8:9] op_sel_hi:[1,1,0]
	v_sub_f32_e32 v12, v26, v24
	v_mov_b32_e32 v14, v28
	v_mov_b32_e32 v8, v20
	v_mov_b32_e32 v10, v16
	v_mov_b32_e32 v11, v18
.LBB0_565:
	s_or_b64 exec, exec, s[0:1]
	v_cvt_pk_bf16_f32 v12, v12, v13
	v_cvt_pk_bf16_f32 v13, v14, v15
	v_cvt_pk_bf16_f32 v14, v8, v9
	v_cvt_pk_bf16_f32 v15, v10, v11
	global_store_dwordx4 v[86:87], v[12:15], off offset:256
	s_nop 0
	s_and_b64 s[18:19], s[40:41], s[54:55]
	v_mov_b32_e32 v8, v185
	v_fmamk_f32 v8, v8, 0x3b800000, v216
	v_mul_f32_e32 v9, 0x4b800000, v8
	v_cmp_gt_f32_e32 vcc, s33, v8
	s_nop 1
	v_cndmask_b32_e32 v8, v8, v9, vcc
	v_rsq_f32_e32 v8, v8
	s_nop 0
	v_mul_f32_e32 v9, 0x45800000, v8
	v_cndmask_b32_e32 v8, v8, v9, vcc
	v_mul_f32_e32 v8, 0x3e16c740, v8
	v_pk_mul_f32 v[4:5], v[4:5], v[8:9] op_sel_hi:[1,0]
	v_pk_mul_f32 v[6:7], v[6:7], v[8:9] op_sel_hi:[1,0]
	v_pk_mul_f32 v[0:1], v[0:1], v[8:9] op_sel_hi:[1,0]
	v_pk_mul_f32 v[2:3], v[2:3], v[8:9] op_sel_hi:[1,0]
	s_and_saveexec_b64 s[0:1], s[18:19]
	s_cbranch_execz .LBB0_567
	v_mov_b32_e32 v85, v36
	v_lshlrev_b64 v[8:9], 7, v[84:85]
	v_lshl_add_u64 v[8:9], s[58:59], 0, v[8:9]
	v_lshl_add_u64 v[12:13], v[78:79], 2, v[8:9]
	global_load_dwordx4 v[8:11], v[12:13], off
	s_nop 0
	global_load_dwordx4 v[12:15], v[12:13], off offset:64
	s_waitcnt vmcnt(0)
	v_pk_mul_f32 v[18:19], v[4:5], v[8:9] op_sel_hi:[1,0]
	v_pk_mul_f32 v[16:17], v[4:5], v[12:13] op_sel:[1,0] op_sel_hi:[0,0]
	v_pk_mul_f32 v[12:13], v[6:7], v[12:13] op_sel:[1,1] op_sel_hi:[0,1]
	v_pk_fma_f32 v[4:5], v[4:5], v[8:9], v[16:17] op_sel_hi:[1,0,1]
	v_pk_fma_f32 v[20:21], v[6:7], v[8:9], v[12:13] op_sel:[0,1,0] neg_lo:[0,0,1] neg_hi:[0,0,1]
	v_pk_fma_f32 v[6:7], v[6:7], v[8:9], v[12:13] op_sel:[0,1,0]
	v_pk_mul_f32 v[8:9], v[0:1], v[14:15] op_sel:[1,0] op_sel_hi:[0,0]
	v_pk_fma_f32 v[12:13], v[0:1], v[10:11], v[8:9] op_sel_hi:[1,0,1] neg_lo:[0,0,1] neg_hi:[0,0,1]
	v_pk_fma_f32 v[0:1], v[0:1], v[10:11], v[8:9] op_sel_hi:[1,0,1]
	v_mov_b32_e32 v14, v11
	v_mul_f32_e32 v0, v3, v15
	v_pk_fma_f32 v[8:9], v[2:3], v[14:15], v[0:1] op_sel_hi:[1,1,0] neg_lo:[0,0,1] neg_hi:[0,0,1]
	v_mov_b32_e32 v10, v15
	v_mul_f32_e32 v0, v3, v11
	v_pk_fma_f32 v[10:11], v[2:3], v[10:11], v[0:1] op_sel_hi:[1,1,0]
	v_sub_f32_e32 v4, v18, v16
	v_mov_b32_e32 v6, v20
	v_mov_b32_e32 v0, v12
	v_mov_b32_e32 v2, v8
	v_mov_b32_e32 v3, v10

; __device__ __forceinline__ unsigned f2bf(float f) { unsigned u = __float_as_uint(f); return (u + 0x7fffu + ((u >> 16) & 1u)) >> 16; }
; __device__ __forceinline__ u32x4 pack8(const float* v) { u32x4 w; w.x = pk2(v[0], v[1]); w.y = pk2(v[2], v[3]); w.z = pk2(v[4], v[5]); w.w = pk2(v[6], v[7]); return w; }
;     __device__ __forceinline__ void operator()(const f32x4 (&acc)[2][2][4][2], const pg8::Unit& u, int wr, int wc, int fr, int fq) const {
;     ...
;             const int b = (t >= TB) ? 1 : 0, i = t - b * TB;
;             const float rstd = rsqrtf(((const float*)(ws + O_SSQ))[t * 2 + 1] * (1.f / 128.f) + EPS);
; #pragma unroll
;             for (int e = 0; e < 8; ++e) v[e] *= rstd;
;             const int h = c0 >> 7, w = c0 & 127;
;             if (w < 64) *(u32x4*)((bf16_t*)(ws + O_KB) + (size_t)t * 768 + h * 96 + w) = pack8(v);
;             else { bf16_t* dst = (bf16_t*)(ws + O_VBT) + ((size_t)(b * 8 + h) * 64 + (w - 64)) * TB + i;
; #pragma unroll
;                 for (int e = 0; e < 8; ++e) dst[(size_t)e * TB] = (bf16_t)f2bf(v[e]); }
.LBB0_599:
	s_lshl_b32 s0, s49, 8
	v_mov_b32_e32 v148, v41
	v_mov_b32_e32 v149, v37
	s_or_b32 s0, s0, s59
	s_nop 0
	v_lshl_add_u32 v163, v149, 3, s0
	s_lshl_b32 s0, s48, 8
	s_add_i32 s0, s0, s58
	v_add_u32_e32 v162, s0, v148
	v_lshlrev_b32_e32 v150, 1, v162
	v_ashrrev_i32_e32 v151, 31, v150
	v_lshl_add_u64 v[150:151], v[150:151], 2, s[4:5]
	s_mov_b32 s0, 0x380000
	v_add_co_u32_e64 v152, s[40:41], s0, v150
	v_and_b32_e32 v166, 0x78, v163
	s_nop 0
	v_addc_co_u32_e64 v153, s[40:41], 0, v151, s[40:41]
	global_load_dword v178, v[152:153], off offset:4
	global_load_dword v179, v[152:153], off offset:132
	global_load_dword v180, v[152:153], off offset:260
	global_load_dword v181, v[152:153], off offset:388
	global_load_dword v182, v[152:153], off offset:1028
	global_load_dword v183, v[152:153], off offset:1156
	global_load_dword v184, v[152:153], off offset:1284
	global_load_dword v185, v[152:153], off offset:1412
	v_subrev_co_u32_e32 v148, vcc, 64, v166
	s_xor_b64 s[48:49], vcc, -1
	v_cmp_lt_i32_e32 vcc, s84, v162
	v_ashrrev_i32_e32 v164, 7, v163
	v_mov_b32_e32 v149, v36
	v_cndmask_b32_e32 v165, 0, v226, vcc
	s_waitcnt vmcnt(0)
	v_mov_b32_e32 v152, v178
	v_fmamk_f32 v152, v152, 0x3c000000, v216
	v_cmp_gt_f32_e64 s[40:41], s33, v152
	v_mul_f32_e32 v153, 0x4b800000, v152
	s_nop 0
	v_cndmask_b32_e64 v152, v152, v153, s[40:41]
	v_rsq_f32_e32 v152, v152
	s_nop 0
	v_mul_f32_e32 v153, 0x45800000, v152
	v_cndmask_b32_e64 v152, v152, v153, s[40:41]
	v_pk_mul_f32 v[156:157], v[134:135], v[152:153] op_sel_hi:[1,0]
	v_add_u32_e32 v134, v165, v162
	v_pk_mul_f32 v[158:159], v[132:133], v[152:153] op_sel_hi:[1,0]
	v_pk_mul_f32 v[154:155], v[136:137], v[152:153] op_sel_hi:[1,0]
	v_pk_mul_f32 v[136:137], v[138:139], v[152:153] op_sel_hi:[1,0]
	v_ashrrev_i32_e32 v135, 31, v134
	v_cndmask_b32_e64 v165, 0, 8, vcc
	s_and_saveexec_b64 s[0:1], s[48:49]
	s_xor_b64 s[0:1], exec, s[0:1]
	s_cbranch_execz .LBB0_601
	v_add_u32_e32 v132, v165, v164
	v_ashrrev_i32_e32 v133, 31, v132
	v_lshlrev_b64 v[132:133], 6, v[132:133]
	v_lshl_add_u64 v[132:133], v[132:133], 0, v[148:149]
	v_mov_b64_e32 v[138:139], s[34:35]
	s_movk_i32 s24, 0x4200
	v_mad_u64_u32 v[138:139], s[18:19], v132, s24, v[138:139]
	v_mad_i32_i24 v139, v133, s24, v139
	v_lshl_add_u64 v[132:133], v[134:135], 1, v[138:139]
	v_bfe_u32 v138, v158, 16, 1
	v_add3_u32 v138, v158, v138, s86
	global_store_short_d16_hi v[132:133], v138, off
	v_bfe_u32 v138, v159, 16, 1
	s_movk_i32 s18, 0x4000
	v_add3_u32 v152, v159, v138, s86
	v_add_co_u32_e32 v138, vcc, s18, v132
	s_mov_b32 s18, 0x8000
	s_nop 0
	v_addc_co_u32_e32 v139, vcc, 0, v133, vcc
	global_store_short_d16_hi v[138:139], v152, off offset:512
	v_bfe_u32 v138, v156, 16, 1
	v_add3_u32 v152, v156, v138, s86
	v_add_co_u32_e32 v138, vcc, s18, v132
	s_nop 1
	v_addc_co_u32_e32 v139, vcc, 0, v133, vcc
	global_store_short_d16_hi v[138:139], v152, off offset:1024
	v_bfe_u32 v138, v157, 16, 1
	v_add3_u32 v152, v157, v138, s86
	v_add_co_u32_e32 v138, vcc, s83, v132
	s_nop 1
	v_addc_co_u32_e32 v139, vcc, 0, v133, vcc
	global_store_short_d16_hi v[138:139], v152, off offset:1536
	v_bfe_u32 v138, v154, 16, 1
	v_add3_u32 v152, v154, v138, s86
	v_add_co_u32_e32 v138, vcc, s79, v132
	s_nop 1
	v_addc_co_u32_e32 v139, vcc, 0, v133, vcc
	global_store_short_d16_hi v[138:139], v152, off offset:2048
	v_bfe_u32 v138, v155, 16, 1
	v_add3_u32 v152, v155, v138, s86
	v_add_co_u32_e32 v138, vcc, s78, v132
	s_nop 1
	v_addc_co_u32_e32 v139, vcc, 0, v133, vcc
	global_store_short_d16_hi v[138:139], v152, off offset:2560
	v_bfe_u32 v138, v136, 16, 1
	v_add3_u32 v136, v136, v138, s86
	v_add_co_u32_e32 v138, vcc, 0x18000, v132
	s_nop 1
	v_addc_co_u32_e32 v139, vcc, 0, v133, vcc
	global_store_short_d16_hi v[138:139], v136, off offset:3072
	v_bfe_u32 v136, v137, 16, 1
	v_add_co_u32_e32 v132, vcc, 0x1c000, v132
	v_add3_u32 v136, v137, v136, s86
	s_nop 0
	v_addc_co_u32_e32 v133, vcc, 0, v133, vcc
	global_store_short_d16_hi v[132:133], v136, off offset:3584

; __device__ __forceinline__ unsigned f2bf(float f) { unsigned u = __float_as_uint(f); return (u + 0x7fffu + ((u >> 16) & 1u)) >> 16; }
; __device__ __forceinline__ u32x4 pack8(const float* v) { u32x4 w; w.x = pk2(v[0], v[1]); w.y = pk2(v[2], v[3]); w.z = pk2(v[4], v[5]); w.w = pk2(v[6], v[7]); return w; }
;     __device__ __forceinline__ void operator()(const f32x4 (&acc)[2][2][4][2], const pg8::Unit& u, int wr, int wc, int fr, int fq) const {
;     ...
;             const int b = (t >= TB) ? 1 : 0, i = t - b * TB;
;             const float rstd = rsqrtf(((const float*)(ws + O_SSQ))[t * 2 + 1] * (1.f / 128.f) + EPS);
; #pragma unroll
;             for (int e = 0; e < 8; ++e) v[e] *= rstd;
;             const int h = c0 >> 7, w = c0 & 127;
;             if (w < 64) *(u32x4*)((bf16_t*)(ws + O_KB) + (size_t)t * 768 + h * 96 + w) = pack8(v);
;             else { bf16_t* dst = (bf16_t*)(ws + O_VBT) + ((size_t)(b * 8 + h) * 64 + (w - 64)) * TB + i;
; #pragma unroll
;                 for (int e = 0; e < 8; ++e) dst[(size_t)e * TB] = (bf16_t)f2bf(v[e]); }
.LBB0_603:
	s_or_b64 exec, exec, s[0:1]
	v_add_u32_e32 v156, 16, v162
	v_lshlrev_b32_e32 v136, 1, v156
	v_ashrrev_i32_e32 v137, 31, v136
	v_lshl_add_u64 v[138:139], v[136:137], 2, s[4:5]
	v_add_co_u32_e32 v136, vcc, 0x380000, v138
	v_cmp_lt_i32_e64 s[40:41], s84, v156
	s_nop 0
	v_addc_co_u32_e32 v137, vcc, 0, v139, vcc
	s_nop 0
	v_cndmask_b32_e64 v157, 0, 8, s[40:41]
	v_mov_b32_e32 v133, v179
	v_fmamk_f32 v133, v133, 0x3c000000, v216
	v_mul_f32_e32 v136, 0x4b800000, v133
	v_cmp_gt_f32_e32 vcc, s33, v133
	s_nop 1
	v_cndmask_b32_e32 v133, v133, v136, vcc
	v_rsq_f32_e32 v133, v133
	v_cndmask_b32_e64 v136, 0, v226, s[40:41]
	v_add_u32_e32 v136, v136, v156
	v_ashrrev_i32_e32 v137, 31, v136
	v_mul_f32_e32 v154, 0x45800000, v133
	v_cndmask_b32_e32 v158, v133, v154, vcc
	v_pk_mul_f32 v[154:155], v[128:129], v[158:159] op_sel_hi:[1,0]
	v_pk_mul_f32 v[130:131], v[130:131], v[158:159] op_sel_hi:[1,0]
	v_pk_mul_f32 v[128:129], v[124:125], v[158:159] op_sel_hi:[1,0]
	v_pk_mul_f32 v[124:125], v[126:127], v[158:159] op_sel_hi:[1,0]
	s_and_saveexec_b64 s[0:1], s[48:49]
	s_xor_b64 s[0:1], exec, s[0:1]
	s_cbranch_execz .LBB0_605
	v_add_u32_e32 v126, v157, v164
	v_ashrrev_i32_e32 v127, 31, v126
	v_lshlrev_b64 v[126:127], 6, v[126:127]
	v_lshl_add_u64 v[126:127], v[126:127], 0, v[148:149]
	v_mov_b64_e32 v[158:159], s[34:35]
	s_movk_i32 s24, 0x4200
	v_mad_u64_u32 v[158:159], s[18:19], v126, s24, v[158:159]
	v_mad_i32_i24 v159, v127, s24, v159
	v_bfe_u32 v133, v154, 16, 1
	v_lshl_add_u64 v[126:127], v[136:137], 1, v[158:159]
	v_add3_u32 v133, v154, v133, s86
	s_movk_i32 s18, 0x4000
	global_store_short_d16_hi v[126:127], v133, off
	v_bfe_u32 v133, v155, 16, 1
	v_add_co_u32_e32 v154, vcc, s18, v126
	v_add3_u32 v133, v155, v133, s86
	s_nop 0
	v_addc_co_u32_e32 v155, vcc, 0, v127, vcc
	s_mov_b32 s18, 0x8000
	global_store_short_d16_hi v[154:155], v133, off offset:512
	v_bfe_u32 v133, v130, 16, 1
	v_add_co_u32_e32 v154, vcc, s18, v126
	v_add3_u32 v130, v130, v133, s86
	s_nop 0
	v_addc_co_u32_e32 v155, vcc, 0, v127, vcc
	global_store_short_d16_hi v[154:155], v130, off offset:1024
	v_bfe_u32 v130, v131, 16, 1
	v_add3_u32 v133, v131, v130, s86
	v_add_co_u32_e32 v130, vcc, s83, v126
	s_nop 1
	v_addc_co_u32_e32 v131, vcc, 0, v127, vcc
	global_store_short_d16_hi v[130:131], v133, off offset:1536
	v_bfe_u32 v130, v128, 16, 1
	v_add3_u32 v128, v128, v130, s86
	v_add_co_u32_e32 v130, vcc, s79, v126
	s_nop 1
	v_addc_co_u32_e32 v131, vcc, 0, v127, vcc
	global_store_short_d16_hi v[130:131], v128, off offset:2048
	v_bfe_u32 v128, v129, 16, 1
	v_add3_u32 v130, v129, v128, s86
	v_add_co_u32_e32 v128, vcc, s78, v126
	s_nop 1
	v_addc_co_u32_e32 v129, vcc, 0, v127, vcc
	global_store_short_d16_hi v[128:129], v130, off offset:2560
	v_bfe_u32 v128, v124, 16, 1
	v_add3_u32 v124, v124, v128, s86
	v_add_co_u32_e32 v128, vcc, 0x18000, v126
	s_nop 1
	v_addc_co_u32_e32 v129, vcc, 0, v127, vcc
	global_store_short_d16_hi v[128:129], v124, off offset:3072
	v_bfe_u32 v124, v125, 16, 1
	v_add3_u32 v128, v125, v124, s86
	v_add_co_u32_e32 v124, vcc, 0x1c000, v126
	s_nop 1
	v_addc_co_u32_e32 v125, vcc, 0, v127, vcc
	global_store_short_d16_hi v[124:125], v128, off offset:3584

; __device__ __forceinline__ unsigned f2bf(float f) { unsigned u = __float_as_uint(f); return (u + 0x7fffu + ((u >> 16) & 1u)) >> 16; }
; __device__ __forceinline__ u32x4 pack8(const float* v) { u32x4 w; w.x = pk2(v[0], v[1]); w.y = pk2(v[2], v[3]); w.z = pk2(v[4], v[5]); w.w = pk2(v[6], v[7]); return w; }
;     __device__ __forceinline__ void operator()(const f32x4 (&acc)[2][2][4][2], const pg8::Unit& u, int wr, int wc, int fr, int fq) const {
;     ...
;             const int b = (t >= TB) ? 1 : 0, i = t - b * TB;
;             const float rstd = rsqrtf(((const float*)(ws + O_SSQ))[t * 2 + 1] * (1.f / 128.f) + EPS);
; #pragma unroll
;             for (int e = 0; e < 8; ++e) v[e] *= rstd;
;             const int h = c0 >> 7, w = c0 & 127;
;             if (w < 64) *(u32x4*)((bf16_t*)(ws + O_KB) + (size_t)t * 768 + h * 96 + w) = pack8(v);
;             else { bf16_t* dst = (bf16_t*)(ws + O_VBT) + ((size_t)(b * 8 + h) * 64 + (w - 64)) * TB + i;
; #pragma unroll
;                 for (int e = 0; e < 8; ++e) dst[(size_t)e * TB] = (bf16_t)f2bf(v[e]); }
.LBB0_607:
	s_or_b64 exec, exec, s[0:1]
	v_add_u32_e32 v130, 32, v162
	v_lshlrev_b32_e32 v124, 1, v130
	v_ashrrev_i32_e32 v125, 31, v124
	v_lshl_add_u64 v[126:127], v[124:125], 2, s[4:5]
	v_add_co_u32_e32 v124, vcc, 0x380000, v126
	v_cmp_lt_i32_e64 s[40:41], s84, v130
	s_nop 0
	v_addc_co_u32_e32 v125, vcc, 0, v127, vcc
	s_nop 0
	v_cndmask_b32_e64 v131, 0, 8, s[40:41]
	v_mov_b32_e32 v124, v180
	v_fmamk_f32 v124, v124, 0x3c000000, v216
	v_mul_f32_e32 v125, 0x4b800000, v124
	v_cmp_gt_f32_e32 vcc, s33, v124
	s_nop 1
	v_cndmask_b32_e32 v124, v124, v125, vcc
	v_rsq_f32_e32 v128, v124
	v_cndmask_b32_e64 v124, 0, v226, s[40:41]
	v_add_u32_e32 v124, v124, v130
	v_ashrrev_i32_e32 v125, 31, v124
	v_mul_f32_e32 v129, 0x45800000, v128
	v_cndmask_b32_e32 v154, v128, v129, vcc
	v_pk_mul_f32 v[128:129], v[120:121], v[154:155] op_sel_hi:[1,0]
	v_pk_mul_f32 v[122:123], v[122:123], v[154:155] op_sel_hi:[1,0]
	v_pk_mul_f32 v[120:121], v[116:117], v[154:155] op_sel_hi:[1,0]
	v_pk_mul_f32 v[116:117], v[118:119], v[154:155] op_sel_hi:[1,0]
	s_and_saveexec_b64 s[0:1], s[48:49]
	s_xor_b64 s[0:1], exec, s[0:1]
	s_cbranch_execz .LBB0_609
	v_add_u32_e32 v118, v131, v164
	v_ashrrev_i32_e32 v119, 31, v118
	v_lshlrev_b64 v[118:119], 6, v[118:119]
	v_lshl_add_u64 v[118:119], v[118:119], 0, v[148:149]
	v_mov_b64_e32 v[154:155], s[34:35]
	s_movk_i32 s24, 0x4200
	v_mad_u64_u32 v[154:155], s[18:19], v118, s24, v[154:155]
	v_mad_i32_i24 v155, v119, s24, v155
	v_bfe_u32 v133, v128, 16, 1
	v_lshl_add_u64 v[118:119], v[124:125], 1, v[154:155]
	v_add3_u32 v128, v128, v133, s86
	global_store_short_d16_hi v[118:119], v128, off
	v_bfe_u32 v128, v129, 16, 1
	s_movk_i32 s18, 0x4000
	v_add3_u32 v133, v129, v128, s86
	v_add_co_u32_e32 v128, vcc, s18, v118
	s_mov_b32 s18, 0x8000
	s_nop 0
	v_addc_co_u32_e32 v129, vcc, 0, v119, vcc
	global_store_short_d16_hi v[128:129], v133, off offset:512
	v_bfe_u32 v128, v122, 16, 1
	v_add3_u32 v122, v122, v128, s86
	v_add_co_u32_e32 v128, vcc, s18, v118
	s_nop 1
	v_addc_co_u32_e32 v129, vcc, 0, v119, vcc
	global_store_short_d16_hi v[128:129], v122, off offset:1024
	v_bfe_u32 v122, v123, 16, 1
	v_add3_u32 v128, v123, v122, s86
	v_add_co_u32_e32 v122, vcc, s83, v118
	s_nop 1
	v_addc_co_u32_e32 v123, vcc, 0, v119, vcc
	global_store_short_d16_hi v[122:123], v128, off offset:1536
	v_bfe_u32 v122, v120, 16, 1
	v_add3_u32 v120, v120, v122, s86
	v_add_co_u32_e32 v122, vcc, s79, v118
	s_nop 1
	v_addc_co_u32_e32 v123, vcc, 0, v119, vcc
	global_store_short_d16_hi v[122:123], v120, off offset:2048
	v_bfe_u32 v120, v121, 16, 1
	v_add3_u32 v122, v121, v120, s86
	v_add_co_u32_e32 v120, vcc, s78, v118
	s_nop 1
	v_addc_co_u32_e32 v121, vcc, 0, v119, vcc
	global_store_short_d16_hi v[120:121], v122, off offset:2560
	v_bfe_u32 v120, v116, 16, 1
	v_add3_u32 v116, v116, v120, s86
	v_add_co_u32_e32 v120, vcc, 0x18000, v118
	s_nop 1
	v_addc_co_u32_e32 v121, vcc, 0, v119, vcc
	global_store_short_d16_hi v[120:121], v116, off offset:3072
	v_bfe_u32 v116, v117, 16, 1
	v_add3_u32 v120, v117, v116, s86
	v_add_co_u32_e32 v116, vcc, 0x1c000, v118
	s_nop 1
	v_addc_co_u32_e32 v117, vcc, 0, v119, vcc
	global_store_short_d16_hi v[116:117], v120, off offset:3584

; __device__ __forceinline__ unsigned f2bf(float f) { unsigned u = __float_as_uint(f); return (u + 0x7fffu + ((u >> 16) & 1u)) >> 16; }
; __device__ __forceinline__ u32x4 pack8(const float* v) { u32x4 w; w.x = pk2(v[0], v[1]); w.y = pk2(v[2], v[3]); w.z = pk2(v[4], v[5]); w.w = pk2(v[6], v[7]); return w; }
;     __device__ __forceinline__ void operator()(const f32x4 (&acc)[2][2][4][2], const pg8::Unit& u, int wr, int wc, int fr, int fq) const {
;     ...
;             const int b = (t >= TB) ? 1 : 0, i = t - b * TB;
;             const float rstd = rsqrtf(((const float*)(ws + O_SSQ))[t * 2 + 1] * (1.f / 128.f) + EPS);
; #pragma unroll
;             for (int e = 0; e < 8; ++e) v[e] *= rstd;
;             const int h = c0 >> 7, w = c0 & 127;
;             if (w < 64) *(u32x4*)((bf16_t*)(ws + O_KB) + (size_t)t * 768 + h * 96 + w) = pack8(v);
;             else { bf16_t* dst = (bf16_t*)(ws + O_VBT) + ((size_t)(b * 8 + h) * 64 + (w - 64)) * TB + i;
; #pragma unroll
;                 for (int e = 0; e < 8; ++e) dst[(size_t)e * TB] = (bf16_t)f2bf(v[e]); }
.LBB0_611:
	s_or_b64 exec, exec, s[0:1]
	v_add_u32_e32 v122, 48, v162
	v_lshlrev_b32_e32 v116, 1, v122
	v_ashrrev_i32_e32 v117, 31, v116
	v_lshl_add_u64 v[118:119], v[116:117], 2, s[4:5]
	v_add_co_u32_e32 v116, vcc, 0x380000, v118
	v_cmp_lt_i32_e64 s[40:41], s84, v122
	s_nop 0
	v_addc_co_u32_e32 v117, vcc, 0, v119, vcc
	s_nop 0
	v_cndmask_b32_e64 v123, 0, 8, s[40:41]
	v_mov_b32_e32 v116, v181
	v_fmamk_f32 v116, v116, 0x3c000000, v216
	v_mul_f32_e32 v117, 0x4b800000, v116
	v_cmp_gt_f32_e32 vcc, s33, v116
	s_nop 1
	v_cndmask_b32_e32 v116, v116, v117, vcc
	v_rsq_f32_e32 v120, v116
	v_cndmask_b32_e64 v116, 0, v226, s[40:41]
	v_add_u32_e32 v116, v116, v122
	v_ashrrev_i32_e32 v117, 31, v116
	v_mul_f32_e32 v121, 0x45800000, v120
	v_cndmask_b32_e32 v128, v120, v121, vcc
	v_pk_mul_f32 v[120:121], v[112:113], v[128:129] op_sel_hi:[1,0]
	v_pk_mul_f32 v[114:115], v[114:115], v[128:129] op_sel_hi:[1,0]
	v_pk_mul_f32 v[112:113], v[108:109], v[128:129] op_sel_hi:[1,0]
	v_pk_mul_f32 v[108:109], v[110:111], v[128:129] op_sel_hi:[1,0]
	s_and_saveexec_b64 s[0:1], s[48:49]
	s_xor_b64 s[0:1], exec, s[0:1]
	s_cbranch_execz .LBB0_613
	v_add_u32_e32 v110, v123, v164
	v_ashrrev_i32_e32 v111, 31, v110
	v_lshlrev_b64 v[110:111], 6, v[110:111]
	v_lshl_add_u64 v[110:111], v[110:111], 0, v[148:149]
	v_mov_b64_e32 v[128:129], s[34:35]
	s_movk_i32 s24, 0x4200
	v_mad_u64_u32 v[128:129], s[18:19], v110, s24, v[128:129]
	v_mad_i32_i24 v129, v111, s24, v129
	v_lshl_add_u64 v[110:111], v[116:117], 1, v[128:129]
	v_bfe_u32 v128, v120, 16, 1
	v_add3_u32 v120, v120, v128, s86
	global_store_short_d16_hi v[110:111], v120, off
	v_bfe_u32 v120, v121, 16, 1
	s_movk_i32 s18, 0x4000
	v_add3_u32 v128, v121, v120, s86
	v_add_co_u32_e32 v120, vcc, s18, v110
	s_mov_b32 s18, 0x8000
	s_nop 0
	v_addc_co_u32_e32 v121, vcc, 0, v111, vcc
	global_store_short_d16_hi v[120:121], v128, off offset:512
	v_bfe_u32 v120, v114, 16, 1
	v_add3_u32 v114, v114, v120, s86
	v_add_co_u32_e32 v120, vcc, s18, v110
	s_nop 1
	v_addc_co_u32_e32 v121, vcc, 0, v111, vcc
	global_store_short_d16_hi v[120:121], v114, off offset:1024
	v_bfe_u32 v114, v115, 16, 1
	v_add3_u32 v120, v115, v114, s86
	v_add_co_u32_e32 v114, vcc, s83, v110
	s_nop 1
	v_addc_co_u32_e32 v115, vcc, 0, v111, vcc
	global_store_short_d16_hi v[114:115], v120, off offset:1536
	v_bfe_u32 v114, v112, 16, 1
	v_add3_u32 v112, v112, v114, s86
	v_add_co_u32_e32 v114, vcc, s79, v110
	s_nop 1
	v_addc_co_u32_e32 v115, vcc, 0, v111, vcc
	global_store_short_d16_hi v[114:115], v112, off offset:2048
	v_bfe_u32 v112, v113, 16, 1
	v_add3_u32 v114, v113, v112, s86
	v_add_co_u32_e32 v112, vcc, s78, v110
	s_nop 1
	v_addc_co_u32_e32 v113, vcc, 0, v111, vcc
	global_store_short_d16_hi v[112:113], v114, off offset:2560
	v_bfe_u32 v112, v108, 16, 1
	v_add3_u32 v108, v108, v112, s86
	v_add_co_u32_e32 v112, vcc, 0x18000, v110
	s_nop 1
	v_addc_co_u32_e32 v113, vcc, 0, v111, vcc
	global_store_short_d16_hi v[112:113], v108, off offset:3072
	v_bfe_u32 v108, v109, 16, 1
	v_add3_u32 v112, v109, v108, s86
	v_add_co_u32_e32 v108, vcc, 0x1c000, v110
	s_nop 1
	v_addc_co_u32_e32 v109, vcc, 0, v111, vcc
	global_store_short_d16_hi v[108:109], v112, off offset:3584

; __device__ __forceinline__ unsigned f2bf(float f) { unsigned u = __float_as_uint(f); return (u + 0x7fffu + ((u >> 16) & 1u)) >> 16; }
; __device__ __forceinline__ u32x4 pack8(const float* v) { u32x4 w; w.x = pk2(v[0], v[1]); w.y = pk2(v[2], v[3]); w.z = pk2(v[4], v[5]); w.w = pk2(v[6], v[7]); return w; }
;     __device__ __forceinline__ void operator()(const f32x4 (&acc)[2][2][4][2], const pg8::Unit& u, int wr, int wc, int fr, int fq) const {
;     ...
;             const int b = (t >= TB) ? 1 : 0, i = t - b * TB;
;             const float rstd = rsqrtf(((const float*)(ws + O_SSQ))[t * 2 + 1] * (1.f / 128.f) + EPS);
; #pragma unroll
;             for (int e = 0; e < 8; ++e) v[e] *= rstd;
;             const int h = c0 >> 7, w = c0 & 127;
;             if (w < 64) *(u32x4*)((bf16_t*)(ws + O_KB) + (size_t)t * 768 + h * 96 + w) = pack8(v);
;             else { bf16_t* dst = (bf16_t*)(ws + O_VBT) + ((size_t)(b * 8 + h) * 64 + (w - 64)) * TB + i;
; #pragma unroll
;                 for (int e = 0; e < 8; ++e) dst[(size_t)e * TB] = (bf16_t)f2bf(v[e]); }
.LBB0_615:
	s_or_b64 exec, exec, s[0:1]
	v_add_u32_e32 v114, 0x80, v162
	v_lshlrev_b32_e32 v108, 1, v114
	v_ashrrev_i32_e32 v109, 31, v108
	v_lshl_add_u64 v[110:111], v[108:109], 2, s[4:5]
	v_add_co_u32_e32 v108, vcc, 0x380000, v110
	v_cmp_lt_i32_e64 s[40:41], s84, v114
	s_nop 0
	v_addc_co_u32_e32 v109, vcc, 0, v111, vcc
	s_nop 0
	v_cndmask_b32_e64 v115, 0, 8, s[40:41]
	v_mov_b32_e32 v108, v182
	v_fmamk_f32 v108, v108, 0x3c000000, v216
	v_mul_f32_e32 v109, 0x4b800000, v108
	v_cmp_gt_f32_e32 vcc, s33, v108
	s_nop 1
	v_cndmask_b32_e32 v108, v108, v109, vcc
	v_rsq_f32_e32 v112, v108
	v_cndmask_b32_e64 v108, 0, v226, s[40:41]
	v_add_u32_e32 v108, v108, v114
	v_ashrrev_i32_e32 v109, 31, v108
	v_mul_f32_e32 v113, 0x45800000, v112
	v_cndmask_b32_e32 v120, v112, v113, vcc
	v_pk_mul_f32 v[112:113], v[104:105], v[120:121] op_sel_hi:[1,0]
	v_pk_mul_f32 v[106:107], v[106:107], v[120:121] op_sel_hi:[1,0]
	v_pk_mul_f32 v[104:105], v[100:101], v[120:121] op_sel_hi:[1,0]
	v_pk_mul_f32 v[100:101], v[102:103], v[120:121] op_sel_hi:[1,0]
	s_and_saveexec_b64 s[0:1], s[48:49]
	s_xor_b64 s[0:1], exec, s[0:1]
	s_cbranch_execz .LBB0_617
	v_add_u32_e32 v102, v115, v164
	v_ashrrev_i32_e32 v103, 31, v102
	v_lshlrev_b64 v[102:103], 6, v[102:103]
	v_lshl_add_u64 v[102:103], v[102:103], 0, v[148:149]
	v_mov_b64_e32 v[120:121], s[34:35]
	s_movk_i32 s24, 0x4200
	v_mad_u64_u32 v[120:121], s[18:19], v102, s24, v[120:121]
	v_mad_i32_i24 v121, v103, s24, v121
	v_lshl_add_u64 v[102:103], v[108:109], 1, v[120:121]
	v_bfe_u32 v120, v112, 16, 1
	v_add3_u32 v112, v112, v120, s86
	global_store_short_d16_hi v[102:103], v112, off
	v_bfe_u32 v112, v113, 16, 1
	s_movk_i32 s18, 0x4000
	v_add3_u32 v120, v113, v112, s86
	v_add_co_u32_e32 v112, vcc, s18, v102
	s_mov_b32 s18, 0x8000
	s_nop 0
	v_addc_co_u32_e32 v113, vcc, 0, v103, vcc
	global_store_short_d16_hi v[112:113], v120, off offset:512
	v_bfe_u32 v112, v106, 16, 1
	v_add3_u32 v106, v106, v112, s86
	v_add_co_u32_e32 v112, vcc, s18, v102
	s_nop 1
	v_addc_co_u32_e32 v113, vcc, 0, v103, vcc
	global_store_short_d16_hi v[112:113], v106, off offset:1024
	v_bfe_u32 v106, v107, 16, 1
	v_add3_u32 v112, v107, v106, s86
	v_add_co_u32_e32 v106, vcc, s83, v102
	s_nop 1
	v_addc_co_u32_e32 v107, vcc, 0, v103, vcc
	global_store_short_d16_hi v[106:107], v112, off offset:1536
	v_bfe_u32 v106, v104, 16, 1
	v_add3_u32 v104, v104, v106, s86
	v_add_co_u32_e32 v106, vcc, s79, v102
	s_nop 1
	v_addc_co_u32_e32 v107, vcc, 0, v103, vcc
	global_store_short_d16_hi v[106:107], v104, off offset:2048
	v_bfe_u32 v104, v105, 16, 1
	v_add3_u32 v106, v105, v104, s86
	v_add_co_u32_e32 v104, vcc, s78, v102
	s_nop 1
	v_addc_co_u32_e32 v105, vcc, 0, v103, vcc
	global_store_short_d16_hi v[104:105], v106, off offset:2560
	v_bfe_u32 v104, v100, 16, 1
	v_add3_u32 v100, v100, v104, s86
	v_add_co_u32_e32 v104, vcc, 0x18000, v102
	s_nop 1
	v_addc_co_u32_e32 v105, vcc, 0, v103, vcc
	global_store_short_d16_hi v[104:105], v100, off offset:3072
	v_bfe_u32 v100, v101, 16, 1
	v_add3_u32 v104, v101, v100, s86
	v_add_co_u32_e32 v100, vcc, 0x1c000, v102
	s_nop 1
	v_addc_co_u32_e32 v101, vcc, 0, v103, vcc
	global_store_short_d16_hi v[100:101], v104, off offset:3584

; __device__ __forceinline__ unsigned f2bf(float f) { unsigned u = __float_as_uint(f); return (u + 0x7fffu + ((u >> 16) & 1u)) >> 16; }
; __device__ __forceinline__ u32x4 pack8(const float* v) { u32x4 w; w.x = pk2(v[0], v[1]); w.y = pk2(v[2], v[3]); w.z = pk2(v[4], v[5]); w.w = pk2(v[6], v[7]); return w; }
;     __device__ __forceinline__ void operator()(const f32x4 (&acc)[2][2][4][2], const pg8::Unit& u, int wr, int wc, int fr, int fq) const {
;     ...
;             const int b = (t >= TB) ? 1 : 0, i = t - b * TB;
;             const float rstd = rsqrtf(((const float*)(ws + O_SSQ))[t * 2 + 1] * (1.f / 128.f) + EPS);
; #pragma unroll
;             for (int e = 0; e < 8; ++e) v[e] *= rstd;
;             const int h = c0 >> 7, w = c0 & 127;
;             if (w < 64) *(u32x4*)((bf16_t*)(ws + O_KB) + (size_t)t * 768 + h * 96 + w) = pack8(v);
;             else { bf16_t* dst = (bf16_t*)(ws + O_VBT) + ((size_t)(b * 8 + h) * 64 + (w - 64)) * TB + i;
; #pragma unroll
;                 for (int e = 0; e < 8; ++e) dst[(size_t)e * TB] = (bf16_t)f2bf(v[e]); }
.LBB0_619:
	s_or_b64 exec, exec, s[0:1]
	v_add_u32_e32 v106, 0x90, v162
	v_lshlrev_b32_e32 v100, 1, v106
	v_ashrrev_i32_e32 v101, 31, v100
	v_lshl_add_u64 v[102:103], v[100:101], 2, s[4:5]
	v_add_co_u32_e32 v100, vcc, 0x380000, v102
	v_cmp_lt_i32_e64 s[40:41], s84, v106
	s_nop 0
	v_addc_co_u32_e32 v101, vcc, 0, v103, vcc
	s_nop 0
	v_cndmask_b32_e64 v107, 0, 8, s[40:41]
	v_mov_b32_e32 v100, v183
	v_fmamk_f32 v100, v100, 0x3c000000, v216
	v_mul_f32_e32 v101, 0x4b800000, v100
	v_cmp_gt_f32_e32 vcc, s33, v100
	s_nop 1
	v_cndmask_b32_e32 v100, v100, v101, vcc
	v_rsq_f32_e32 v104, v100
	v_cndmask_b32_e64 v100, 0, v226, s[40:41]
	v_add_u32_e32 v100, v100, v106
	v_ashrrev_i32_e32 v101, 31, v100
	v_mul_f32_e32 v105, 0x45800000, v104
	v_cndmask_b32_e32 v112, v104, v105, vcc
	v_pk_mul_f32 v[104:105], v[96:97], v[112:113] op_sel_hi:[1,0]
	v_pk_mul_f32 v[98:99], v[98:99], v[112:113] op_sel_hi:[1,0]
	v_pk_mul_f32 v[96:97], v[92:93], v[112:113] op_sel_hi:[1,0]
	v_pk_mul_f32 v[92:93], v[94:95], v[112:113] op_sel_hi:[1,0]
	s_and_saveexec_b64 s[0:1], s[48:49]
	s_xor_b64 s[0:1], exec, s[0:1]
	s_cbranch_execz .LBB0_621
	v_add_u32_e32 v94, v107, v164
	v_ashrrev_i32_e32 v95, 31, v94
	v_lshlrev_b64 v[94:95], 6, v[94:95]
	v_lshl_add_u64 v[94:95], v[94:95], 0, v[148:149]
	v_mov_b64_e32 v[112:113], s[34:35]
	s_movk_i32 s24, 0x4200
	v_mad_u64_u32 v[112:113], s[18:19], v94, s24, v[112:113]
	v_mad_i32_i24 v113, v95, s24, v113
	v_lshl_add_u64 v[94:95], v[100:101], 1, v[112:113]
	v_bfe_u32 v112, v104, 16, 1
	v_add3_u32 v104, v104, v112, s86
	global_store_short_d16_hi v[94:95], v104, off
	v_bfe_u32 v104, v105, 16, 1
	s_movk_i32 s18, 0x4000
	v_add3_u32 v112, v105, v104, s86
	v_add_co_u32_e32 v104, vcc, s18, v94
	s_mov_b32 s18, 0x8000
	s_nop 0
	v_addc_co_u32_e32 v105, vcc, 0, v95, vcc
	global_store_short_d16_hi v[104:105], v112, off offset:512
	v_bfe_u32 v104, v98, 16, 1
	v_add3_u32 v98, v98, v104, s86
	v_add_co_u32_e32 v104, vcc, s18, v94
	s_nop 1
	v_addc_co_u32_e32 v105, vcc, 0, v95, vcc
	global_store_short_d16_hi v[104:105], v98, off offset:1024
	v_bfe_u32 v98, v99, 16, 1
	v_add3_u32 v104, v99, v98, s86
	v_add_co_u32_e32 v98, vcc, s83, v94
	s_nop 1
	v_addc_co_u32_e32 v99, vcc, 0, v95, vcc
	global_store_short_d16_hi v[98:99], v104, off offset:1536
	v_bfe_u32 v98, v96, 16, 1
	v_add3_u32 v96, v96, v98, s86
	v_add_co_u32_e32 v98, vcc, s79, v94
	s_nop 1
	v_addc_co_u32_e32 v99, vcc, 0, v95, vcc
	global_store_short_d16_hi v[98:99], v96, off offset:2048
	v_bfe_u32 v96, v97, 16, 1
	v_add3_u32 v98, v97, v96, s86
	v_add_co_u32_e32 v96, vcc, s78, v94
	s_nop 1
	v_addc_co_u32_e32 v97, vcc, 0, v95, vcc
	global_store_short_d16_hi v[96:97], v98, off offset:2560
	v_bfe_u32 v96, v92, 16, 1
	v_add3_u32 v92, v92, v96, s86
	v_add_co_u32_e32 v96, vcc, 0x18000, v94
	s_nop 1
	v_addc_co_u32_e32 v97, vcc, 0, v95, vcc
	global_store_short_d16_hi v[96:97], v92, off offset:3072
	v_bfe_u32 v92, v93, 16, 1
	v_add3_u32 v96, v93, v92, s86
	v_add_co_u32_e32 v92, vcc, 0x1c000, v94
	s_nop 1
	v_addc_co_u32_e32 v93, vcc, 0, v95, vcc
	global_store_short_d16_hi v[92:93], v96, off offset:3584

; __device__ __forceinline__ unsigned f2bf(float f) { unsigned u = __float_as_uint(f); return (u + 0x7fffu + ((u >> 16) & 1u)) >> 16; }
; __device__ __forceinline__ u32x4 pack8(const float* v) { u32x4 w; w.x = pk2(v[0], v[1]); w.y = pk2(v[2], v[3]); w.z = pk2(v[4], v[5]); w.w = pk2(v[6], v[7]); return w; }
;     __device__ __forceinline__ void operator()(const f32x4 (&acc)[2][2][4][2], const pg8::Unit& u, int wr, int wc, int fr, int fq) const {
;     ...
;             const int b = (t >= TB) ? 1 : 0, i = t - b * TB;
;             const float rstd = rsqrtf(((const float*)(ws + O_SSQ))[t * 2 + 1] * (1.f / 128.f) + EPS);
; #pragma unroll
;             for (int e = 0; e < 8; ++e) v[e] *= rstd;
;             const int h = c0 >> 7, w = c0 & 127;
;             if (w < 64) *(u32x4*)((bf16_t*)(ws + O_KB) + (size_t)t * 768 + h * 96 + w) = pack8(v);
;             else { bf16_t* dst = (bf16_t*)(ws + O_VBT) + ((size_t)(b * 8 + h) * 64 + (w - 64)) * TB + i;
; #pragma unroll
;                 for (int e = 0; e < 8; ++e) dst[(size_t)e * TB] = (bf16_t)f2bf(v[e]); }
.LBB0_623:
	s_or_b64 exec, exec, s[0:1]
	v_add_u32_e32 v98, 0xa0, v162
	v_lshlrev_b32_e32 v92, 1, v98
	v_ashrrev_i32_e32 v93, 31, v92
	v_lshl_add_u64 v[94:95], v[92:93], 2, s[4:5]
	v_add_co_u32_e32 v92, vcc, 0x380000, v94
	v_cmp_lt_i32_e64 s[40:41], s84, v98
	s_nop 0
	v_addc_co_u32_e32 v93, vcc, 0, v95, vcc
	s_nop 0
	v_cndmask_b32_e64 v99, 0, 8, s[40:41]
	v_mov_b32_e32 v92, v184
	v_fmamk_f32 v92, v92, 0x3c000000, v216
	v_mul_f32_e32 v93, 0x4b800000, v92
	v_cmp_gt_f32_e32 vcc, s33, v92
	s_nop 1
	v_cndmask_b32_e32 v92, v92, v93, vcc
	v_rsq_f32_e32 v96, v92
	v_cndmask_b32_e64 v92, 0, v226, s[40:41]
	v_add_u32_e32 v92, v92, v98
	v_ashrrev_i32_e32 v93, 31, v92
	v_mul_f32_e32 v97, 0x45800000, v96
	v_cndmask_b32_e32 v104, v96, v97, vcc
	v_pk_mul_f32 v[96:97], v[88:89], v[104:105] op_sel_hi:[1,0]
	v_pk_mul_f32 v[90:91], v[90:91], v[104:105] op_sel_hi:[1,0]
	v_pk_mul_f32 v[88:89], v[84:85], v[104:105] op_sel_hi:[1,0]
	v_pk_mul_f32 v[84:85], v[86:87], v[104:105] op_sel_hi:[1,0]
	s_and_saveexec_b64 s[0:1], s[48:49]
	s_xor_b64 s[0:1], exec, s[0:1]
	s_cbranch_execz .LBB0_625
	v_add_u32_e32 v86, v99, v164
	v_ashrrev_i32_e32 v87, 31, v86
	v_lshlrev_b64 v[86:87], 6, v[86:87]
	v_lshl_add_u64 v[86:87], v[86:87], 0, v[148:149]
	v_mov_b64_e32 v[104:105], s[34:35]
	s_movk_i32 s24, 0x4200
	v_mad_u64_u32 v[104:105], s[18:19], v86, s24, v[104:105]
	v_mad_i32_i24 v105, v87, s24, v105
	v_lshl_add_u64 v[86:87], v[92:93], 1, v[104:105]
	v_bfe_u32 v104, v96, 16, 1
	v_add3_u32 v96, v96, v104, s86
	global_store_short_d16_hi v[86:87], v96, off
	v_bfe_u32 v96, v97, 16, 1
	s_movk_i32 s18, 0x4000
	v_add3_u32 v104, v97, v96, s86
	v_add_co_u32_e32 v96, vcc, s18, v86
	s_mov_b32 s18, 0x8000
	s_nop 0
	v_addc_co_u32_e32 v97, vcc, 0, v87, vcc
	global_store_short_d16_hi v[96:97], v104, off offset:512
	v_bfe_u32 v96, v90, 16, 1
	v_add3_u32 v90, v90, v96, s86
	v_add_co_u32_e32 v96, vcc, s18, v86
	s_nop 1
	v_addc_co_u32_e32 v97, vcc, 0, v87, vcc
	global_store_short_d16_hi v[96:97], v90, off offset:1024
	v_bfe_u32 v90, v91, 16, 1
	v_add3_u32 v96, v91, v90, s86
	v_add_co_u32_e32 v90, vcc, s83, v86
	s_nop 1
	v_addc_co_u32_e32 v91, vcc, 0, v87, vcc
	global_store_short_d16_hi v[90:91], v96, off offset:1536
	v_bfe_u32 v90, v88, 16, 1
	v_add3_u32 v88, v88, v90, s86
	v_add_co_u32_e32 v90, vcc, s79, v86
	s_nop 1
	v_addc_co_u32_e32 v91, vcc, 0, v87, vcc
	global_store_short_d16_hi v[90:91], v88, off offset:2048
	v_bfe_u32 v88, v89, 16, 1
	v_add3_u32 v90, v89, v88, s86
	v_add_co_u32_e32 v88, vcc, s78, v86
	s_nop 1
	v_addc_co_u32_e32 v89, vcc, 0, v87, vcc
	global_store_short_d16_hi v[88:89], v90, off offset:2560
	v_bfe_u32 v88, v84, 16, 1
	v_add3_u32 v84, v84, v88, s86
	v_add_co_u32_e32 v88, vcc, 0x18000, v86
	s_nop 1
	v_addc_co_u32_e32 v89, vcc, 0, v87, vcc
	global_store_short_d16_hi v[88:89], v84, off offset:3072
	v_bfe_u32 v84, v85, 16, 1
	v_add3_u32 v88, v85, v84, s86
	v_add_co_u32_e32 v84, vcc, 0x1c000, v86
	s_nop 1
	v_addc_co_u32_e32 v85, vcc, 0, v87, vcc
	global_store_short_d16_hi v[84:85], v88, off offset:3584

; __device__ __forceinline__ unsigned f2bf(float f) { unsigned u = __float_as_uint(f); return (u + 0x7fffu + ((u >> 16) & 1u)) >> 16; }
; __device__ __forceinline__ u32x4 pack8(const float* v) { u32x4 w; w.x = pk2(v[0], v[1]); w.y = pk2(v[2], v[3]); w.z = pk2(v[4], v[5]); w.w = pk2(v[6], v[7]); return w; }
;     __device__ __forceinline__ void operator()(const f32x4 (&acc)[2][2][4][2], const pg8::Unit& u, int wr, int wc, int fr, int fq) const {
;     ...
;             const int b = (t >= TB) ? 1 : 0, i = t - b * TB;
;             const float rstd = rsqrtf(((const float*)(ws + O_SSQ))[t * 2 + 1] * (1.f / 128.f) + EPS);
; #pragma unroll
;             for (int e = 0; e < 8; ++e) v[e] *= rstd;
;             const int h = c0 >> 7, w = c0 & 127;
;             if (w < 64) *(u32x4*)((bf16_t*)(ws + O_KB) + (size_t)t * 768 + h * 96 + w) = pack8(v);
;             else { bf16_t* dst = (bf16_t*)(ws + O_VBT) + ((size_t)(b * 8 + h) * 64 + (w - 64)) * TB + i;
; #pragma unroll
;                 for (int e = 0; e < 8; ++e) dst[(size_t)e * TB] = (bf16_t)f2bf(v[e]); }
.LBB0_627:
	s_or_b64 exec, exec, s[0:1]
	v_add_u32_e32 v90, 0xb0, v162
	v_lshlrev_b32_e32 v84, 1, v90
	v_ashrrev_i32_e32 v85, 31, v84
	v_lshl_add_u64 v[86:87], v[84:85], 2, s[4:5]
	v_add_co_u32_e32 v84, vcc, 0x380000, v86
	v_cmp_lt_i32_e64 s[40:41], s84, v90
	s_nop 0
	v_addc_co_u32_e32 v85, vcc, 0, v87, vcc
	s_nop 0
	v_mov_b32_e32 v84, v185
	v_fmamk_f32 v84, v84, 0x3c000000, v216
	v_mul_f32_e32 v85, 0x4b800000, v84
	v_cmp_gt_f32_e32 vcc, s33, v84
	s_nop 1
	v_cndmask_b32_e32 v84, v84, v85, vcc
	v_rsq_f32_e32 v88, v84
	v_cndmask_b32_e64 v84, 0, v226, s[40:41]
	v_add_u32_e32 v84, v84, v90
	v_ashrrev_i32_e32 v85, 31, v84
	v_mul_f32_e32 v89, 0x45800000, v88
	v_cndmask_b32_e32 v96, v88, v89, vcc
	v_pk_mul_f32 v[88:89], v[80:81], v[96:97] op_sel_hi:[1,0]
	v_pk_mul_f32 v[82:83], v[82:83], v[96:97] op_sel_hi:[1,0]
	v_pk_mul_f32 v[80:81], v[76:77], v[96:97] op_sel_hi:[1,0]
	v_pk_mul_f32 v[76:77], v[78:79], v[96:97] op_sel_hi:[1,0]
	v_cndmask_b32_e64 v78, 0, 8, s[40:41]
	s_and_saveexec_b64 s[0:1], s[48:49]
	s_xor_b64 s[0:1], exec, s[0:1]
	s_cbranch_execz .LBB0_629
	v_add_u32_e32 v96, v78, v164
	v_ashrrev_i32_e32 v97, 31, v96
	v_lshlrev_b64 v[96:97], 6, v[96:97]
	v_lshl_add_u64 v[96:97], v[96:97], 0, v[148:149]
	v_mov_b64_e32 v[104:105], s[34:35]
	s_movk_i32 s24, 0x4200
	v_mad_u64_u32 v[104:105], s[18:19], v96, s24, v[104:105]
	v_mad_i32_i24 v105, v97, s24, v105
	v_bfe_u32 v79, v88, 16, 1
	v_lshl_add_u64 v[96:97], v[84:85], 1, v[104:105]
	v_add3_u32 v79, v88, v79, s86
	s_movk_i32 s18, 0x4000
	global_store_short_d16_hi v[96:97], v79, off
	v_bfe_u32 v79, v89, 16, 1
	v_add_co_u32_e32 v88, vcc, s18, v96
	v_add3_u32 v79, v89, v79, s86
	s_nop 0
	v_addc_co_u32_e32 v89, vcc, 0, v97, vcc
	s_mov_b32 s18, 0x8000
	global_store_short_d16_hi v[88:89], v79, off offset:512
	v_bfe_u32 v79, v82, 16, 1
	v_add_co_u32_e32 v88, vcc, s18, v96
	v_add3_u32 v79, v82, v79, s86
	s_nop 0
	v_addc_co_u32_e32 v89, vcc, 0, v97, vcc
	global_store_short_d16_hi v[88:89], v79, off offset:1024
	v_bfe_u32 v79, v83, 16, 1
	v_add_co_u32_e32 v82, vcc, s83, v96
	v_add3_u32 v79, v83, v79, s86
	s_nop 0
	v_addc_co_u32_e32 v83, vcc, 0, v97, vcc
	global_store_short_d16_hi v[82:83], v79, off offset:1536
	v_bfe_u32 v79, v80, 16, 1
	v_add_co_u32_e32 v82, vcc, s79, v96
	v_add3_u32 v79, v80, v79, s86
	s_nop 0
	v_addc_co_u32_e32 v83, vcc, 0, v97, vcc
	global_store_short_d16_hi v[82:83], v79, off offset:2048
	v_bfe_u32 v79, v81, 16, 1
	v_add_co_u32_e32 v80, vcc, s78, v96
	v_add3_u32 v79, v81, v79, s86
	s_nop 0
	v_addc_co_u32_e32 v81, vcc, 0, v97, vcc
	global_store_short_d16_hi v[80:81], v79, off offset:2560
	v_bfe_u32 v79, v76, 16, 1
	v_add_co_u32_e32 v80, vcc, 0x18000, v96
	v_add3_u32 v76, v76, v79, s86
	s_nop 0
	v_addc_co_u32_e32 v81, vcc, 0, v97, vcc
	global_store_short_d16_hi v[80:81], v76, off offset:3072
	v_bfe_u32 v76, v77, 16, 1
	v_add3_u32 v79, v77, v76, s86
	v_add_co_u32_e32 v76, vcc, 0x1c000, v96
	s_nop 1
	v_addc_co_u32_e32 v77, vcc, 0, v97, vcc
	global_store_short_d16_hi v[76:77], v79, off offset:3584

; __device__ __forceinline__ unsigned f2bf(float f) { unsigned u = __float_as_uint(f); return (u + 0x7fffu + ((u >> 16) & 1u)) >> 16; }
; __device__ __forceinline__ u32x4 pack8(const float* v) { u32x4 w; w.x = pk2(v[0], v[1]); w.y = pk2(v[2], v[3]); w.z = pk2(v[4], v[5]); w.w = pk2(v[6], v[7]); return w; }
;     __device__ __forceinline__ void operator()(const f32x4 (&acc)[2][2][4][2], const pg8::Unit& u, int wr, int wc, int fr, int fq) const {
;     ...
;             const int b = (t >= TB) ? 1 : 0, i = t - b * TB;
;             const float rstd = rsqrtf(((const float*)(ws + O_SSQ))[t * 2 + 1] * (1.f / 128.f) + EPS);
; #pragma unroll
;             for (int e = 0; e < 8; ++e) v[e] *= rstd;
;             const int h = c0 >> 7, w = c0 & 127;
;             if (w < 64) *(u32x4*)((bf16_t*)(ws + O_KB) + (size_t)t * 768 + h * 96 + w) = pack8(v);
;             else { bf16_t* dst = (bf16_t*)(ws + O_VBT) + ((size_t)(b * 8 + h) * 64 + (w - 64)) * TB + i;
; #pragma unroll
;                 for (int e = 0; e < 8; ++e) dst[(size_t)e * TB] = (bf16_t)f2bf(v[e]); }
.LBB0_631:
	s_or_b64 exec, exec, s[0:1]
	s_mov_b64 s[0:1], 0x380004
	v_lshl_add_u64 v[76:77], v[150:151], 0, s[0:1]
	s_nop 0
	v_mov_b32_e32 v76, v178
	v_fmamk_f32 v76, v76, 0x3c000000, v216
	v_mul_f32_e32 v77, 0x4b800000, v76
	v_cmp_gt_f32_e32 vcc, s33, v76
	s_nop 1
	v_cndmask_b32_e32 v76, v76, v77, vcc
	v_rsq_f32_e32 v76, v76
	v_add_u32_e32 v77, 0x80, v163
	v_ashrrev_i32_e32 v79, 7, v77
	v_mul_f32_e32 v77, 0x45800000, v76
	v_cndmask_b32_e32 v80, v76, v77, vcc
	v_pk_mul_f32 v[76:77], v[72:73], v[80:81] op_sel_hi:[1,0]
	v_pk_mul_f32 v[74:75], v[74:75], v[80:81] op_sel_hi:[1,0]
	v_pk_mul_f32 v[72:73], v[68:69], v[80:81] op_sel_hi:[1,0]
	v_pk_mul_f32 v[70:71], v[70:71], v[80:81] op_sel_hi:[1,0]
	s_and_saveexec_b64 s[0:1], s[48:49]
	s_xor_b64 s[0:1], exec, s[0:1]
	s_cbranch_execz .LBB0_633
	v_add_u32_e32 v68, v79, v165
	v_ashrrev_i32_e32 v69, 31, v68
	v_lshlrev_b64 v[68:69], 6, v[68:69]
	v_lshl_add_u64 v[68:69], v[68:69], 0, v[148:149]
	v_mov_b64_e32 v[80:81], s[34:35]
	s_movk_i32 s24, 0x4200
	v_mad_u64_u32 v[80:81], s[18:19], v68, s24, v[80:81]
	v_mad_i32_i24 v81, v69, s24, v81
	v_lshl_add_u64 v[68:69], v[134:135], 1, v[80:81]
	v_bfe_u32 v80, v76, 16, 1
	v_add3_u32 v76, v76, v80, s86
	global_store_short_d16_hi v[68:69], v76, off
	v_bfe_u32 v76, v77, 16, 1
	s_movk_i32 s18, 0x4000
	v_add3_u32 v80, v77, v76, s86
	v_add_co_u32_e32 v76, vcc, s18, v68
	s_mov_b32 s18, 0x8000
	s_nop 0
	v_addc_co_u32_e32 v77, vcc, 0, v69, vcc
	global_store_short_d16_hi v[76:77], v80, off offset:512
	v_bfe_u32 v76, v74, 16, 1
	v_add3_u32 v74, v74, v76, s86
	v_add_co_u32_e32 v76, vcc, s18, v68
	s_nop 1
	v_addc_co_u32_e32 v77, vcc, 0, v69, vcc
	global_store_short_d16_hi v[76:77], v74, off offset:1024
	v_bfe_u32 v74, v75, 16, 1
	v_add3_u32 v76, v75, v74, s86
	v_add_co_u32_e32 v74, vcc, s83, v68
	s_nop 1
	v_addc_co_u32_e32 v75, vcc, 0, v69, vcc
	global_store_short_d16_hi v[74:75], v76, off offset:1536
	v_bfe_u32 v74, v72, 16, 1
	v_add3_u32 v72, v72, v74, s86
	v_add_co_u32_e32 v74, vcc, s79, v68
	s_nop 1
	v_addc_co_u32_e32 v75, vcc, 0, v69, vcc
	global_store_short_d16_hi v[74:75], v72, off offset:2048
	v_bfe_u32 v72, v73, 16, 1
	v_add3_u32 v74, v73, v72, s86
	v_add_co_u32_e32 v72, vcc, s78, v68
	s_nop 1
	v_addc_co_u32_e32 v73, vcc, 0, v69, vcc
	global_store_short_d16_hi v[72:73], v74, off offset:2560
	v_bfe_u32 v72, v70, 16, 1
	v_add3_u32 v70, v70, v72, s86
	v_add_co_u32_e32 v72, vcc, 0x18000, v68
	s_nop 1
	v_addc_co_u32_e32 v73, vcc, 0, v69, vcc
	global_store_short_d16_hi v[72:73], v70, off offset:3072
	v_bfe_u32 v70, v71, 16, 1
	v_add_co_u32_e32 v68, vcc, 0x1c000, v68
	v_add3_u32 v70, v71, v70, s86
	s_nop 0
	v_addc_co_u32_e32 v69, vcc, 0, v69, vcc
	global_store_short_d16_hi v[68:69], v70, off offset:3584

; __device__ __forceinline__ unsigned f2bf(float f) { unsigned u = __float_as_uint(f); return (u + 0x7fffu + ((u >> 16) & 1u)) >> 16; }
; __device__ __forceinline__ u32x4 pack8(const float* v) { u32x4 w; w.x = pk2(v[0], v[1]); w.y = pk2(v[2], v[3]); w.z = pk2(v[4], v[5]); w.w = pk2(v[6], v[7]); return w; }
;     __device__ __forceinline__ void operator()(const f32x4 (&acc)[2][2][4][2], const pg8::Unit& u, int wr, int wc, int fr, int fq) const {
;     ...
;             const int b = (t >= TB) ? 1 : 0, i = t - b * TB;
;             const float rstd = rsqrtf(((const float*)(ws + O_SSQ))[t * 2 + 1] * (1.f / 128.f) + EPS);
; #pragma unroll
;             for (int e = 0; e < 8; ++e) v[e] *= rstd;
;             const int h = c0 >> 7, w = c0 & 127;
;             if (w < 64) *(u32x4*)((bf16_t*)(ws + O_KB) + (size_t)t * 768 + h * 96 + w) = pack8(v);
;             else { bf16_t* dst = (bf16_t*)(ws + O_VBT) + ((size_t)(b * 8 + h) * 64 + (w - 64)) * TB + i;
; #pragma unroll
;                 for (int e = 0; e < 8; ++e) dst[(size_t)e * TB] = (bf16_t)f2bf(v[e]); }
.LBB0_635:
	s_or_b64 exec, exec, s[0:1]
	s_mov_b64 s[0:1], 0x380004
	v_lshl_add_u64 v[70:71], v[138:139], 0, s[0:1]
	s_nop 0
	v_mov_b32_e32 v70, v179
	v_fmamk_f32 v70, v70, 0x3c000000, v216
	v_mul_f32_e32 v71, 0x4b800000, v70
	v_cmp_gt_f32_e32 vcc, s33, v70
	s_nop 1
	v_cndmask_b32_e32 v70, v70, v71, vcc
	v_rsq_f32_e32 v70, v70
	s_nop 0
	v_mul_f32_e32 v71, 0x45800000, v70
	v_cndmask_b32_e32 v72, v70, v71, vcc
	v_pk_mul_f32 v[70:71], v[64:65], v[72:73] op_sel_hi:[1,0]
	v_pk_mul_f32 v[66:67], v[66:67], v[72:73] op_sel_hi:[1,0]
	v_pk_mul_f32 v[64:65], v[60:61], v[72:73] op_sel_hi:[1,0]
	v_pk_mul_f32 v[60:61], v[62:63], v[72:73] op_sel_hi:[1,0]
	s_and_saveexec_b64 s[0:1], s[48:49]
	s_xor_b64 s[0:1], exec, s[0:1]
	s_cbranch_execz .LBB0_637
	v_add_u32_e32 v62, v157, v79
	v_ashrrev_i32_e32 v63, 31, v62
	v_lshlrev_b64 v[62:63], 6, v[62:63]
	v_lshl_add_u64 v[62:63], v[62:63], 0, v[148:149]
	v_mov_b64_e32 v[72:73], s[34:35]
	s_movk_i32 s24, 0x4200
	v_mad_u64_u32 v[72:73], s[18:19], v62, s24, v[72:73]
	v_mad_i32_i24 v73, v63, s24, v73
	v_lshl_add_u64 v[62:63], v[136:137], 1, v[72:73]
	v_bfe_u32 v72, v70, 16, 1
	v_add3_u32 v70, v70, v72, s86
	global_store_short_d16_hi v[62:63], v70, off
	v_bfe_u32 v70, v71, 16, 1
	s_movk_i32 s18, 0x4000
	v_add3_u32 v72, v71, v70, s86
	v_add_co_u32_e32 v70, vcc, s18, v62
	s_mov_b32 s18, 0x8000
	s_nop 0
	v_addc_co_u32_e32 v71, vcc, 0, v63, vcc
	global_store_short_d16_hi v[70:71], v72, off offset:512
	v_bfe_u32 v70, v66, 16, 1
	v_add3_u32 v66, v66, v70, s86
	v_add_co_u32_e32 v70, vcc, s18, v62
	s_nop 1
	v_addc_co_u32_e32 v71, vcc, 0, v63, vcc
	global_store_short_d16_hi v[70:71], v66, off offset:1024
	v_bfe_u32 v66, v67, 16, 1
	v_add3_u32 v70, v67, v66, s86
	v_add_co_u32_e32 v66, vcc, s83, v62
	s_nop 1
	v_addc_co_u32_e32 v67, vcc, 0, v63, vcc
	global_store_short_d16_hi v[66:67], v70, off offset:1536
	v_bfe_u32 v66, v64, 16, 1
	v_add3_u32 v64, v64, v66, s86
	v_add_co_u32_e32 v66, vcc, s79, v62
	s_nop 1
	v_addc_co_u32_e32 v67, vcc, 0, v63, vcc
	global_store_short_d16_hi v[66:67], v64, off offset:2048
	v_bfe_u32 v64, v65, 16, 1
	v_add3_u32 v66, v65, v64, s86
	v_add_co_u32_e32 v64, vcc, s78, v62
	s_nop 1
	v_addc_co_u32_e32 v65, vcc, 0, v63, vcc
	global_store_short_d16_hi v[64:65], v66, off offset:2560
	v_bfe_u32 v64, v60, 16, 1
	v_add3_u32 v60, v60, v64, s86
	v_add_co_u32_e32 v64, vcc, 0x18000, v62
	s_nop 1
	v_addc_co_u32_e32 v65, vcc, 0, v63, vcc
	global_store_short_d16_hi v[64:65], v60, off offset:3072
	v_bfe_u32 v60, v61, 16, 1
	v_add3_u32 v64, v61, v60, s86
	v_add_co_u32_e32 v60, vcc, 0x1c000, v62
	s_nop 1
	v_addc_co_u32_e32 v61, vcc, 0, v63, vcc
	global_store_short_d16_hi v[60:61], v64, off offset:3584

; __device__ __forceinline__ unsigned f2bf(float f) { unsigned u = __float_as_uint(f); return (u + 0x7fffu + ((u >> 16) & 1u)) >> 16; }
; __device__ __forceinline__ u32x4 pack8(const float* v) { u32x4 w; w.x = pk2(v[0], v[1]); w.y = pk2(v[2], v[3]); w.z = pk2(v[4], v[5]); w.w = pk2(v[6], v[7]); return w; }
;     __device__ __forceinline__ void operator()(const f32x4 (&acc)[2][2][4][2], const pg8::Unit& u, int wr, int wc, int fr, int fq) const {
;     ...
;             const int b = (t >= TB) ? 1 : 0, i = t - b * TB;
;             const float rstd = rsqrtf(((const float*)(ws + O_SSQ))[t * 2 + 1] * (1.f / 128.f) + EPS);
; #pragma unroll
;             for (int e = 0; e < 8; ++e) v[e] *= rstd;
;             const int h = c0 >> 7, w = c0 & 127;
;             if (w < 64) *(u32x4*)((bf16_t*)(ws + O_KB) + (size_t)t * 768 + h * 96 + w) = pack8(v);
;             else { bf16_t* dst = (bf16_t*)(ws + O_VBT) + ((size_t)(b * 8 + h) * 64 + (w - 64)) * TB + i;
; #pragma unroll
;                 for (int e = 0; e < 8; ++e) dst[(size_t)e * TB] = (bf16_t)f2bf(v[e]); }
.LBB0_639:
	s_or_b64 exec, exec, s[0:1]
	s_mov_b64 s[0:1], 0x380004
	v_lshl_add_u64 v[60:61], v[126:127], 0, s[0:1]
	s_nop 0
	v_mov_b32_e32 v60, v180
	v_fmamk_f32 v60, v60, 0x3c000000, v216
	v_mul_f32_e32 v61, 0x4b800000, v60
	v_cmp_gt_f32_e32 vcc, s33, v60
	s_nop 1
	v_cndmask_b32_e32 v60, v60, v61, vcc
	v_rsq_f32_e32 v60, v60
	s_nop 0
	v_mul_f32_e32 v61, 0x45800000, v60
	v_cndmask_b32_e32 v62, v60, v61, vcc
	v_pk_mul_f32 v[60:61], v[56:57], v[62:63] op_sel_hi:[1,0]
	v_pk_mul_f32 v[58:59], v[58:59], v[62:63] op_sel_hi:[1,0]
	v_pk_mul_f32 v[56:57], v[52:53], v[62:63] op_sel_hi:[1,0]
	v_pk_mul_f32 v[52:53], v[54:55], v[62:63] op_sel_hi:[1,0]
	s_and_saveexec_b64 s[0:1], s[48:49]
	s_xor_b64 s[0:1], exec, s[0:1]
	s_cbranch_execz .LBB0_641
	v_add_u32_e32 v54, v131, v79
	v_ashrrev_i32_e32 v55, 31, v54
	v_lshlrev_b64 v[54:55], 6, v[54:55]
	v_lshl_add_u64 v[54:55], v[54:55], 0, v[148:149]
	v_mov_b64_e32 v[62:63], s[34:35]
	s_movk_i32 s24, 0x4200
	v_mad_u64_u32 v[62:63], s[18:19], v54, s24, v[62:63]
	v_mad_i32_i24 v63, v55, s24, v63
	v_lshl_add_u64 v[54:55], v[124:125], 1, v[62:63]
	v_bfe_u32 v62, v60, 16, 1
	v_add3_u32 v60, v60, v62, s86
	global_store_short_d16_hi v[54:55], v60, off
	v_bfe_u32 v60, v61, 16, 1
	s_movk_i32 s18, 0x4000
	v_add3_u32 v62, v61, v60, s86
	v_add_co_u32_e32 v60, vcc, s18, v54
	s_mov_b32 s18, 0x8000
	s_nop 0
	v_addc_co_u32_e32 v61, vcc, 0, v55, vcc
	global_store_short_d16_hi v[60:61], v62, off offset:512
	v_bfe_u32 v60, v58, 16, 1
	v_add3_u32 v58, v58, v60, s86
	v_add_co_u32_e32 v60, vcc, s18, v54
	s_nop 1
	v_addc_co_u32_e32 v61, vcc, 0, v55, vcc
	global_store_short_d16_hi v[60:61], v58, off offset:1024
	v_bfe_u32 v58, v59, 16, 1
	v_add3_u32 v60, v59, v58, s86
	v_add_co_u32_e32 v58, vcc, s83, v54
	s_nop 1
	v_addc_co_u32_e32 v59, vcc, 0, v55, vcc
	global_store_short_d16_hi v[58:59], v60, off offset:1536
	v_bfe_u32 v58, v56, 16, 1
	v_add3_u32 v56, v56, v58, s86
	v_add_co_u32_e32 v58, vcc, s79, v54
	s_nop 1
	v_addc_co_u32_e32 v59, vcc, 0, v55, vcc
	global_store_short_d16_hi v[58:59], v56, off offset:2048
	v_bfe_u32 v56, v57, 16, 1
	v_add3_u32 v58, v57, v56, s86
	v_add_co_u32_e32 v56, vcc, s78, v54
	s_nop 1
	v_addc_co_u32_e32 v57, vcc, 0, v55, vcc
	global_store_short_d16_hi v[56:57], v58, off offset:2560
	v_bfe_u32 v56, v52, 16, 1
	v_add3_u32 v52, v52, v56, s86
	v_add_co_u32_e32 v56, vcc, 0x18000, v54
	s_nop 1
	v_addc_co_u32_e32 v57, vcc, 0, v55, vcc
	global_store_short_d16_hi v[56:57], v52, off offset:3072
	v_bfe_u32 v52, v53, 16, 1
	v_add3_u32 v56, v53, v52, s86
	v_add_co_u32_e32 v52, vcc, 0x1c000, v54
	s_nop 1
	v_addc_co_u32_e32 v53, vcc, 0, v55, vcc
	global_store_short_d16_hi v[52:53], v56, off offset:3584

; __device__ __forceinline__ unsigned f2bf(float f) { unsigned u = __float_as_uint(f); return (u + 0x7fffu + ((u >> 16) & 1u)) >> 16; }
; __device__ __forceinline__ u32x4 pack8(const float* v) { u32x4 w; w.x = pk2(v[0], v[1]); w.y = pk2(v[2], v[3]); w.z = pk2(v[4], v[5]); w.w = pk2(v[6], v[7]); return w; }
;     __device__ __forceinline__ void operator()(const f32x4 (&acc)[2][2][4][2], const pg8::Unit& u, int wr, int wc, int fr, int fq) const {
;     ...
;             const int b = (t >= TB) ? 1 : 0, i = t - b * TB;
;             const float rstd = rsqrtf(((const float*)(ws + O_SSQ))[t * 2 + 1] * (1.f / 128.f) + EPS);
; #pragma unroll
;             for (int e = 0; e < 8; ++e) v[e] *= rstd;
;             const int h = c0 >> 7, w = c0 & 127;
;             if (w < 64) *(u32x4*)((bf16_t*)(ws + O_KB) + (size_t)t * 768 + h * 96 + w) = pack8(v);
;             else { bf16_t* dst = (bf16_t*)(ws + O_VBT) + ((size_t)(b * 8 + h) * 64 + (w - 64)) * TB + i;
; #pragma unroll
;                 for (int e = 0; e < 8; ++e) dst[(size_t)e * TB] = (bf16_t)f2bf(v[e]); }
.LBB0_643:
	s_or_b64 exec, exec, s[0:1]
	s_mov_b64 s[0:1], 0x380004
	v_lshl_add_u64 v[52:53], v[118:119], 0, s[0:1]
	s_nop 0
	v_mov_b32_e32 v52, v181
	v_fmamk_f32 v52, v52, 0x3c000000, v216
	v_mul_f32_e32 v53, 0x4b800000, v52
	v_cmp_gt_f32_e32 vcc, s33, v52
	s_nop 1
	v_cndmask_b32_e32 v52, v52, v53, vcc
	v_rsq_f32_e32 v52, v52
	s_nop 0
	v_mul_f32_e32 v53, 0x45800000, v52
	v_cndmask_b32_e32 v54, v52, v53, vcc
	v_pk_mul_f32 v[52:53], v[48:49], v[54:55] op_sel_hi:[1,0]
	v_pk_mul_f32 v[50:51], v[50:51], v[54:55] op_sel_hi:[1,0]
	v_pk_mul_f32 v[48:49], v[32:33], v[54:55] op_sel_hi:[1,0]
	v_pk_mul_f32 v[32:33], v[34:35], v[54:55] op_sel_hi:[1,0]
	s_and_saveexec_b64 s[0:1], s[48:49]
	s_xor_b64 s[0:1], exec, s[0:1]
	s_cbranch_execz .LBB0_645
	v_add_u32_e32 v34, v123, v79
	v_ashrrev_i32_e32 v35, 31, v34
	v_lshlrev_b64 v[34:35], 6, v[34:35]
	v_lshl_add_u64 v[34:35], v[34:35], 0, v[148:149]
	v_mov_b64_e32 v[54:55], s[34:35]
	s_movk_i32 s24, 0x4200
	v_mad_u64_u32 v[54:55], s[18:19], v34, s24, v[54:55]
	v_mad_i32_i24 v55, v35, s24, v55
	v_lshl_add_u64 v[34:35], v[116:117], 1, v[54:55]
	v_bfe_u32 v54, v52, 16, 1
	v_add3_u32 v52, v52, v54, s86
	global_store_short_d16_hi v[34:35], v52, off
	v_bfe_u32 v52, v53, 16, 1
	s_movk_i32 s18, 0x4000
	v_add3_u32 v54, v53, v52, s86
	v_add_co_u32_e32 v52, vcc, s18, v34
	s_mov_b32 s18, 0x8000
	s_nop 0
	v_addc_co_u32_e32 v53, vcc, 0, v35, vcc
	global_store_short_d16_hi v[52:53], v54, off offset:512
	v_bfe_u32 v52, v50, 16, 1
	v_add3_u32 v50, v50, v52, s86
	v_add_co_u32_e32 v52, vcc, s18, v34
	s_nop 1
	v_addc_co_u32_e32 v53, vcc, 0, v35, vcc
	global_store_short_d16_hi v[52:53], v50, off offset:1024
	v_bfe_u32 v50, v51, 16, 1
	v_add3_u32 v52, v51, v50, s86
	v_add_co_u32_e32 v50, vcc, s83, v34
	s_nop 1
	v_addc_co_u32_e32 v51, vcc, 0, v35, vcc
	global_store_short_d16_hi v[50:51], v52, off offset:1536
	v_bfe_u32 v50, v48, 16, 1
	v_add3_u32 v48, v48, v50, s86
	v_add_co_u32_e32 v50, vcc, s79, v34
	s_nop 1
	v_addc_co_u32_e32 v51, vcc, 0, v35, vcc
	global_store_short_d16_hi v[50:51], v48, off offset:2048
	v_bfe_u32 v48, v49, 16, 1
	v_add3_u32 v50, v49, v48, s86
	v_add_co_u32_e32 v48, vcc, s78, v34
	s_nop 1
	v_addc_co_u32_e32 v49, vcc, 0, v35, vcc
	global_store_short_d16_hi v[48:49], v50, off offset:2560
	v_bfe_u32 v48, v32, 16, 1
	v_add3_u32 v32, v32, v48, s86
	v_add_co_u32_e32 v48, vcc, 0x18000, v34
	s_nop 1
	v_addc_co_u32_e32 v49, vcc, 0, v35, vcc
	global_store_short_d16_hi v[48:49], v32, off offset:3072
	v_bfe_u32 v32, v33, 16, 1
	v_add3_u32 v48, v33, v32, s86
	v_add_co_u32_e32 v32, vcc, 0x1c000, v34
	s_nop 1
	v_addc_co_u32_e32 v33, vcc, 0, v35, vcc
	global_store_short_d16_hi v[32:33], v48, off offset:3584

; __device__ __forceinline__ unsigned f2bf(float f) { unsigned u = __float_as_uint(f); return (u + 0x7fffu + ((u >> 16) & 1u)) >> 16; }
; __device__ __forceinline__ u32x4 pack8(const float* v) { u32x4 w; w.x = pk2(v[0], v[1]); w.y = pk2(v[2], v[3]); w.z = pk2(v[4], v[5]); w.w = pk2(v[6], v[7]); return w; }
;     __device__ __forceinline__ void operator()(const f32x4 (&acc)[2][2][4][2], const pg8::Unit& u, int wr, int wc, int fr, int fq) const {
;     ...
;             const int b = (t >= TB) ? 1 : 0, i = t - b * TB;
;             const float rstd = rsqrtf(((const float*)(ws + O_SSQ))[t * 2 + 1] * (1.f / 128.f) + EPS);
; #pragma unroll
;             for (int e = 0; e < 8; ++e) v[e] *= rstd;
;             const int h = c0 >> 7, w = c0 & 127;
;             if (w < 64) *(u32x4*)((bf16_t*)(ws + O_KB) + (size_t)t * 768 + h * 96 + w) = pack8(v);
;             else { bf16_t* dst = (bf16_t*)(ws + O_VBT) + ((size_t)(b * 8 + h) * 64 + (w - 64)) * TB + i;
; #pragma unroll
;                 for (int e = 0; e < 8; ++e) dst[(size_t)e * TB] = (bf16_t)f2bf(v[e]); }
.LBB0_647:
	s_or_b64 exec, exec, s[0:1]
	s_mov_b64 s[0:1], 0x380004
	v_lshl_add_u64 v[32:33], v[110:111], 0, s[0:1]
	s_nop 0
	v_mov_b32_e32 v32, v182
	v_fmamk_f32 v32, v32, 0x3c000000, v216
	v_mul_f32_e32 v33, 0x4b800000, v32
	v_cmp_gt_f32_e32 vcc, s33, v32
	s_nop 1
	v_cndmask_b32_e32 v32, v32, v33, vcc
	v_rsq_f32_e32 v32, v32
	s_nop 0
	v_mul_f32_e32 v33, 0x45800000, v32
	v_cndmask_b32_e32 v34, v32, v33, vcc
	v_pk_mul_f32 v[32:33], v[28:29], v[34:35] op_sel_hi:[1,0]
	v_pk_mul_f32 v[30:31], v[30:31], v[34:35] op_sel_hi:[1,0]
	v_pk_mul_f32 v[28:29], v[24:25], v[34:35] op_sel_hi:[1,0]
	v_pk_mul_f32 v[24:25], v[26:27], v[34:35] op_sel_hi:[1,0]
	s_and_saveexec_b64 s[0:1], s[48:49]
	s_xor_b64 s[0:1], exec, s[0:1]
	s_cbranch_execz .LBB0_649
	v_add_u32_e32 v26, v115, v79
	v_ashrrev_i32_e32 v27, 31, v26
	v_lshlrev_b64 v[26:27], 6, v[26:27]
	v_lshl_add_u64 v[26:27], v[26:27], 0, v[148:149]
	v_mov_b64_e32 v[34:35], s[34:35]
	s_movk_i32 s24, 0x4200
	v_mad_u64_u32 v[34:35], s[18:19], v26, s24, v[34:35]
	v_mad_i32_i24 v35, v27, s24, v35
	v_lshl_add_u64 v[26:27], v[108:109], 1, v[34:35]
	v_bfe_u32 v34, v32, 16, 1
	v_add3_u32 v32, v32, v34, s86
	global_store_short_d16_hi v[26:27], v32, off
	v_bfe_u32 v32, v33, 16, 1
	s_movk_i32 s18, 0x4000
	v_add3_u32 v34, v33, v32, s86
	v_add_co_u32_e32 v32, vcc, s18, v26
	s_mov_b32 s18, 0x8000
	s_nop 0
	v_addc_co_u32_e32 v33, vcc, 0, v27, vcc
	global_store_short_d16_hi v[32:33], v34, off offset:512
	v_bfe_u32 v32, v30, 16, 1
	v_add3_u32 v30, v30, v32, s86
	v_add_co_u32_e32 v32, vcc, s18, v26
	s_nop 1
	v_addc_co_u32_e32 v33, vcc, 0, v27, vcc
	global_store_short_d16_hi v[32:33], v30, off offset:1024
	v_bfe_u32 v30, v31, 16, 1
	v_add3_u32 v32, v31, v30, s86
	v_add_co_u32_e32 v30, vcc, s83, v26
	s_nop 1
	v_addc_co_u32_e32 v31, vcc, 0, v27, vcc
	global_store_short_d16_hi v[30:31], v32, off offset:1536
	v_bfe_u32 v30, v28, 16, 1
	v_add3_u32 v28, v28, v30, s86
	v_add_co_u32_e32 v30, vcc, s79, v26
	s_nop 1
	v_addc_co_u32_e32 v31, vcc, 0, v27, vcc
	global_store_short_d16_hi v[30:31], v28, off offset:2048
	v_bfe_u32 v28, v29, 16, 1
	v_add3_u32 v30, v29, v28, s86
	v_add_co_u32_e32 v28, vcc, s78, v26
	s_nop 1
	v_addc_co_u32_e32 v29, vcc, 0, v27, vcc
	global_store_short_d16_hi v[28:29], v30, off offset:2560
	v_bfe_u32 v28, v24, 16, 1
	v_add3_u32 v24, v24, v28, s86
	v_add_co_u32_e32 v28, vcc, 0x18000, v26
	s_nop 1
	v_addc_co_u32_e32 v29, vcc, 0, v27, vcc
	global_store_short_d16_hi v[28:29], v24, off offset:3072
	v_bfe_u32 v24, v25, 16, 1
	v_add3_u32 v28, v25, v24, s86
	v_add_co_u32_e32 v24, vcc, 0x1c000, v26
	s_nop 1
	v_addc_co_u32_e32 v25, vcc, 0, v27, vcc
	global_store_short_d16_hi v[24:25], v28, off offset:3584

; __device__ __forceinline__ unsigned f2bf(float f) { unsigned u = __float_as_uint(f); return (u + 0x7fffu + ((u >> 16) & 1u)) >> 16; }
; __device__ __forceinline__ u32x4 pack8(const float* v) { u32x4 w; w.x = pk2(v[0], v[1]); w.y = pk2(v[2], v[3]); w.z = pk2(v[4], v[5]); w.w = pk2(v[6], v[7]); return w; }
;     __device__ __forceinline__ void operator()(const f32x4 (&acc)[2][2][4][2], const pg8::Unit& u, int wr, int wc, int fr, int fq) const {
;     ...
;             const int b = (t >= TB) ? 1 : 0, i = t - b * TB;
;             const float rstd = rsqrtf(((const float*)(ws + O_SSQ))[t * 2 + 1] * (1.f / 128.f) + EPS);
; #pragma unroll
;             for (int e = 0; e < 8; ++e) v[e] *= rstd;
;             const int h = c0 >> 7, w = c0 & 127;
;             if (w < 64) *(u32x4*)((bf16_t*)(ws + O_KB) + (size_t)t * 768 + h * 96 + w) = pack8(v);
;             else { bf16_t* dst = (bf16_t*)(ws + O_VBT) + ((size_t)(b * 8 + h) * 64 + (w - 64)) * TB + i;
; #pragma unroll
;                 for (int e = 0; e < 8; ++e) dst[(size_t)e * TB] = (bf16_t)f2bf(v[e]); }
.LBB0_651:
	s_or_b64 exec, exec, s[0:1]
	s_mov_b64 s[0:1], 0x380004
	v_lshl_add_u64 v[24:25], v[102:103], 0, s[0:1]
	s_nop 0
	v_mov_b32_e32 v24, v183
	v_fmamk_f32 v24, v24, 0x3c000000, v216
	v_mul_f32_e32 v25, 0x4b800000, v24
	v_cmp_gt_f32_e32 vcc, s33, v24
	s_nop 1
	v_cndmask_b32_e32 v24, v24, v25, vcc
	v_rsq_f32_e32 v24, v24
	s_nop 0
	v_mul_f32_e32 v25, 0x45800000, v24
	v_cndmask_b32_e32 v26, v24, v25, vcc
	v_pk_mul_f32 v[24:25], v[20:21], v[26:27] op_sel_hi:[1,0]
	v_pk_mul_f32 v[22:23], v[22:23], v[26:27] op_sel_hi:[1,0]
	v_pk_mul_f32 v[20:21], v[16:17], v[26:27] op_sel_hi:[1,0]
	v_pk_mul_f32 v[16:17], v[18:19], v[26:27] op_sel_hi:[1,0]
	s_and_saveexec_b64 s[0:1], s[48:49]
	s_xor_b64 s[0:1], exec, s[0:1]
	s_cbranch_execz .LBB0_653
	v_add_u32_e32 v18, v107, v79
	v_ashrrev_i32_e32 v19, 31, v18
	v_lshlrev_b64 v[18:19], 6, v[18:19]
	v_lshl_add_u64 v[18:19], v[18:19], 0, v[148:149]
	v_mov_b64_e32 v[26:27], s[34:35]
	s_movk_i32 s24, 0x4200
	v_mad_u64_u32 v[26:27], s[18:19], v18, s24, v[26:27]
	v_mad_i32_i24 v27, v19, s24, v27
	v_lshl_add_u64 v[18:19], v[100:101], 1, v[26:27]
	v_bfe_u32 v26, v24, 16, 1
	v_add3_u32 v24, v24, v26, s86
	global_store_short_d16_hi v[18:19], v24, off
	v_bfe_u32 v24, v25, 16, 1
	s_movk_i32 s18, 0x4000
	v_add3_u32 v26, v25, v24, s86
	v_add_co_u32_e32 v24, vcc, s18, v18
	s_mov_b32 s18, 0x8000
	s_nop 0
	v_addc_co_u32_e32 v25, vcc, 0, v19, vcc
	global_store_short_d16_hi v[24:25], v26, off offset:512
	v_bfe_u32 v24, v22, 16, 1
	v_add3_u32 v22, v22, v24, s86
	v_add_co_u32_e32 v24, vcc, s18, v18
	s_nop 1
	v_addc_co_u32_e32 v25, vcc, 0, v19, vcc
	global_store_short_d16_hi v[24:25], v22, off offset:1024
	v_bfe_u32 v22, v23, 16, 1
	v_add3_u32 v24, v23, v22, s86
	v_add_co_u32_e32 v22, vcc, s83, v18
	s_nop 1
	v_addc_co_u32_e32 v23, vcc, 0, v19, vcc
	global_store_short_d16_hi v[22:23], v24, off offset:1536
	v_bfe_u32 v22, v20, 16, 1
	v_add3_u32 v20, v20, v22, s86
	v_add_co_u32_e32 v22, vcc, s79, v18
	s_nop 1
	v_addc_co_u32_e32 v23, vcc, 0, v19, vcc
	global_store_short_d16_hi v[22:23], v20, off offset:2048
	v_bfe_u32 v20, v21, 16, 1
	v_add3_u32 v22, v21, v20, s86
	v_add_co_u32_e32 v20, vcc, s78, v18
	s_nop 1
	v_addc_co_u32_e32 v21, vcc, 0, v19, vcc
	global_store_short_d16_hi v[20:21], v22, off offset:2560
	v_bfe_u32 v20, v16, 16, 1
	v_add3_u32 v16, v16, v20, s86
	v_add_co_u32_e32 v20, vcc, 0x18000, v18
	s_nop 1
	v_addc_co_u32_e32 v21, vcc, 0, v19, vcc
	global_store_short_d16_hi v[20:21], v16, off offset:3072
	v_bfe_u32 v16, v17, 16, 1
	v_add3_u32 v20, v17, v16, s86
	v_add_co_u32_e32 v16, vcc, 0x1c000, v18
	s_nop 1
	v_addc_co_u32_e32 v17, vcc, 0, v19, vcc
	global_store_short_d16_hi v[16:17], v20, off offset:3584

; __device__ __forceinline__ unsigned f2bf(float f) { unsigned u = __float_as_uint(f); return (u + 0x7fffu + ((u >> 16) & 1u)) >> 16; }
; __device__ __forceinline__ u32x4 pack8(const float* v) { u32x4 w; w.x = pk2(v[0], v[1]); w.y = pk2(v[2], v[3]); w.z = pk2(v[4], v[5]); w.w = pk2(v[6], v[7]); return w; }
;     __device__ __forceinline__ void operator()(const f32x4 (&acc)[2][2][4][2], const pg8::Unit& u, int wr, int wc, int fr, int fq) const {
;     ...
;             const int b = (t >= TB) ? 1 : 0, i = t - b * TB;
;             const float rstd = rsqrtf(((const float*)(ws + O_SSQ))[t * 2 + 1] * (1.f / 128.f) + EPS);
; #pragma unroll
;             for (int e = 0; e < 8; ++e) v[e] *= rstd;
;             const int h = c0 >> 7, w = c0 & 127;
;             if (w < 64) *(u32x4*)((bf16_t*)(ws + O_KB) + (size_t)t * 768 + h * 96 + w) = pack8(v);
;             else { bf16_t* dst = (bf16_t*)(ws + O_VBT) + ((size_t)(b * 8 + h) * 64 + (w - 64)) * TB + i;
; #pragma unroll
;                 for (int e = 0; e < 8; ++e) dst[(size_t)e * TB] = (bf16_t)f2bf(v[e]); }
.LBB0_655:
	s_or_b64 exec, exec, s[0:1]
	s_mov_b64 s[0:1], 0x380004
	v_lshl_add_u64 v[16:17], v[94:95], 0, s[0:1]
	s_nop 0
	v_mov_b32_e32 v16, v184
	v_fmamk_f32 v16, v16, 0x3c000000, v216
	v_mul_f32_e32 v17, 0x4b800000, v16
	v_cmp_gt_f32_e32 vcc, s33, v16
	s_nop 1
	v_cndmask_b32_e32 v16, v16, v17, vcc
	v_rsq_f32_e32 v16, v16
	s_nop 0
	v_mul_f32_e32 v17, 0x45800000, v16
	v_cndmask_b32_e32 v18, v16, v17, vcc
	v_pk_mul_f32 v[16:17], v[12:13], v[18:19] op_sel_hi:[1,0]
	v_pk_mul_f32 v[14:15], v[14:15], v[18:19] op_sel_hi:[1,0]
	v_pk_mul_f32 v[12:13], v[8:9], v[18:19] op_sel_hi:[1,0]
	v_pk_mul_f32 v[8:9], v[10:11], v[18:19] op_sel_hi:[1,0]
	s_and_saveexec_b64 s[0:1], s[48:49]
	s_xor_b64 s[0:1], exec, s[0:1]
	s_cbranch_execz .LBB0_657
	v_add_u32_e32 v10, v99, v79
	v_ashrrev_i32_e32 v11, 31, v10
	v_lshlrev_b64 v[10:11], 6, v[10:11]
	v_lshl_add_u64 v[10:11], v[10:11], 0, v[148:149]
	v_mov_b64_e32 v[18:19], s[34:35]
	s_movk_i32 s24, 0x4200
	v_mad_u64_u32 v[18:19], s[18:19], v10, s24, v[18:19]
	v_mad_i32_i24 v19, v11, s24, v19
	v_lshl_add_u64 v[10:11], v[92:93], 1, v[18:19]
	v_bfe_u32 v18, v16, 16, 1
	v_add3_u32 v16, v16, v18, s86
	global_store_short_d16_hi v[10:11], v16, off
	v_bfe_u32 v16, v17, 16, 1
	s_movk_i32 s18, 0x4000
	v_add3_u32 v18, v17, v16, s86
	v_add_co_u32_e32 v16, vcc, s18, v10
	s_mov_b32 s18, 0x8000
	s_nop 0
	v_addc_co_u32_e32 v17, vcc, 0, v11, vcc
	global_store_short_d16_hi v[16:17], v18, off offset:512
	v_bfe_u32 v16, v14, 16, 1
	v_add3_u32 v14, v14, v16, s86
	v_add_co_u32_e32 v16, vcc, s18, v10
	s_nop 1
	v_addc_co_u32_e32 v17, vcc, 0, v11, vcc
	global_store_short_d16_hi v[16:17], v14, off offset:1024
	v_bfe_u32 v14, v15, 16, 1
	v_add3_u32 v16, v15, v14, s86
	v_add_co_u32_e32 v14, vcc, s83, v10
	s_nop 1
	v_addc_co_u32_e32 v15, vcc, 0, v11, vcc
	global_store_short_d16_hi v[14:15], v16, off offset:1536
	v_bfe_u32 v14, v12, 16, 1
	v_add3_u32 v12, v12, v14, s86
	v_add_co_u32_e32 v14, vcc, s79, v10
	s_nop 1
	v_addc_co_u32_e32 v15, vcc, 0, v11, vcc
	global_store_short_d16_hi v[14:15], v12, off offset:2048
	v_bfe_u32 v12, v13, 16, 1
	v_add3_u32 v14, v13, v12, s86
	v_add_co_u32_e32 v12, vcc, s78, v10
	s_nop 1
	v_addc_co_u32_e32 v13, vcc, 0, v11, vcc
	global_store_short_d16_hi v[12:13], v14, off offset:2560
	v_bfe_u32 v12, v8, 16, 1
	v_add3_u32 v8, v8, v12, s86
	v_add_co_u32_e32 v12, vcc, 0x18000, v10
	s_nop 1
	v_addc_co_u32_e32 v13, vcc, 0, v11, vcc
	global_store_short_d16_hi v[12:13], v8, off offset:3072
	v_bfe_u32 v8, v9, 16, 1
	v_add3_u32 v12, v9, v8, s86
	v_add_co_u32_e32 v8, vcc, 0x1c000, v10
	s_nop 1
	v_addc_co_u32_e32 v9, vcc, 0, v11, vcc
	global_store_short_d16_hi v[8:9], v12, off offset:3584

; __device__ __forceinline__ unsigned f2bf(float f) { unsigned u = __float_as_uint(f); return (u + 0x7fffu + ((u >> 16) & 1u)) >> 16; }
; __device__ __forceinline__ u32x4 pack8(const float* v) { u32x4 w; w.x = pk2(v[0], v[1]); w.y = pk2(v[2], v[3]); w.z = pk2(v[4], v[5]); w.w = pk2(v[6], v[7]); return w; }
;     __device__ __forceinline__ void operator()(const f32x4 (&acc)[2][2][4][2], const pg8::Unit& u, int wr, int wc, int fr, int fq) const {
;     ...
;             const int b = (t >= TB) ? 1 : 0, i = t - b * TB;
;             const float rstd = rsqrtf(((const float*)(ws + O_SSQ))[t * 2 + 1] * (1.f / 128.f) + EPS);
; #pragma unroll
;             for (int e = 0; e < 8; ++e) v[e] *= rstd;
;             const int h = c0 >> 7, w = c0 & 127;
;             if (w < 64) *(u32x4*)((bf16_t*)(ws + O_KB) + (size_t)t * 768 + h * 96 + w) = pack8(v);
;             else { bf16_t* dst = (bf16_t*)(ws + O_VBT) + ((size_t)(b * 8 + h) * 64 + (w - 64)) * TB + i;
; #pragma unroll
;                 for (int e = 0; e < 8; ++e) dst[(size_t)e * TB] = (bf16_t)f2bf(v[e]); }
.LBB0_659:
	s_or_b64 exec, exec, s[0:1]
	s_mov_b64 s[0:1], 0x380004
	v_lshl_add_u64 v[8:9], v[86:87], 0, s[0:1]
	s_nop 0
	v_mov_b32_e32 v8, v185
	v_fmamk_f32 v8, v8, 0x3c000000, v216
	v_mul_f32_e32 v9, 0x4b800000, v8
	v_cmp_gt_f32_e32 vcc, s33, v8
	s_nop 1
	v_cndmask_b32_e32 v8, v8, v9, vcc
	v_rsq_f32_e32 v8, v8
	s_nop 0
	v_mul_f32_e32 v9, 0x45800000, v8
	v_cndmask_b32_e32 v10, v8, v9, vcc
	v_pk_mul_f32 v[8:9], v[4:5], v[10:11] op_sel_hi:[1,0]
	v_pk_mul_f32 v[6:7], v[6:7], v[10:11] op_sel_hi:[1,0]
	v_pk_mul_f32 v[4:5], v[0:1], v[10:11] op_sel_hi:[1,0]
	v_pk_mul_f32 v[0:1], v[2:3], v[10:11] op_sel_hi:[1,0]
	s_and_saveexec_b64 s[0:1], s[48:49]
	s_xor_b64 s[0:1], exec, s[0:1]
	s_cbranch_execz .LBB0_661
	v_add_u32_e32 v2, v78, v79
	v_ashrrev_i32_e32 v3, 31, v2
	v_lshlrev_b64 v[2:3], 6, v[2:3]
	v_lshl_add_u64 v[2:3], v[2:3], 0, v[148:149]
	v_mov_b64_e32 v[10:11], s[34:35]
	s_movk_i32 s24, 0x4200
	v_mad_u64_u32 v[10:11], s[18:19], v2, s24, v[10:11]
	v_mad_i32_i24 v11, v3, s24, v11
	v_lshl_add_u64 v[2:3], v[84:85], 1, v[10:11]
	v_bfe_u32 v10, v8, 16, 1
	v_add3_u32 v8, v8, v10, s86
	global_store_short_d16_hi v[2:3], v8, off
	v_bfe_u32 v8, v9, 16, 1
	s_movk_i32 s18, 0x4000
	v_add3_u32 v10, v9, v8, s86
	v_add_co_u32_e32 v8, vcc, s18, v2
	s_mov_b32 s18, 0x8000
	s_nop 0
	v_addc_co_u32_e32 v9, vcc, 0, v3, vcc
	global_store_short_d16_hi v[8:9], v10, off offset:512
	v_bfe_u32 v8, v6, 16, 1
	v_add3_u32 v6, v6, v8, s86
	v_add_co_u32_e32 v8, vcc, s18, v2
	s_nop 1
	v_addc_co_u32_e32 v9, vcc, 0, v3, vcc
	global_store_short_d16_hi v[8:9], v6, off offset:1024
	v_bfe_u32 v6, v7, 16, 1
	v_add3_u32 v8, v7, v6, s86
	v_add_co_u32_e32 v6, vcc, s83, v2
	s_nop 1
	v_addc_co_u32_e32 v7, vcc, 0, v3, vcc
	global_store_short_d16_hi v[6:7], v8, off offset:1536
	v_bfe_u32 v6, v4, 16, 1
	v_add3_u32 v4, v4, v6, s86
	v_add_co_u32_e32 v6, vcc, s79, v2
	s_nop 1
	v_addc_co_u32_e32 v7, vcc, 0, v3, vcc
	global_store_short_d16_hi v[6:7], v4, off offset:2048
	v_bfe_u32 v4, v5, 16, 1
	v_add3_u32 v6, v5, v4, s86
	v_add_co_u32_e32 v4, vcc, s78, v2
	s_nop 1
	v_addc_co_u32_e32 v5, vcc, 0, v3, vcc
	global_store_short_d16_hi v[4:5], v6, off offset:2560
	v_bfe_u32 v4, v0, 16, 1
	v_add3_u32 v0, v0, v4, s86
	v_add_co_u32_e32 v4, vcc, 0x18000, v2
	s_nop 1
	v_addc_co_u32_e32 v5, vcc, 0, v3, vcc
	global_store_short_d16_hi v[4:5], v0, off offset:3072
	v_bfe_u32 v0, v1, 16, 1
	v_add3_u32 v4, v1, v0, s86
	v_add_co_u32_e32 v0, vcc, 0x1c000, v2
	s_nop 1
	v_addc_co_u32_e32 v1, vcc, 0, v3, vcc
	global_store_short_d16_hi v[0:1], v4, off offset:3584
